# depack P12,P4,P2: packed f32 VALU ops split into scalar pairs (bit-identical)
# baseline (speedup 1.0000x reference)
.LBB0_282:
	s_add_i32 s25, s18, s84
	s_cmpk_gt_i32 s25, 0xfff
	s_cselect_b64 s[16:17], -1, 0
	s_cmpk_lt_i32 s25, 0x1000
	s_cselect_b32 s20, s25, s18
	s_ashr_i32 s21, s20, 31
	s_lshl_b64 s[26:27], s[20:21], 16
	s_add_u32 s26, s12, s26
	s_addc_u32 s27, s13, s27
	v_lshl_add_u64 v[8:9], s[26:27], 0, v[16:17]
	v_add_co_u32_e32 v0, vcc, s3, v8
	s_and_b32 s19, s20, 0x180
	s_nop 0
	v_addc_co_u32_e32 v1, vcc, 0, v9, vcc
	v_add_co_u32_e32 v4, vcc, s15, v8
	v_or_b32_e32 v22, s19, v71
	s_nop 0
	v_addc_co_u32_e32 v5, vcc, 0, v9, vcc
	v_add_co_u32_e32 v10, vcc, s22, v8
	v_lshlrev_b32_e32 v22, 2, v22
	s_nop 0
	v_addc_co_u32_e32 v11, vcc, 0, v9, vcc
	v_add_co_u32_e32 v12, vcc, s23, v8
	global_load_dwordx4 v[0:3], v[0:1], off
	s_nop 0
	global_load_dwordx4 v[4:7], v[4:5], off
	v_addc_co_u32_e32 v13, vcc, 0, v9, vcc
	global_load_dwordx4 v[8:11], v[10:11], off
	s_nop 0
	global_load_dwordx4 v[12:15], v[12:13], off
	s_nop 0
	global_load_dword v83, v22, s[62:63]
	global_load_dword v84, v22, s[62:63] offset:2048
	ds_read_u16 v22, v79
	ds_read_u16 v23, v79 offset:288
	ds_read_u16 v24, v79 offset:576
	ds_read_u16 v25, v79 offset:864
	ds_read_u16 v26, v79 offset:1152
	ds_read_u16 v27, v79 offset:1440
	ds_read_u16 v28, v79 offset:1728
	ds_read_u16 v29, v79 offset:2016
	ds_read_u16 v30, v79 offset:2304
	ds_read_u16 v31, v79 offset:2592
	ds_read_u16 v34, v79 offset:2880
	s_waitcnt lgkmcnt(0)
	ds_read_u16 v35, v79 offset:3168
	ds_read_u16 v36, v79 offset:3456
	ds_read_u16 v37, v79 offset:3744
	ds_read_u16 v38, v79 offset:4032
	ds_read_u16 v32, v79 offset:4320
	ds_read_u16 v93, v79 offset:20480
	ds_read_u16 v97, v79 offset:20768
	ds_read_u16 v94, v79 offset:21056
	ds_read_u16 v98, v79 offset:21344
	ds_read_u16 v95, v79 offset:21632
	ds_read_u16 v99, v79 offset:21920
	ds_read_u16 v96, v79 offset:22208
	ds_read_u16 v100, v79 offset:22496
	ds_read_u16 v85, v79 offset:22784
	ds_read_u16 v89, v79 offset:23072
	ds_read_u16 v86, v79 offset:23360
	ds_read_u16 v90, v79 offset:23648
	ds_read_u16 v87, v79 offset:23936
	ds_read_u16 v91, v79 offset:24224
	ds_read_u16 v88, v79 offset:24512
	ds_read_u16 v92, v79 offset:24800
	s_waitcnt lgkmcnt(0)
	s_barrier
	s_bfe_u32 s19, s18, 0x30007
	s_cmp_gt_u32 s19, 3
	s_waitcnt lgkmcnt(14)
	v_lshlrev_b32_e32 v33, 16, v32
	v_lshlrev_b32_e32 v32, 16, v22
	v_lshlrev_b32_e32 v65, 16, v23
	v_lshlrev_b32_e32 v64, 16, v24
	v_lshlrev_b32_e32 v61, 16, v25
	v_lshlrev_b32_e32 v60, 16, v26
	v_lshlrev_b32_e32 v59, 16, v27
	v_lshlrev_b32_e32 v58, 16, v28
	v_lshlrev_b32_e32 v51, 16, v29
	v_lshlrev_b32_e32 v50, 16, v30
	v_lshlrev_b32_e32 v49, 16, v31
	v_lshlrev_b32_e32 v48, 16, v34
	v_lshlrev_b32_e32 v43, 16, v35
	v_lshlrev_b32_e32 v42, 16, v36
	v_lshlrev_b32_e32 v37, 16, v37
	v_lshlrev_b32_e32 v36, 16, v38
	s_cbranch_scc0 .LBB0_284
	s_add_i32 s19, s19, -4
	v_cvt_f32_u32_e32 v26, s19
	v_mul_f32_e32 v22, s14, v64
	v_mul_f32_e32 v23, s14, v65
	v_mul_f32_e32 v24, s14, v60
	v_mul_f32_e32 v25, s14, v61
	v_mul_f32_e32 v28, s14, v58
	v_mul_f32_e32 v29, s14, v59
	v_sub_f32_e32 v26, 0xc0a00000, v26
	v_cmp_gt_f32_e32 vcc, s24, v26
	s_and_b64 s[20:21], vcc, exec
	s_cselect_b32 s19, 0xffffffc0, 0
	v_cndmask_b32_e32 v27, 0, v82, vcc
	v_add_f32_e32 v26, v26, v27
	v_exp_f32_e32 v26, v26
	v_mul_f32_e32 v38, s14, v50
	v_mul_f32_e32 v39, s14, v51
	v_mul_f32_e32 v46, s14, v48
	v_mul_f32_e32 v47, s14, v49
	v_mul_f32_e32 v56, s14, v42
	v_mul_f32_e32 v57, s14, v43
	v_ldexp_f32 v26, v26, s19
	v_sub_f32_e32 v70, 1.0, v26
	v_mul_f32_e32 v62, s14, v36
	v_mul_f32_e32 v63, s14, v37
	v_mul_f32_e32 v34, s14, v32
	v_mul_f32_e32 v35, s14, v33
	s_mov_b64 s[20:21], 0
	v_mov_b64_e32 v[52:53], v[70:71]
	s_branch .LBB0_285

.LBB0_285:
	v_mov_b64_e32 v[54:55], v[52:53]
	v_mov_b64_e32 v[44:45], v[52:53]
	v_mov_b64_e32 v[40:41], v[52:53]
	v_mov_b64_e32 v[30:31], v[52:53]
	v_mov_b64_e32 v[26:27], v[52:53]
	v_mov_b64_e32 v[66:67], v[52:53]
	v_mov_b64_e32 v[68:69], v[52:53]
	s_andn2_b64 vcc, exec, s[20:21]
	v_mov_b32_e32 v55, v70
	v_mov_b32_e32 v45, v70
	v_mov_b32_e32 v41, v70
	v_mov_b32_e32 v31, v70
	v_mov_b32_e32 v27, v70
	v_mov_b32_e32 v67, v70
	v_mov_b32_e32 v69, v70
	s_cbranch_vccnz .LBB0_287
	v_max_f32_e32 v22, v101, v101
	v_max_f32_e32 v23, v102, v102
	v_max_f32_e32 v22, v23, v22
	v_sub_f32_e32 v23, v102, v22
	v_sub_f32_e32 v22, v101, v22
	v_mul_f32_e32 v23, 0x3fb8aa3b, v23
	v_mul_f32_e32 v22, 0x3fb8aa3b, v22
	v_exp_f32_e32 v26, v23
	v_exp_f32_e32 v22, v22
	v_mul_f32_e32 v38, 0xbfb8aa3b, v49
	v_exp_f32_e32 v38, v38
	v_mul_f32_e32 v37, 0xbfb8aa3b, v37
	v_add_f32_e32 v27, v26, v22
	v_div_scale_f32 v22, s[20:21], v27, v27, v26
	v_rcp_f32_e32 v23, v22
	v_exp_f32_e32 v37, v37
	v_fma_f32 v24, -v22, v23, 1.0
	v_fmac_f32_e32 v23, v24, v23
	v_div_scale_f32 v24, vcc, v26, v27, v26
	v_mul_f32_e32 v25, v24, v23
	v_fma_f32 v28, -v22, v25, v24
	v_fmac_f32_e32 v25, v28, v23
	v_fma_f32 v22, -v22, v25, v24
	v_mul_f32_e32 v24, 0xbfb8aa3b, v32
	v_exp_f32_e32 v24, v24
	v_mul_f32_e32 v28, 0xbfb8aa3b, v65
	v_exp_f32_e32 v28, v28
	v_div_fmas_f32 v29, v22, v23, v25
	v_add_f32_e32 v22, 1.0, v24
	v_mul_f32_e32 v24, 0xbfb8aa3b, v64
	v_exp_f32_e32 v24, v24
	v_mul_f32_e32 v25, 0xbfb8aa3b, v61
	v_rcp_f32_e32 v23, v22
	v_add_f32_e32 v22, 1.0, v28
	v_exp_f32_e32 v28, v25
	v_add_f32_e32 v24, 1.0, v24
	v_rcp_f32_e32 v25, v24
	v_div_fixup_f32 v32, v29, v27, v26
	v_add_f32_e32 v24, 1.0, v28
	v_rcp_f32_e32 v24, v24
	v_sub_f32_e32 v34, 1.0, v32
	v_rcp_f32_e32 v22, v22
	v_mul_f32_e32 v29, 0xbfb8aa3b, v51
	v_fma_f32 v30, v34, v24, v32
	v_fma_f32 v31, v34, v25, v32
	v_mul_f32_e32 v24, 0xbfb8aa3b, v60
	v_exp_f32_e32 v24, v24
	v_mul_f32_e32 v25, 0xbfb8aa3b, v59
	v_exp_f32_e32 v28, v25
	v_fma_f32 v26, v34, v22, v32
	v_fma_f32 v27, v34, v23, v32
	v_add_f32_e32 v24, 1.0, v24
	v_rcp_f32_e32 v25, v24
	v_add_f32_e32 v24, 1.0, v28
	v_mul_f32_e32 v28, 0xbfb8aa3b, v58
	v_exp_f32_e32 v28, v28
	v_exp_f32_e32 v35, v29
	v_rcp_f32_e32 v24, v24
	v_pk_mov_b32 v[22:23], v[30:31], v[26:27] op_sel:[1,0]
	v_add_f32_e32 v28, 1.0, v28
	v_rcp_f32_e32 v29, v28
	v_add_f32_e32 v28, 1.0, v35
	v_rcp_f32_e32 v28, v28
	v_fma_f32 v40, v34, v24, v32
	v_fma_f32 v41, v34, v25, v32
	v_pk_mov_b32 v[24:25], v[40:41], v[30:31] op_sel:[1,0]
	v_add_f32_e64 v22, -v22, 1.0
	v_add_f32_e64 v23, -v23, 1.0
	v_fma_f32 v44, v34, v28, v32
	v_fma_f32 v45, v34, v29, v32
	v_mul_f32_e32 v35, 0xbfb8aa3b, v50
	v_exp_f32_e32 v35, v35
	v_pk_mov_b32 v[28:29], v[44:45], v[40:41] op_sel:[1,0]
	v_add_f32_e64 v24, -v24, 1.0
	v_add_f32_e64 v25, -v25, 1.0
	v_add_f32_e64 v28, -v28, 1.0
	v_add_f32_e64 v29, -v29, 1.0
	v_add_f32_e32 v35, 1.0, v35
	v_rcp_f32_e32 v39, v35
	v_add_f32_e32 v35, 1.0, v38
	v_mul_f32_e32 v38, 0xbfb8aa3b, v48
	v_exp_f32_e32 v46, v38
	v_mul_f32_e32 v38, 0xbfb8aa3b, v43
	v_exp_f32_e32 v43, v38
	v_rcp_f32_e32 v38, v35
	v_add_f32_e32 v35, 1.0, v46
	v_rcp_f32_e32 v47, v35
	v_add_f32_e32 v35, 1.0, v43
	v_rcp_f32_e32 v46, v35
	v_fma_f32 v54, v34, v38, v32
	v_fma_f32 v55, v34, v39, v32
	v_pk_mov_b32 v[38:39], v[54:55], v[44:45] op_sel:[1,0]
	v_fma_f32 v52, v34, v46, v32
	v_fma_f32 v53, v34, v47, v32
	v_mul_f32_e32 v35, 0xbfb8aa3b, v42
	v_exp_f32_e32 v35, v35
	v_mul_f32_e32 v33, 0xbfb8aa3b, v33
	v_exp_f32_e32 v33, v33
	v_pk_mov_b32 v[46:47], v[52:53], v[54:55] op_sel:[1,0]
	v_add_f32_e32 v35, 1.0, v35
	v_rcp_f32_e32 v42, v35
	v_add_f32_e32 v35, 1.0, v37
	v_rcp_f32_e32 v43, v35
	v_mul_f32_e32 v35, 0xbfb8aa3b, v36
	v_exp_f32_e32 v35, v35
	v_add_f32_e64 v38, -v38, 1.0
	v_add_f32_e64 v39, -v39, 1.0
	v_add_f32_e64 v46, -v46, 1.0
	v_add_f32_e64 v47, -v47, 1.0
	v_mov_b32_e32 v70, v53
	v_fma_f32 v66, v34, v42, v32
	v_fma_f32 v67, v34, v43, v32
	v_add_f32_e32 v35, 1.0, v35
	v_add_f32_e32 v33, 1.0, v33
	v_rcp_f32_e32 v36, v35
	v_rcp_f32_e32 v37, v33
	v_mov_b32_e32 v42, v66
	v_mov_b32_e32 v43, v52
	v_add_f32_e64 v56, -v42, 1.0
	v_add_f32_e64 v57, -v43, 1.0
	v_fma_f32 v68, v34, v36, v32
	v_fma_f32 v69, v34, v37, v32
	v_mov_b32_e32 v32, v68
	v_mov_b32_e32 v33, v67
	v_add_f32_e64 v62, -v32, 1.0
	v_add_f32_e64 v63, -v33, 1.0
	v_mov_b32_e32 v32, v27
	v_mov_b32_e32 v33, v69
	v_add_f32_e64 v34, -v32, 1.0
	v_add_f32_e64 v35, -v33, 1.0
.LBB0_287:
	v_lshlrev_b32_e32 v32, 16, v97
	v_or_b32_sdwa v48, v32, v93 dst_sel:DWORD dst_unused:UNUSED_PAD src0_sel:DWORD src1_sel:WORD_0
	s_waitcnt lgkmcnt(12)
	v_lshlrev_b32_e32 v32, 16, v98
	v_or_b32_sdwa v49, v32, v94 dst_sel:DWORD dst_unused:UNUSED_PAD src0_sel:DWORD src1_sel:WORD_0
	s_waitcnt lgkmcnt(10)
	v_lshlrev_b32_e32 v32, 16, v99
	v_or_b32_sdwa v50, v32, v95 dst_sel:DWORD dst_unused:UNUSED_PAD src0_sel:DWORD src1_sel:WORD_0
	s_waitcnt lgkmcnt(8)
	v_lshlrev_b32_e32 v32, 16, v100
	v_or_b32_sdwa v51, v32, v96 dst_sel:DWORD dst_unused:UNUSED_PAD src0_sel:DWORD src1_sel:WORD_0
	s_waitcnt lgkmcnt(6)
	v_lshlrev_b32_e32 v32, 16, v89
	v_or_b32_sdwa v58, v32, v85 dst_sel:DWORD dst_unused:UNUSED_PAD src0_sel:DWORD src1_sel:WORD_0
	s_waitcnt lgkmcnt(4)
	v_lshlrev_b32_e32 v32, 16, v90
	v_or_b32_sdwa v59, v32, v86 dst_sel:DWORD dst_unused:UNUSED_PAD src0_sel:DWORD src1_sel:WORD_0
	s_waitcnt lgkmcnt(2)
	v_lshlrev_b32_e32 v32, 16, v91
	v_or_b32_sdwa v60, v32, v87 dst_sel:DWORD dst_unused:UNUSED_PAD src0_sel:DWORD src1_sel:WORD_0
	s_waitcnt lgkmcnt(0)
	v_lshlrev_b32_e32 v32, 16, v92
	v_or_b32_sdwa v61, v32, v88 dst_sel:DWORD dst_unused:UNUSED_PAD src0_sel:DWORD src1_sel:WORD_0
	v_mul_f32_e32 v32, v68, v69
	v_mul_f32_e32 v33, v69, v68
	v_mov_b32_e32 v53, v70
	v_mul_f32_e32 v42, v67, v32
	v_mul_f32_e32 v43, v66, v33
	v_mov_b32_e32 v65, v32
	v_mul_f32_e32 v32, v66, v42
	v_mul_f32_e32 v33, v67, v43
	v_mul_f32_e32 v36, v62, v69
	v_mul_f32_e32 v37, v63, v68
	v_mov_b32_e32 v62, v56
	v_mov_b32_e32 v64, v42
	v_mul_f32_e32 v42, v52, v32
	v_mul_f32_e32 v43, v53, v33
	v_mul_f32_e32 v62, v62, v64
	v_mul_f32_e32 v63, v63, v65
	v_mov_b32_e32 v65, v32
	v_mul_f32_e32 v32, v53, v42
	v_mul_f32_e32 v33, v52, v43
	v_mov_b32_e32 v64, v42
	v_mul_f32_e32 v42, v54, v32
	v_mul_f32_e32 v43, v55, v33
	v_mov_b32_e32 v56, v46
	v_mov_b32_e32 v46, v38
	v_mov_b32_e32 v52, v42
	v_mov_b32_e32 v53, v32
	v_mul_f32_e32 v42, v55, v42
	v_mul_f32_e32 v43, v54, v43
	v_mul_f32_e32 v32, v46, v52
	v_mul_f32_e32 v33, v47, v53
	v_mul_f32_e32 v46, v44, v42
	v_mul_f32_e32 v47, v45, v43
	v_mov_b32_e32 v53, v42
	v_mul_f32_e32 v42, v45, v46
	v_mul_f32_e32 v43, v44, v47
	v_mul_f32_e32 v44, v40, v42
	v_mul_f32_e32 v45, v41, v43
	v_mov_b32_e32 v38, v28
	v_mov_b32_e32 v52, v46
	v_mov_b32_e32 v28, v24
	v_mov_b32_e32 v46, v44
	v_mov_b32_e32 v47, v42
	v_mul_f32_e32 v42, v28, v46
	v_mul_f32_e32 v43, v29, v47
	v_mul_f32_e32 v28, v41, v44
	v_mul_f32_e32 v29, v40, v45
	v_mul_f32_e32 v40, v30, v28
	v_mul_f32_e32 v41, v31, v29
	v_mov_b32_e32 v45, v28
	v_mul_f32_e32 v28, v31, v40
	v_mul_f32_e32 v29, v30, v41
	v_mul_f32_e32 v30, v26, v28
	v_mul_f32_e32 v31, v27, v29
	v_mov_b32_e32 v24, v22
	v_mul_f32_e32 v22, v27, v30
	ds_write_b32 v74, v22 offset:40960
	v_add_u32_e32 v22, v75, v76
	ds_write_b128 v22, v[48:51] offset:20480
	ds_write_b128 v22, v[58:61] offset:20496
	v_mov_b32_e32 v44, v40
	s_waitcnt lgkmcnt(0)
	s_barrier
	v_mul_f32_e32 v44, v24, v44
	v_mul_f32_e32 v45, v25, v45
	ds_read2st64_b32 v[24:25], v77 offset0:160 offset1:162
	ds_read2st64_b32 v[26:27], v77 offset0:164 offset1:166
	v_mov_b32_e32 v31, v28
	v_mov_b32_e32 v22, v34
	v_mul_f32_e32 v22, v22, v30
	v_mul_f32_e32 v23, v23, v31
	s_waitcnt lgkmcnt(1)
	v_cndmask_b32_e64 v28, 1.0, v25, s[4:5]
	s_waitcnt lgkmcnt(0)
	v_mul_f32_e32 v28, v28, v26
	v_cndmask_b32_e64 v28, 1.0, v28, s[8:9]
	v_mul_f32_e32 v28, v27, v28
	v_cndmask_b32_e64 v40, 1.0, v28, s[10:11]
	v_mul_f32_e32 v22, v40, v22
	v_mul_f32_e32 v23, v40, v23
	v_cvt_pk_bf16_f32 v28, v22, v23
	v_mul_f32_e32 v22, v44, v40
	v_mul_f32_e32 v23, v45, v40
	v_mul_f32_e32 v38, v38, v52
	v_mul_f32_e32 v39, v39, v53
	v_cvt_pk_bf16_f32 v29, v22, v23
	v_mul_f32_e32 v22, v42, v40
	v_mul_f32_e32 v23, v43, v40
	v_mul_f32_e32 v56, v56, v64
	v_mul_f32_e32 v57, v57, v65
	v_cvt_pk_bf16_f32 v30, v22, v23
	v_mul_f32_e32 v22, v38, v40
	v_mul_f32_e32 v23, v39, v40
	v_mov_b32_e32 v37, v35
	v_cvt_pk_bf16_f32 v31, v22, v23
	v_mul_f32_e32 v22, v32, v40
	v_mul_f32_e32 v23, v33, v40
	s_nop 0
	v_cvt_pk_bf16_f32 v32, v22, v23
	v_mul_f32_e32 v22, v56, v40
	v_mul_f32_e32 v23, v57, v40
	s_nop 0
	v_cvt_pk_bf16_f32 v33, v22, v23
	v_mul_f32_e32 v22, v62, v40
	v_mul_f32_e32 v23, v63, v40
	s_nop 0
	v_cvt_pk_bf16_f32 v34, v22, v23
	v_mul_f32_e32 v22, v36, v40
	v_mul_f32_e32 v23, v37, v40
	s_nop 0
	v_cvt_pk_bf16_f32 v35, v22, v23
	ds_write_b128 v80, v[28:31]
	ds_write_b128 v80, v[32:35] offset:16
	s_and_saveexec_b64 s[20:21], s[6:7]
	s_xor_b64 s[20:21], exec, s[20:21]
	s_ashr_i32 s19, s18, 31
	s_or_saveexec_b64 s[20:21], s[20:21]
	v_mov_b64_e32 v[22:23], s[18:19]
	s_xor_b64 exec, exec, s[20:21]
	s_cbranch_execz .LBB0_281
	v_mul_f32_e32 v22, v24, v25
	s_ashr_i32 s19, s18, 31
	v_mul_f32_e32 v22, v22, v26
	s_lshl_b64 s[26:27], s[18:19], 9
	v_mul_f32_e32 v24, v22, v27
	v_lshl_add_u64 v[22:23], v[18:19], 0, s[26:27]
	global_store_dword v[22:23], v24, off
	v_mov_b64_e32 v[22:23], s[18:19]
	s_branch .LBB0_281

.LBB0_294:
	s_cmp_lg_u32 s16, 15
	s_cselect_b64 s[20:21], -1, 0
	s_cmp_lg_u64 s[20:21], 0
	s_addc_u32 s25, s10, s16
	v_cndmask_b32_e64 v32, 0, 1, s[20:21]
	s_add_u32 s20, s10, s16
	v_mov_b32_e32 v33, s24
	s_addc_u32 s21, s11, s17
	v_lshl_add_u64 v[32:33], s[20:21], 0, v[32:33]
	v_lshlrev_b64 v[32:33], 16, v[32:33]
	v_lshl_add_u64 v[32:33], s[12:13], 0, v[32:33]
	v_lshl_add_u64 v[40:41], v[32:33], 0, v[48:49]
	v_add_co_u32_e32 v32, vcc, s3, v40
	s_and_b32 s20, s25, 0x180
	s_nop 0
	v_addc_co_u32_e32 v33, vcc, 0, v41, vcc
	v_add_co_u32_e32 v36, vcc, s19, v40
	v_or_b32_e32 v52, s20, v102
	s_nop 0
	v_addc_co_u32_e32 v37, vcc, 0, v41, vcc
	v_add_co_u32_e32 v42, vcc, s22, v40
	v_lshlrev_b32_e32 v52, 2, v52
	s_nop 0
	v_addc_co_u32_e32 v43, vcc, 0, v41, vcc
	v_add_co_u32_e32 v44, vcc, s23, v40
	s_waitcnt lgkmcnt(0)
	global_load_dwordx4 v[32:35], v[32:33], off
	s_nop 0
	global_load_dwordx4 v[36:39], v[36:37], off
	v_addc_co_u32_e32 v45, vcc, 0, v41, vcc
	global_load_dwordx4 v[40:43], v[42:43], off
	s_nop 0
	global_load_dwordx4 v[44:47], v[44:45], off
	s_nop 0
	global_load_dword v116, v52, s[62:63]
	global_load_dword v117, v52, s[62:63] offset:2048
	ds_read_u16 v52, v113
	ds_read_u16 v53, v113 offset:288
	ds_read_u16 v54, v113 offset:576
	ds_read_u16 v55, v113 offset:864
	ds_read_u16 v56, v113 offset:1152
	ds_read_u16 v57, v113 offset:1440
	ds_read_u16 v58, v113 offset:1728
	ds_read_u16 v59, v113 offset:2016
	ds_read_u16 v60, v113 offset:2304
	ds_read_u16 v61, v113 offset:2592
	ds_read_u16 v62, v113 offset:2880
	ds_read_u16 v63, v113 offset:3168
	ds_read_u16 v64, v113 offset:3456
	ds_read_u16 v65, v113 offset:3744
	ds_read_u16 v66, v113 offset:4032
	ds_read_u16 v67, v113 offset:4320
	ds_read_u16 v126, v113 offset:20480
	ds_read_u16 v132, v113 offset:20768
	ds_read_u16 v127, v113 offset:21056
	ds_read_u16 v133, v113 offset:21344
	ds_read_u16 v130, v113 offset:21632
	ds_read_u16 v134, v113 offset:21920
	ds_read_u16 v131, v113 offset:22208
	ds_read_u16 v135, v113 offset:22496
	ds_read_u16 v118, v113 offset:22784
	ds_read_u16 v122, v113 offset:23072
	ds_read_u16 v119, v113 offset:23360
	ds_read_u16 v123, v113 offset:23648
	ds_read_u16 v120, v113 offset:23936
	ds_read_u16 v124, v113 offset:24224
	ds_read_u16 v121, v113 offset:24512
	ds_read_u16 v125, v113 offset:24800
	s_waitcnt lgkmcnt(0)
	s_barrier
	s_and_b64 vcc, exec, s[14:15]
	s_waitcnt lgkmcnt(14)
	v_lshlrev_b32_e32 v69, 16, v67
	v_lshlrev_b32_e32 v68, 16, v52
	v_lshlrev_b32_e32 v99, 16, v53
	v_lshlrev_b32_e32 v98, 16, v54
	v_lshlrev_b32_e32 v93, 16, v55
	v_lshlrev_b32_e32 v92, 16, v56
	v_lshlrev_b32_e32 v91, 16, v57
	v_lshlrev_b32_e32 v90, 16, v58
	v_lshlrev_b32_e32 v87, 16, v59
	v_lshlrev_b32_e32 v86, 16, v60
	v_lshlrev_b32_e32 v81, 16, v61
	v_lshlrev_b32_e32 v80, 16, v62
	v_lshlrev_b32_e32 v77, 16, v63
	v_lshlrev_b32_e32 v76, 16, v64
	v_lshlrev_b32_e32 v75, 16, v65
	v_lshlrev_b32_e32 v74, 16, v66
	s_mov_b64 s[20:21], -1
	s_cbranch_vccz .LBB0_296
	v_mul_f32_e32 v52, s18, v98
	v_mul_f32_e32 v53, s18, v99
	v_mul_f32_e32 v54, s18, v92
	v_mul_f32_e32 v55, s18, v93
	v_mul_f32_e32 v58, s18, v90
	v_mul_f32_e32 v59, s18, v91
	v_mul_f32_e32 v64, s18, v86
	v_mul_f32_e32 v65, s18, v87
	v_mul_f32_e32 v72, s18, v80
	v_mul_f32_e32 v73, s18, v81
	v_mul_f32_e32 v82, s18, v76
	v_mul_f32_e32 v83, s18, v77
	v_mul_f32_e32 v88, s18, v74
	v_mul_f32_e32 v89, s18, v75
	v_mul_f32_e32 v62, s18, v68
	v_mul_f32_e32 v63, s18, v69
	s_mov_b64 s[20:21], 0
.LBB0_296:
	v_mov_b64_e32 v[96:97], v[50:51]
	v_mov_b64_e32 v[94:95], v[50:51]
	v_mov_b64_e32 v[84:85], v[50:51]
	v_mov_b64_e32 v[78:79], v[50:51]
	v_mov_b64_e32 v[70:71], v[50:51]
	v_mov_b64_e32 v[66:67], v[50:51]
	v_mov_b64_e32 v[60:61], v[50:51]
	v_mov_b64_e32 v[56:57], v[50:51]
	s_andn2_b64 vcc, exec, s[20:21]
	v_mov_b32_e32 v97, v50
	v_mov_b32_e32 v95, v50
	v_mov_b32_e32 v85, v50
	v_mov_b32_e32 v79, v50
	v_mov_b32_e32 v71, v50
	v_mov_b32_e32 v67, v50
	v_mov_b32_e32 v61, v50
	v_mov_b32_e32 v57, v50
	s_cbranch_vccnz .LBB0_298
	v_max_f32_e32 v52, v136, v136
	v_max_f32_e32 v53, v137, v137
	v_max_f32_e32 v52, v53, v52
	v_sub_f32_e32 v53, v137, v52
	v_sub_f32_e32 v52, v136, v52
	v_mul_f32_e32 v53, 0x3fb8aa3b, v53
	v_mul_f32_e32 v52, 0x3fb8aa3b, v52
	v_exp_f32_e32 v56, v53
	v_exp_f32_e32 v52, v52
	v_mul_f32_e32 v64, 0xbfb8aa3b, v81
	v_exp_f32_e32 v64, v64
	v_mul_f32_e32 v75, 0xbfb8aa3b, v75
	v_add_f32_e32 v57, v56, v52
	v_div_scale_f32 v52, s[20:21], v57, v57, v56
	v_rcp_f32_e32 v53, v52
	v_mul_f32_e32 v74, 0xbfb8aa3b, v74
	v_fma_f32 v54, -v52, v53, 1.0
	v_fmac_f32_e32 v53, v54, v53
	v_div_scale_f32 v54, vcc, v56, v57, v56
	v_mul_f32_e32 v55, v54, v53
	v_fma_f32 v58, -v52, v55, v54
	v_fmac_f32_e32 v55, v58, v53
	v_fma_f32 v52, -v52, v55, v54
	v_mul_f32_e32 v54, 0xbfb8aa3b, v68
	v_exp_f32_e32 v54, v54
	v_mul_f32_e32 v58, 0xbfb8aa3b, v99
	v_exp_f32_e32 v58, v58
	v_div_fmas_f32 v59, v52, v53, v55
	v_add_f32_e32 v52, 1.0, v54
	v_mul_f32_e32 v54, 0xbfb8aa3b, v98
	v_exp_f32_e32 v54, v54
	v_mul_f32_e32 v55, 0xbfb8aa3b, v93
	v_rcp_f32_e32 v53, v52
	v_add_f32_e32 v52, 1.0, v58
	v_exp_f32_e32 v58, v55
	v_add_f32_e32 v54, 1.0, v54
	v_rcp_f32_e32 v55, v54
	v_div_fixup_f32 v62, v59, v57, v56
	v_add_f32_e32 v54, 1.0, v58
	v_rcp_f32_e32 v54, v54
	v_sub_f32_e32 v68, 1.0, v62
	v_rcp_f32_e32 v52, v52
	v_mul_f32_e32 v59, 0xbfb8aa3b, v87
	v_fma_f32 v60, v68, v54, v62
	v_fma_f32 v61, v68, v55, v62
	v_mul_f32_e32 v54, 0xbfb8aa3b, v92
	v_exp_f32_e32 v54, v54
	v_mul_f32_e32 v55, 0xbfb8aa3b, v91
	v_exp_f32_e32 v58, v55
	v_fma_f32 v56, v68, v52, v62
	v_fma_f32 v57, v68, v53, v62
	v_add_f32_e32 v54, 1.0, v54
	v_rcp_f32_e32 v55, v54
	v_add_f32_e32 v54, 1.0, v58
	v_mul_f32_e32 v58, 0xbfb8aa3b, v90
	v_exp_f32_e32 v58, v58
	v_exp_f32_e32 v63, v59
	v_rcp_f32_e32 v54, v54
	v_pk_mov_b32 v[52:53], v[60:61], v[56:57] op_sel:[1,0]
	v_add_f32_e32 v58, 1.0, v58
	v_rcp_f32_e32 v59, v58
	v_add_f32_e32 v58, 1.0, v63
	v_rcp_f32_e32 v58, v58
	v_fma_f32 v66, v68, v54, v62
	v_fma_f32 v67, v68, v55, v62
	v_pk_mov_b32 v[54:55], v[66:67], v[60:61] op_sel:[1,0]
	v_add_f32_e64 v52, -v52, 1.0
	v_add_f32_e64 v53, -v53, 1.0
	v_fma_f32 v70, v68, v58, v62
	v_fma_f32 v71, v68, v59, v62
	v_mul_f32_e32 v63, 0xbfb8aa3b, v86
	v_exp_f32_e32 v63, v63
	v_pk_mov_b32 v[58:59], v[70:71], v[66:67] op_sel:[1,0]
	v_add_f32_e64 v54, -v54, 1.0
	v_add_f32_e64 v55, -v55, 1.0
	v_add_f32_e64 v58, -v58, 1.0
	v_add_f32_e64 v59, -v59, 1.0
	v_add_f32_e32 v63, 1.0, v63
	v_rcp_f32_e32 v65, v63
	v_add_f32_e32 v63, 1.0, v64
	v_mul_f32_e32 v64, 0xbfb8aa3b, v80
	v_exp_f32_e32 v72, v64
	v_mul_f32_e32 v64, 0xbfb8aa3b, v77
	v_exp_f32_e32 v77, v64
	v_rcp_f32_e32 v64, v63
	v_add_f32_e32 v63, 1.0, v72
	v_rcp_f32_e32 v73, v63
	v_add_f32_e32 v63, 1.0, v77
	v_rcp_f32_e32 v72, v63
	v_fma_f32 v78, v68, v64, v62
	v_fma_f32 v79, v68, v65, v62
	v_pk_mov_b32 v[64:65], v[78:79], v[70:71] op_sel:[1,0]
	v_fma_f32 v84, v68, v72, v62
	v_fma_f32 v85, v68, v73, v62
	v_mul_f32_e32 v63, 0xbfb8aa3b, v76
	v_exp_f32_e32 v63, v63
	v_exp_f32_e32 v76, v75
	v_mul_f32_e32 v69, 0xbfb8aa3b, v69
	v_exp_f32_e32 v69, v69
	v_add_f32_e32 v63, 1.0, v63
	v_rcp_f32_e32 v75, v63
	v_add_f32_e32 v63, 1.0, v76
	v_exp_f32_e32 v76, v74
	v_rcp_f32_e32 v74, v63
	v_pk_mov_b32 v[72:73], v[84:85], v[78:79] op_sel:[1,0]
	v_add_f32_e64 v64, -v64, 1.0
	v_add_f32_e64 v65, -v65, 1.0
	v_add_f32_e32 v63, 1.0, v76
	v_rcp_f32_e32 v76, v63
	v_add_f32_e32 v63, 1.0, v69
	v_rcp_f32_e32 v77, v63
	v_fma_f32 v94, v68, v74, v62
	v_fma_f32 v95, v68, v75, v62
	v_pk_mov_b32 v[74:75], v[94:95], v[84:85] op_sel:[1,0]
	v_add_f32_e64 v72, -v72, 1.0
	v_add_f32_e64 v73, -v73, 1.0
	v_fma_f32 v96, v68, v76, v62
	v_fma_f32 v97, v68, v77, v62
	v_mov_b32_e32 v62, v96
	v_mov_b32_e32 v63, v94
	v_add_f32_e64 v88, -v62, 1.0
	v_add_f32_e64 v89, -v63, 1.0
	v_mov_b32_e32 v62, v57
	v_mov_b32_e32 v63, v97
	v_add_f32_e64 v82, -v74, 1.0
	v_add_f32_e64 v83, -v75, 1.0
	v_add_f32_e64 v62, -v62, 1.0
	v_add_f32_e64 v63, -v63, 1.0
.LBB0_298:
	v_mul_f32_e32 v80, v97, v96
	v_mul_f32_e32 v81, v96, v97
	v_mul_f32_e32 v86, v80, v94
	v_mul_f32_e32 v87, v81, v95
	v_mul_f32_e32 v68, v97, v88
	v_mul_f32_e32 v69, v96, v89
	v_mov_b32_e32 v96, v86
	v_mov_b32_e32 v97, v80
	v_mov_b32_e32 v88, v82
	v_mul_f32_e32 v86, v86, v95
	v_mul_f32_e32 v87, v87, v94
	v_mul_f32_e32 v80, v96, v88
	v_mul_f32_e32 v81, v97, v89
	v_mul_f32_e32 v88, v86, v84
	v_mul_f32_e32 v89, v87, v85
	v_mov_b32_e32 v95, v86
	v_pk_mul_f32 v[84:85], v[88:89], v[84:85] op_sel:[0,1] op_sel_hi:[1,0]
	v_lshlrev_b32_e32 v69, 16, v132
	v_mul_f32_e32 v86, v84, v78
	v_mul_f32_e32 v87, v85, v79
	v_mov_b32_e32 v89, v84
	v_pk_mul_f32 v[78:79], v[86:87], v[78:79] op_sel:[0,1] op_sel_hi:[1,0]
	v_or_b32_sdwa v74, v69, v126 dst_sel:DWORD dst_unused:UNUSED_PAD src0_sel:DWORD src1_sel:WORD_0
	v_mul_f32_e32 v84, v78, v70
	v_mul_f32_e32 v85, v79, v71
	v_mov_b32_e32 v87, v78
	v_pk_mul_f32 v[70:71], v[84:85], v[70:71] op_sel:[0,1] op_sel_hi:[1,0]
	s_waitcnt lgkmcnt(12)
	v_lshlrev_b32_e32 v69, 16, v133
	v_mul_f32_e32 v78, v70, v66
	v_mul_f32_e32 v79, v71, v67
	v_mov_b32_e32 v94, v88
	v_mov_b32_e32 v82, v72
	v_mov_b32_e32 v88, v86
	v_mov_b32_e32 v72, v64
	v_mov_b32_e32 v86, v84
	v_mov_b32_e32 v64, v58
	v_mov_b32_e32 v84, v78
	v_mov_b32_e32 v85, v70
	v_mov_b32_e32 v58, v54
	v_or_b32_sdwa v75, v69, v127 dst_sel:DWORD dst_unused:UNUSED_PAD src0_sel:DWORD src1_sel:WORD_0
	s_waitcnt lgkmcnt(10)
	v_lshlrev_b32_e32 v69, 16, v134
	v_mul_f32_e32 v70, v84, v58
	v_mul_f32_e32 v71, v85, v59
	v_mul_f32_e32 v58, v78, v67
	v_mul_f32_e32 v59, v79, v66
	v_or_b32_sdwa v76, v69, v130 dst_sel:DWORD dst_unused:UNUSED_PAD src0_sel:DWORD src1_sel:WORD_0
	s_waitcnt lgkmcnt(8)
	v_lshlrev_b32_e32 v69, 16, v135
	v_mul_f32_e32 v66, v58, v60
	v_mul_f32_e32 v67, v59, v61
	v_or_b32_sdwa v77, v69, v131 dst_sel:DWORD dst_unused:UNUSED_PAD src0_sel:DWORD src1_sel:WORD_0
	s_waitcnt lgkmcnt(6)
	v_lshlrev_b32_e32 v69, 16, v122
	v_mov_b32_e32 v79, v58
	v_mul_f32_e32 v58, v66, v61
	v_mul_f32_e32 v59, v67, v60
	v_or_b32_sdwa v90, v69, v118 dst_sel:DWORD dst_unused:UNUSED_PAD src0_sel:DWORD src1_sel:WORD_0
	s_waitcnt lgkmcnt(4)
	v_lshlrev_b32_e32 v69, 16, v123
	v_mul_f32_e32 v60, v58, v56
	v_mul_f32_e32 v61, v59, v57
	v_or_b32_sdwa v91, v69, v119 dst_sel:DWORD dst_unused:UNUSED_PAD src0_sel:DWORD src1_sel:WORD_0
	s_waitcnt lgkmcnt(2)
	v_lshlrev_b32_e32 v69, 16, v124
	v_mov_b32_e32 v54, v52
	v_mul_f32_e32 v52, v60, v57
	v_or_b32_sdwa v92, v69, v120 dst_sel:DWORD dst_unused:UNUSED_PAD src0_sel:DWORD src1_sel:WORD_0
	s_waitcnt lgkmcnt(0)
	v_lshlrev_b32_e32 v69, 16, v125
	ds_write_b32 v104, v52 offset:40960
	v_add_u32_e32 v52, v106, v105
	v_or_b32_sdwa v93, v69, v121 dst_sel:DWORD dst_unused:UNUSED_PAD src0_sel:DWORD src1_sel:WORD_0
	ds_write_b128 v52, v[74:77] offset:20480
	ds_write_b128 v52, v[90:93] offset:20496
	v_mov_b32_e32 v78, v66
	s_waitcnt lgkmcnt(0)
	s_barrier
	v_mul_f32_e32 v78, v78, v54
	v_mul_f32_e32 v79, v79, v55
	ds_read2st64_b32 v[54:55], v109 offset0:160 offset1:162
	ds_read2st64_b32 v[56:57], v109 offset0:164 offset1:166
	v_mov_b32_e32 v61, v58
	v_mov_b32_e32 v52, v62
	v_mul_f32_e32 v52, v60, v52
	v_mul_f32_e32 v53, v61, v53
	s_waitcnt lgkmcnt(1)
	v_cndmask_b32_e64 v58, 1.0, v55, s[4:5]
	s_waitcnt lgkmcnt(0)
	v_mul_f32_e32 v58, v58, v56
	v_cndmask_b32_e64 v58, 1.0, v58, s[6:7]
	v_mul_f32_e32 v58, v57, v58
	v_cndmask_b32_e64 v62, 1.0, v58, s[8:9]
	v_mul_f32_e32 v52, v52, v62
	v_mul_f32_e32 v53, v53, v62
	v_mul_f32_e32 v64, v86, v64
	v_mul_f32_e32 v65, v87, v65
	v_cvt_pk_bf16_f32 v58, v52, v53
	v_mul_f32_e32 v52, v78, v62
	v_mul_f32_e32 v53, v79, v62
	v_mul_f32_e32 v72, v88, v72
	v_mul_f32_e32 v73, v89, v73
	v_cvt_pk_bf16_f32 v59, v52, v53
	v_mul_f32_e32 v52, v70, v62
	v_mul_f32_e32 v53, v71, v62
	v_mul_f32_e32 v82, v94, v82
	v_mul_f32_e32 v83, v95, v83
	v_cvt_pk_bf16_f32 v60, v52, v53
	v_mul_f32_e32 v52, v64, v62
	v_mul_f32_e32 v53, v65, v62
	v_mov_b32_e32 v69, v63
	v_cvt_pk_bf16_f32 v61, v52, v53
	v_mul_f32_e32 v52, v72, v62
	v_mul_f32_e32 v53, v73, v62
	s_nop 0
	v_cvt_pk_bf16_f32 v64, v52, v53
	v_mul_f32_e32 v52, v82, v62
	v_mul_f32_e32 v53, v83, v62
	s_nop 0
	v_cvt_pk_bf16_f32 v65, v52, v53
	v_mul_f32_e32 v52, v80, v62
	v_mul_f32_e32 v53, v81, v62
	s_nop 0
	v_cvt_pk_bf16_f32 v66, v52, v53
	v_mul_f32_e32 v52, v68, v62
	v_mul_f32_e32 v53, v69, v62
	s_nop 0
	v_cvt_pk_bf16_f32 v67, v52, v53
	v_add_u32_e32 v52, v110, v105
	ds_write_b128 v52, v[58:61]
	ds_write_b128 v52, v[64:67] offset:16
	s_and_saveexec_b64 s[20:21], s[4:5]
	v_mul_f32_e32 v52, v54, v55
	v_mul_f32_e32 v52, v52, v56
	v_mul_f32_e32 v52, v52, v57
	v_mul_f32_e32 v101, v101, v52
	ds_write_b32 v114, v52 offset:43008
	s_or_b64 exec, exec, s[20:21]
	s_waitcnt lgkmcnt(0)
	s_barrier
	ds_read_b128 v[52:55], v111 offset:43008
	ds_read_b128 v[56:59], v111 offset:43072
	ds_read_b128 v[62:65], v115
	s_add_u32 s16, s16, 1
	s_addc_u32 s17, s17, 0
	s_waitcnt lgkmcnt(2)
	v_mul_f32_e32 v30, v30, v54
	v_mul_f32_e32 v31, v31, v55
	v_mul_f32_e32 v28, v28, v52
	v_mul_f32_e32 v29, v29, v53
	ds_read_b128 v[52:55], v111 offset:43136
	s_waitcnt lgkmcnt(2)
	v_mul_f32_e32 v26, v26, v58
	v_mul_f32_e32 v27, v27, v59
	ds_read_b128 v[58:61], v111 offset:43200
	v_mul_f32_e32 v24, v24, v56
	v_mul_f32_e32 v25, v25, v57
	s_cmp_eq_u32 s16, 16
	s_waitcnt lgkmcnt(1)
	v_mul_f32_e32 v22, v22, v54
	v_mul_f32_e32 v23, v23, v55
	v_mul_f32_e32 v20, v20, v52
	v_mul_f32_e32 v21, v21, v53
	ds_read_b128 v[52:55], v112 offset:20480
	s_waitcnt lgkmcnt(1)
	v_mul_f32_e32 v16, v16, v58
	v_mul_f32_e32 v17, v17, v59
	ds_read_b128 v[56:59], v115 offset:2560
	ds_read_b128 v[66:69], v112 offset:20544
	ds_read_b128 v[70:73], v115 offset:64
	v_mul_f32_e32 v18, v18, v60
	v_mul_f32_e32 v19, v19, v61
	s_waitcnt lgkmcnt(3)
	v_mfma_f32_16x16x32_bf16 v[28:31], v[62:65], v[52:55], v[28:31]
	ds_read_b128 v[60:63], v115 offset:5120
	ds_read_b128 v[74:77], v111 offset:43264
	ds_read_b128 v[78:81], v111 offset:43328
	ds_read_b128 v[82:85], v115 offset:7680
	ds_read_b128 v[86:89], v115 offset:2624
	s_waitcnt lgkmcnt(3)
	v_mul_f32_e32 v14, v14, v76
	v_mul_f32_e32 v15, v15, v77
	v_mfma_f32_16x16x32_bf16 v[24:27], v[56:59], v[52:55], v[24:27]
	ds_read_b128 v[56:59], v115 offset:10240
	ds_read_b128 v[90:93], v115 offset:5184
	v_mul_f32_e32 v12, v12, v74
	v_mul_f32_e32 v13, v13, v75
	ds_read_b128 v[74:77], v115 offset:12800
	v_mfma_f32_16x16x32_bf16 v[20:23], v[60:63], v[52:55], v[20:23]
	s_waitcnt lgkmcnt(5)
	v_mul_f32_e32 v10, v10, v80
	v_mul_f32_e32 v11, v11, v81
	ds_read_b128 v[60:63], v115 offset:7744
	v_mul_f32_e32 v8, v8, v78
	v_mul_f32_e32 v9, v9, v79
	s_waitcnt lgkmcnt(5)
	v_mfma_f32_16x16x32_bf16 v[16:19], v[82:85], v[52:55], v[16:19]
	ds_read_b128 v[78:81], v115 offset:10304
	s_waitcnt lgkmcnt(4)
	v_mfma_f32_16x16x32_bf16 v[12:15], v[56:59], v[52:55], v[12:15]
	ds_read_b128 v[56:59], v115 offset:15360
	ds_read_b128 v[82:85], v111 offset:43392
	ds_read_b128 v[94:97], v111 offset:43456
	ds_read_b128 v[118:121], v115 offset:17920
	ds_read_b128 v[122:125], v115 offset:12864
	s_waitcnt lgkmcnt(3)
	v_mul_f32_e32 v2, v2, v84
	v_mul_f32_e32 v3, v3, v85
	v_mul_f32_e32 v0, v0, v82
	v_mul_f32_e32 v1, v1, v83
	v_mfma_f32_16x16x32_bf16 v[8:11], v[74:77], v[52:55], v[8:11]
	ds_read_b128 v[74:77], v115 offset:15424
	s_waitcnt lgkmcnt(3)
	v_mul_f32_e32 v6, v6, v96
	v_mul_f32_e32 v7, v7, v97
	v_mul_f32_e32 v4, v4, v94
	v_mul_f32_e32 v5, v5, v95
	v_mfma_f32_16x16x32_bf16 v[0:3], v[56:59], v[52:55], v[0:3]
	ds_read_b128 v[56:59], v115 offset:17984
	s_waitcnt lgkmcnt(0)
	s_barrier
	s_waitcnt lgkmcnt(3)
	v_mfma_f32_16x16x32_bf16 v[4:7], v[118:121], v[52:55], v[4:7]
	s_waitcnt vmcnt(5)
	ds_write_b128 v107, v[32:35]
	s_waitcnt vmcnt(4)
	ds_write_b128 v107, v[36:39] offset:20480
	s_waitcnt vmcnt(3)
	ds_write_b128 v108, v[40:43]
	s_waitcnt vmcnt(2)
	ds_write_b128 v108, v[44:47] offset:20480
	s_waitcnt lgkmcnt(0)
	v_mfma_f32_16x16x32_bf16 v[28:31], v[70:73], v[66:69], v[28:31]
	s_barrier
	v_mfma_f32_16x16x32_bf16 v[24:27], v[86:89], v[66:69], v[24:27]
	v_mfma_f32_16x16x32_bf16 v[20:23], v[90:93], v[66:69], v[20:23]
	v_mfma_f32_16x16x32_bf16 v[16:19], v[60:63], v[66:69], v[16:19]
	v_mfma_f32_16x16x32_bf16 v[12:15], v[78:81], v[66:69], v[12:15]
	s_waitcnt lgkmcnt(6)
	v_mfma_f32_16x16x32_bf16 v[8:11], v[122:125], v[66:69], v[8:11]
	s_waitcnt lgkmcnt(5)
	v_mfma_f32_16x16x32_bf16 v[0:3], v[74:77], v[66:69], v[0:3]
	s_waitcnt lgkmcnt(4)
	v_mfma_f32_16x16x32_bf16 v[4:7], v[56:59], v[66:69], v[4:7]
	s_cbranch_scc1 .LBB0_302
	s_waitcnt vmcnt(0)
	v_mov_b32_e32 v136, v117
	v_mov_b32_e32 v137, v116
	s_branch .LBB0_294

.LBB0_429:
	s_or_b64 exec, exec, s[70:71]
	s_waitcnt lgkmcnt(0)
	s_barrier
	s_waitcnt lgkmcnt(0)
	ds_read2st64_b32 v[60:61], v135 offset1:1
	s_lshr_b32 s70, s56, 7
	s_and_b32 s56, s97, 0xffffe000
	s_and_b32 s71, s78, 0x1fc0
	s_or_b32 s56, s56, s71
	s_waitcnt lgkmcnt(0)
	v_add_f32_e32 v60, v60, v61
	v_fmamk_f32 v60, v60, 0x3c000000, v150
	v_cmp_gt_f32_e32 vcc, s80, v60
	v_mul_f32_e32 v61, 0x4b800000, v60
	v_mov_b32_e32 v71, v69
	v_cndmask_b32_e32 v60, v60, v61, vcc
	v_rsq_f32_e32 v60, v60
	s_add_i32 s78, s78, s79
	s_add_i32 s97, s97, s33
	s_waitcnt vmcnt(0)
	v_mov_b32_e32 v92, v157
	v_mul_f32_e32 v61, 0x45800000, v60
	v_cndmask_b32_e32 v72, v60, v61, vcc
	v_or_b32_e32 v60, s56, v134
	v_ashrrev_i32_e32 v61, 31, v60
	v_lshlrev_b64 v[60:61], 11, v[60:61]
	v_lshl_add_u64 v[60:61], s[48:49], 0, v[60:61]
	s_lshl_b32 s56, s82, 8
	v_lshl_add_u64 v[78:79], v[60:61], 0, s[56:57]
	s_lshl_b32 s56, s70, 7
	s_and_b32 s56, s56, 0x200
	v_add_u32_e32 v73, s56, v143
	ds_read_b128 v[74:77], v73
	ds_read2_b64 v[60:63], v142 offset1:4
	v_mul_f32_e32 v64, v64, v72
	v_mul_f32_e32 v65, v65, v72
	v_mul_f32_e32 v66, v66, v72
	v_mul_f32_e32 v67, v67, v72
	v_mul_f32_e32 v56, v56, v72
	v_mul_f32_e32 v57, v57, v72
	s_waitcnt lgkmcnt(1)
	v_mul_f32_e32 v64, v74, v64
	v_mul_f32_e32 v65, v75, v65
	s_waitcnt lgkmcnt(0)
	v_lshlrev_b32_e32 v80, 16, v60
	v_and_b32_e32 v81, 0xffff0000, v60
	v_mul_f32_e32 v60, 0xbfb8aa3b, v80
	v_exp_f32_e32 v60, v60
	v_mul_f32_e32 v66, v76, v66
	v_mul_f32_e32 v67, v77, v67
	v_mul_f32_e32 v58, v58, v72
	v_mul_f32_e32 v59, v59, v72
	v_mul_f32_e32 v52, v52, v72
	v_mul_f32_e32 v53, v53, v72
	v_add_f32_e32 v60, 1.0, v60
	v_rcp_f32_e32 v82, v60
	v_mul_f32_e32 v60, 0xbfb8aa3b, v81
	v_exp_f32_e32 v60, v60
	v_mul_f32_e32 v54, v54, v72
	v_mul_f32_e32 v55, v55, v72
	v_mul_f32_e32 v48, v48, v72
	v_mul_f32_e32 v49, v49, v72
	v_mul_f32_e32 v50, v50, v72
	v_mul_f32_e32 v51, v51, v72
	v_add_f32_e32 v60, 1.0, v60
	v_rcp_f32_e32 v83, v60
	v_lshlrev_b32_e32 v60, 16, v61
	v_and_b32_e32 v61, 0xffff0000, v61
	s_andn2_b64 vcc, exec, s[68:69]
	v_mul_f32_e32 v74, v82, v80
	v_mul_f32_e32 v75, v83, v81
	s_mov_b32 s56, s81
	v_mul_f32_e32 v64, v64, v74
	v_mul_f32_e32 v65, v65, v75
	v_mov_b32_e32 v93, v156
	v_cvt_pk_bf16_f32 v64, v64, v65
	v_mul_f32_e32 v65, 0xbfb8aa3b, v60
	v_exp_f32_e32 v65, v65
	s_nop 0
	v_add_f32_e32 v65, 1.0, v65
	v_rcp_f32_e32 v74, v65
	v_mul_f32_e32 v65, 0xbfb8aa3b, v61
	v_exp_f32_e32 v65, v65
	s_nop 0
	v_add_f32_e32 v65, 1.0, v65
	v_rcp_f32_e32 v75, v65
	s_nop 0
	v_mul_f32_e32 v60, v74, v60
	v_mul_f32_e32 v61, v75, v61
	v_lshlrev_b32_e32 v74, 16, v62
	v_and_b32_e32 v75, 0xffff0000, v62
	v_mul_f32_e32 v62, 0xbfb8aa3b, v74
	v_exp_f32_e32 v62, v62
	v_mul_f32_e32 v60, v66, v60
	v_mul_f32_e32 v61, v67, v61
	v_add_f32_e32 v62, 1.0, v62
	v_rcp_f32_e32 v76, v62
	v_mul_f32_e32 v62, 0xbfb8aa3b, v75
	v_exp_f32_e32 v62, v62
	v_cvt_pk_bf16_f32 v65, v60, v61
	v_lshl_add_u64 v[60:61], v[78:79], 0, v[70:71]
	global_store_dwordx2 v[60:61], v[64:65], off
	ds_read_b128 v[64:67], v73 offset:64
	v_add_f32_e32 v62, 1.0, v62
	v_rcp_f32_e32 v77, v62
	v_lshlrev_b32_e32 v62, 16, v63
	v_and_b32_e32 v63, 0xffff0000, v63
	s_waitcnt lgkmcnt(0)
	v_mul_f32_e32 v56, v64, v56
	v_mul_f32_e32 v57, v65, v57
	v_mul_f32_e32 v64, v76, v74
	v_mul_f32_e32 v65, v77, v75
	v_mul_f32_e32 v58, v66, v58
	v_mul_f32_e32 v59, v67, v59
	v_mul_f32_e32 v56, v56, v64
	v_mul_f32_e32 v57, v57, v65
	s_nop 0
	v_cvt_pk_bf16_f32 v56, v56, v57
	v_mul_f32_e32 v57, 0xbfb8aa3b, v62
	v_exp_f32_e32 v57, v57
	s_nop 0
	v_add_f32_e32 v57, 1.0, v57
	v_rcp_f32_e32 v64, v57
	v_mul_f32_e32 v57, 0xbfb8aa3b, v63
	v_exp_f32_e32 v57, v57
	s_nop 0
	v_add_f32_e32 v57, 1.0, v57
	v_rcp_f32_e32 v65, v57
	s_nop 0
	v_mul_f32_e32 v62, v64, v62
	v_mul_f32_e32 v63, v65, v63
	s_nop 0
	v_mul_f32_e32 v58, v58, v62
	v_mul_f32_e32 v59, v59, v63
	s_nop 0
	v_cvt_pk_bf16_f32 v57, v58, v59
	global_store_dwordx2 v[60:61], v[56:57], off offset:32
	ds_read_b128 v[62:65], v73 offset:128
	ds_read2_b64 v[56:59], v142 offset0:8 offset1:12
	s_waitcnt lgkmcnt(1)
	v_mul_f32_e32 v52, v62, v52
	v_mul_f32_e32 v53, v63, v53
	s_waitcnt lgkmcnt(0)
	v_lshlrev_b32_e32 v66, 16, v56
	v_and_b32_e32 v67, 0xffff0000, v56
	v_mul_f32_e32 v56, 0xbfb8aa3b, v66
	v_exp_f32_e32 v56, v56
	v_mul_f32_e32 v54, v64, v54
	v_mul_f32_e32 v55, v65, v55
	v_add_f32_e32 v56, 1.0, v56
	v_rcp_f32_e32 v74, v56
	v_mul_f32_e32 v56, 0xbfb8aa3b, v67
	v_exp_f32_e32 v56, v56
	s_nop 0
	v_add_f32_e32 v56, 1.0, v56
	v_rcp_f32_e32 v75, v56
	v_lshlrev_b32_e32 v56, 16, v57
	v_and_b32_e32 v57, 0xffff0000, v57
	v_mul_f32_e32 v62, v74, v66
	v_mul_f32_e32 v63, v75, v67
	s_nop 0
	v_mul_f32_e32 v52, v52, v62
	v_mul_f32_e32 v53, v53, v63
	s_nop 0
	v_cvt_pk_bf16_f32 v52, v52, v53
	v_mul_f32_e32 v53, 0xbfb8aa3b, v56
	v_exp_f32_e32 v53, v53
	s_nop 0
	v_add_f32_e32 v53, 1.0, v53
	v_rcp_f32_e32 v62, v53
	v_mul_f32_e32 v53, 0xbfb8aa3b, v57
	v_exp_f32_e32 v53, v53
	s_nop 0
	v_add_f32_e32 v53, 1.0, v53
	v_rcp_f32_e32 v63, v53
	s_nop 0
	v_mul_f32_e32 v56, v62, v56
	v_mul_f32_e32 v57, v63, v57
	s_nop 0
	v_mul_f32_e32 v54, v54, v56
	v_mul_f32_e32 v55, v55, v57
	v_lshlrev_b32_e32 v56, 16, v58
	v_cvt_pk_bf16_f32 v53, v54, v55
	global_store_dwordx2 v[60:61], v[52:53], off offset:64
	ds_read_b128 v[52:55], v73 offset:192
	v_and_b32_e32 v57, 0xffff0000, v58
	v_mul_f32_e32 v58, 0xbfb8aa3b, v56
	v_exp_f32_e32 v58, v58
	s_waitcnt lgkmcnt(0)
	v_mul_f32_e32 v48, v48, v52
	v_mul_f32_e32 v49, v49, v53
	v_mul_f32_e32 v52, 0xbfb8aa3b, v57
	v_exp_f32_e32 v52, v52
	v_add_f32_e32 v58, 1.0, v58
	v_rcp_f32_e32 v62, v58
	v_mul_f32_e32 v50, v50, v54
	v_mul_f32_e32 v51, v51, v55
	v_add_f32_e32 v52, 1.0, v52
	v_rcp_f32_e32 v63, v52
	s_nop 0
	v_mul_f32_e32 v52, v62, v56
	v_mul_f32_e32 v53, v63, v57
	s_nop 0
	v_mul_f32_e32 v48, v48, v52
	v_mul_f32_e32 v49, v49, v53
	v_lshlrev_b32_e32 v52, 16, v59
	v_cvt_pk_bf16_f32 v48, v48, v49
	v_mul_f32_e32 v49, 0xbfb8aa3b, v52
	v_exp_f32_e32 v49, v49
	v_and_b32_e32 v53, 0xffff0000, v59
	v_add_f32_e32 v49, 1.0, v49
	v_rcp_f32_e32 v56, v49
	v_mul_f32_e32 v49, 0xbfb8aa3b, v53
	v_exp_f32_e32 v49, v49
	s_nop 0
	v_add_f32_e32 v49, 1.0, v49
	v_rcp_f32_e32 v57, v49
	s_nop 0
	v_mul_f32_e32 v52, v56, v52
	v_mul_f32_e32 v53, v57, v53
	s_nop 0
	v_mul_f32_e32 v50, v50, v52
	v_mul_f32_e32 v51, v51, v53
	s_nop 0
	v_cvt_pk_bf16_f32 v49, v50, v51
	global_store_dwordx2 v[60:61], v[48:49], off offset:96
	s_waitcnt lgkmcnt(0)
	s_barrier
	ds_write_b128 v126, v[28:31]
	ds_write_b128 v126, v[36:39] offset:18432
	ds_write_b128 v126, v[0:3] offset:36864
	ds_write_b128 v127, v[4:7]
	ds_write_b128 v132, v[8:11]
	ds_write_b128 v132, v[12:15] offset:18432
	ds_write_b128 v132, v[16:19] offset:36864
	ds_write_b128 v133, v[20:23]
	ds_write_b128 v151, v[24:27]
	ds_write_b128 v152, v[40:43]
	ds_write_b128 v151, v[32:35] offset:18432
	ds_write_b128 v153, v[44:47]
	s_waitcnt lgkmcnt(0)
	s_barrier
	s_cbranch_vccz .LBB0_445
.LBB0_430:
	s_add_i32 s81, s56, s84
	s_cmpk_gt_i32 s81, 0xfff
	s_cselect_b64 s[68:69], -1, 0
	s_cmpk_lt_i32 s81, 0x1000
	s_cselect_b32 s70, s81, s56
	s_ashr_i32 s71, s70, 31
	s_lshl_b64 s[82:83], s[70:71], 16
	s_add_u32 s82, s54, s82
	s_addc_u32 s83, s55, s83
	s_lshl_b64 s[90:91], s[70:71], 15
	s_and_b32 s89, s70, 0x180
	v_lshl_add_u64 v[16:17], s[82:83], 0, v[68:69]
	s_movk_i32 s70, 0x4000
	v_add_co_u32_e32 v32, vcc, s70, v16
	s_mov_b32 s70, 0x8000
	s_nop 0
	v_addc_co_u32_e32 v33, vcc, 0, v17, vcc
	v_add_co_u32_e32 v0, vcc, s70, v16
	s_mov_b32 s70, 0xc000
	s_nop 0
	v_addc_co_u32_e32 v1, vcc, 0, v17, vcc
	v_add_co_u32_e32 v4, vcc, s70, v16
	s_mov_b32 s70, 0xa000
	s_nop 0
	v_addc_co_u32_e32 v5, vcc, 0, v17, vcc
	v_add_co_u32_e32 v8, vcc, s3, v16
	v_or_b32_e32 v48, s89, v136
	s_nop 0
	v_addc_co_u32_e32 v9, vcc, 0, v17, vcc
	v_add_co_u32_e32 v12, vcc, s77, v16
	v_lshlrev_b32_e32 v48, 2, v48
	s_nop 0
	v_addc_co_u32_e32 v13, vcc, 0, v17, vcc
	v_add_co_u32_e32 v18, vcc, s70, v16
	s_mov_b32 s70, 0xe000
	s_nop 0
	v_addc_co_u32_e32 v19, vcc, 0, v17, vcc
	v_add_co_u32_e32 v20, vcc, s70, v16
	s_add_u32 s70, s76, s90
	s_addc_u32 s71, s61, s91
	v_addc_co_u32_e32 v21, vcc, 0, v17, vcc
	v_lshl_add_u64 v[40:41], s[70:71], 0, v[68:69]
	v_add_co_u32_e32 v42, vcc, s3, v40
	global_load_dwordx4 v[0:3], v[0:1], off
	s_nop 0
	global_load_dwordx4 v[4:7], v[4:5], off
	v_addc_co_u32_e32 v43, vcc, 0, v41, vcc
	v_add_co_u32_e32 v44, vcc, s77, v40
	global_load_dwordx4 v[8:11], v[8:9], off
	s_nop 0
	global_load_dwordx4 v[12:15], v[12:13], off
	v_addc_co_u32_e32 v45, vcc, 0, v41, vcc
	global_load_dwordx4 v[16:19], v[18:19], off
	s_nop 0
	global_load_dwordx4 v[20:23], v[20:21], off
	s_nop 0
	global_load_dwordx4 v[28:31], v68, s[82:83]
	global_load_dwordx4 v[24:27], v68, s[70:71]
	global_load_dwordx4 v[36:39], v[32:33], off
	s_nop 0
	global_load_dwordx4 v[32:35], v125, s[70:71]
	s_nop 0
	global_load_dwordx4 v[40:43], v[42:43], off
	s_nop 0
	global_load_dwordx4 v[44:47], v[44:45], off
	s_nop 0
	global_load_dword v156, v48, s[62:63]
	global_load_dword v157, v48, s[62:63] offset:2048
	ds_read_u16 v48, v144
	ds_read_u16 v49, v144 offset:288
	ds_read_u16 v50, v144 offset:576
	ds_read_u16 v51, v144 offset:864
	ds_read_u16 v52, v144 offset:1152
	ds_read_u16 v53, v144 offset:1440
	ds_read_u16 v54, v144 offset:1728
	ds_read_u16 v55, v144 offset:2016
	ds_read_u16 v64, v144 offset:2304
	ds_read_u16 v65, v144 offset:2592
	ds_read_u16 v66, v144 offset:2880
	ds_read_u16 v67, v144 offset:3168
	ds_read_u16 v72, v144 offset:3456
	ds_read_u16 v73, v144 offset:3744
	ds_read_u16 v74, v144 offset:4032
	ds_read_u16 v75, v144 offset:4320
	ds_read_u16 v56, v144 offset:18432
	ds_read_u16 v57, v144 offset:18720
	ds_read_u16 v58, v144 offset:19008
	ds_read_u16 v59, v144 offset:19296
	ds_read_u16 v60, v144 offset:19584
	ds_read_u16 v61, v144 offset:19872
	ds_read_u16 v62, v144 offset:20160
	ds_read_u16 v63, v144 offset:20448
	ds_read_u16 v76, v144 offset:20736
	ds_read_u16 v77, v144 offset:21024
	ds_read_u16 v78, v144 offset:21312
	ds_read_u16 v79, v144 offset:21600
	ds_read_u16 v80, v144 offset:21888
	ds_read_u16 v82, v144 offset:22176
	ds_read_u16 v83, v144 offset:22464
	ds_read_u16 v84, v144 offset:22752
	ds_read_u16 v166, v144 offset:36864
	ds_read_u16 v170, v144 offset:37152
	ds_read_u16 v167, v144 offset:37440
	ds_read_u16 v171, v144 offset:37728
	ds_read_u16 v168, v144 offset:38016
	ds_read_u16 v172, v144 offset:38304
	ds_read_u16 v169, v144 offset:38592
	ds_read_u16 v173, v144 offset:38880
	ds_read_u16 v71, v144 offset:39168
	ds_read_u16 v162, v144 offset:39456
	ds_read_u16 v159, v144 offset:39744
	ds_read_u16 v163, v144 offset:40032
	ds_read_u16 v160, v144 offset:40320
	ds_read_u16 v164, v144 offset:40608
	ds_read_u16 v161, v144 offset:40896
	ds_read_u16 v165, v144 offset:41184
	s_waitcnt lgkmcnt(0)
	s_barrier
	s_bfe_u32 s82, s56, 0x30007
	s_cmp_gt_u32 s82, 3
	s_waitcnt lgkmcnt(14)
	v_lshlrev_b32_e32 v115, 16, v56
	v_lshlrev_b32_e32 v114, 16, v57
	v_lshlrev_b32_e32 v111, 16, v58
	v_lshlrev_b32_e32 v110, 16, v59
	v_lshlrev_b32_e32 v105, 16, v60
	v_lshlrev_b32_e32 v104, 16, v61
	v_lshlrev_b32_e32 v103, 16, v62
	v_lshlrev_b32_e32 v102, 16, v63
	v_lshlrev_b32_e32 v97, 16, v76
	v_lshlrev_b32_e32 v96, 16, v77
	v_lshlrev_b32_e32 v89, 16, v78
	v_lshlrev_b32_e32 v88, 16, v79
	v_lshlrev_b32_e32 v81, 16, v80
	v_lshlrev_b32_e32 v80, 16, v82
	v_lshlrev_b32_e32 v77, 16, v83
	v_lshlrev_b32_e32 v76, 16, v84
	v_lshlrev_b32_e32 v63, 16, v48
	v_lshlrev_b32_e32 v62, 16, v49
	v_lshlrev_b32_e32 v61, 16, v50
	v_lshlrev_b32_e32 v60, 16, v51
	v_lshlrev_b32_e32 v59, 16, v52
	v_lshlrev_b32_e32 v58, 16, v53
	v_lshlrev_b32_e32 v57, 16, v54
	v_lshlrev_b32_e32 v56, 16, v55
	v_lshlrev_b32_e32 v55, 16, v64
	v_lshlrev_b32_e32 v54, 16, v65
	v_lshlrev_b32_e32 v53, 16, v66
	v_lshlrev_b32_e32 v52, 16, v67
	v_lshlrev_b32_e32 v51, 16, v72
	v_lshlrev_b32_e32 v50, 16, v73
	v_lshlrev_b32_e32 v49, 16, v74
	v_lshlrev_b32_e32 v48, 16, v75
	s_cbranch_scc0 .LBB0_432
	s_add_i32 s70, s82, -4
	v_cvt_f32_u32_e32 v72, s70
	s_mov_b32 s70, 0xc2fc0000
	v_mul_f32_e32 v64, s60, v114
	v_mul_f32_e32 v65, s60, v115
	v_mul_f32_e32 v66, s60, v110
	v_mul_f32_e32 v67, s60, v111
	v_sub_f32_e32 v72, 0xc0a00000, v72
	v_cmp_gt_f32_e32 vcc, s70, v72
	s_and_b64 s[70:71], vcc, exec
	s_cselect_b32 s70, 0xffffffc0, 0
	v_cndmask_b32_e32 v73, 0, v154, vcc
	v_add_f32_e32 v72, v72, v73
	v_exp_f32_e32 v74, v72
	v_mul_f32_e32 v72, s60, v104
	v_mul_f32_e32 v73, s60, v105
	v_mul_f32_e32 v78, s60, v102
	v_mul_f32_e32 v79, s60, v103
	v_mul_f32_e32 v82, s60, v96
	v_mul_f32_e32 v83, s60, v97
	v_ldexp_f32 v74, v74, s70
	v_sub_f32_e32 v118, 1.0, v74
	v_mul_f32_e32 v84, s60, v88
	v_mul_f32_e32 v85, s60, v89
	v_mul_f32_e32 v94, s60, v80
	v_mul_f32_e32 v95, s60, v81
	v_mul_f32_e32 v90, s60, v76
	v_mul_f32_e32 v91, s60, v77
	s_mov_b64 s[70:71], 0
	v_mov_b64_e32 v[116:117], v[118:119]
	s_branch .LBB0_433

.LBB0_433:
	v_mov_b64_e32 v[112:113], v[116:117]
	v_mov_b64_e32 v[108:109], v[116:117]
	v_mov_b64_e32 v[106:107], v[116:117]
	v_mov_b64_e32 v[100:101], v[116:117]
	v_mov_b64_e32 v[98:99], v[116:117]
	v_mov_b64_e32 v[86:87], v[116:117]
	v_mov_b64_e32 v[74:75], v[116:117]
	s_andn2_b64 vcc, exec, s[70:71]
	v_mov_b32_e32 v113, v118
	v_mov_b32_e32 v109, v118
	v_mov_b32_e32 v107, v118
	v_mov_b32_e32 v101, v118
	v_mov_b32_e32 v99, v118
	v_mov_b32_e32 v87, v118
	v_mov_b32_e32 v75, v118
	s_cbranch_vccnz .LBB0_435
	v_max_f32_e32 v64, v92, v92
	v_max_f32_e32 v65, v93, v93
	v_max_f32_e32 v64, v65, v64
	v_sub_f32_e32 v65, v93, v64
	v_sub_f32_e32 v64, v92, v64
	v_mul_f32_e32 v65, 0x3fb8aa3b, v65
	v_mul_f32_e32 v64, 0x3fb8aa3b, v64
	v_exp_f32_e32 v65, v65
	v_exp_f32_e32 v64, v64
	v_mul_f32_e32 v84, 0xbfb8aa3b, v55
	v_exp_f32_e32 v84, v84
	v_mul_f32_e32 v78, 0xbfb8aa3b, v59
	v_add_f32_e32 v64, v65, v64
	v_div_scale_f32 v66, s[70:71], v64, v64, v65
	v_rcp_f32_e32 v67, v66
	v_mul_f32_e32 v82, 0xbfb8aa3b, v57
	v_add_f32_e32 v84, 1.0, v84
	v_exp_f32_e32 v78, v78
	v_fma_f32 v72, -v66, v67, 1.0
	v_fmac_f32_e32 v67, v72, v67
	v_div_scale_f32 v72, vcc, v65, v64, v65
	v_mul_f32_e32 v73, v72, v67
	v_fma_f32 v74, -v66, v73, v72
	v_fmac_f32_e32 v73, v74, v67
	v_fma_f32 v66, -v66, v73, v72
	v_div_fmas_f32 v66, v66, v67, v73
	v_div_fixup_f32 v90, v66, v64, v65
	v_mul_f32_e32 v66, 0xbfb8aa3b, v63
	v_mul_f32_e32 v72, 0xbfb8aa3b, v61
	v_exp_f32_e32 v66, v66
	v_exp_f32_e32 v72, v72
	v_exp_f32_e32 v82, v82
	v_rcp_f32_e32 v85, v84
	v_mul_f32_e32 v84, 0xbfb8aa3b, v54
	v_exp_f32_e32 v84, v84
	v_add_f32_e32 v66, 1.0, v66
	v_add_f32_e32 v72, 1.0, v72
	v_add_f32_e32 v78, 1.0, v78
	v_add_f32_e32 v82, 1.0, v82
	v_rcp_f32_e32 v67, v66
	v_mul_f32_e32 v66, 0xbfb8aa3b, v62
	v_rcp_f32_e32 v73, v72
	v_mul_f32_e32 v72, 0xbfb8aa3b, v60
	v_rcp_f32_e32 v79, v78
	v_mul_f32_e32 v78, 0xbfb8aa3b, v58
	v_rcp_f32_e32 v83, v82
	v_mul_f32_e32 v82, 0xbfb8aa3b, v56
	v_add_f32_e32 v84, 1.0, v84
	v_exp_f32_e32 v66, v66
	v_exp_f32_e32 v72, v72
	v_exp_f32_e32 v78, v78
	v_exp_f32_e32 v82, v82
	v_rcp_f32_e32 v84, v84
	v_mul_f32_e32 v81, 0xbfb8aa3b, v81
	v_mul_f32_e32 v80, 0xbfb8aa3b, v80
	v_mul_f32_e32 v77, 0xbfb8aa3b, v77
	v_mul_f32_e32 v76, 0xbfb8aa3b, v76
	v_exp_f32_e32 v81, v81
	v_exp_f32_e32 v80, v80
	v_exp_f32_e32 v77, v77
	v_exp_f32_e32 v76, v76
	v_add_f32_e32 v66, 1.0, v66
	v_add_f32_e32 v72, 1.0, v72
	v_add_f32_e32 v78, 1.0, v78
	v_add_f32_e32 v82, 1.0, v82
	v_mul_f32_e32 v54, v84, v54
	v_mul_f32_e32 v55, v85, v55
	v_mul_f32_e32 v84, 0xbfb8aa3b, v89
	v_rcp_f32_e32 v66, v66
	v_rcp_f32_e32 v72, v72
	v_rcp_f32_e32 v78, v78
	v_rcp_f32_e32 v82, v82
	v_exp_f32_e32 v84, v84
	v_add_f32_e32 v81, 1.0, v81
	v_add_f32_e32 v80, 1.0, v80
	v_add_f32_e32 v77, 1.0, v77
	v_add_f32_e32 v76, 1.0, v76
	v_rcp_f32_e32 v81, v81
	v_rcp_f32_e32 v80, v80
	v_rcp_f32_e32 v77, v77
	v_rcp_f32_e32 v76, v76
	v_sub_f32_e32 v92, 1.0, v90
	v_mul_f32_e32 v64, 0xbfb8aa3b, v115
	v_mul_f32_e32 v62, v66, v62
	v_mul_f32_e32 v63, v67, v63
	v_mul_f32_e32 v66, 0xbfb8aa3b, v111
	v_mul_f32_e32 v60, v72, v60
	v_mul_f32_e32 v61, v73, v61
	v_mul_f32_e32 v72, 0xbfb8aa3b, v105
	v_mul_f32_e32 v58, v78, v58
	v_mul_f32_e32 v59, v79, v59
	v_mul_f32_e32 v78, 0xbfb8aa3b, v103
	v_mul_f32_e32 v56, v82, v56
	v_mul_f32_e32 v57, v83, v57
	v_mul_f32_e32 v82, 0xbfb8aa3b, v97
	v_add_f32_e32 v84, 1.0, v84
	v_exp_f32_e32 v64, v64
	v_exp_f32_e32 v66, v66
	v_exp_f32_e32 v72, v72
	v_exp_f32_e32 v78, v78
	v_exp_f32_e32 v82, v82
	v_rcp_f32_e32 v85, v84
	v_mul_f32_e32 v84, 0xbfb8aa3b, v88
	v_mul_f32_e32 v88, 0xbfb8aa3b, v53
	v_fma_f32 v112, v92, v80, v90
	v_fma_f32 v113, v92, v81, v90
	v_mul_f32_e32 v80, 0xbfb8aa3b, v51
	v_fma_f32 v116, v92, v76, v90
	v_fma_f32 v117, v92, v77, v90
	v_mul_f32_e32 v76, 0xbfb8aa3b, v49
	v_exp_f32_e32 v88, v88
	v_exp_f32_e32 v80, v80
	v_exp_f32_e32 v76, v76
	v_add_f32_e32 v64, 1.0, v64
	v_add_f32_e32 v66, 1.0, v66
	v_add_f32_e32 v72, 1.0, v72
	v_add_f32_e32 v78, 1.0, v78
	v_add_f32_e32 v82, 1.0, v82
	v_rcp_f32_e32 v65, v64
	v_mul_f32_e32 v64, 0xbfb8aa3b, v114
	v_rcp_f32_e32 v67, v66
	v_mul_f32_e32 v66, 0xbfb8aa3b, v110
	v_rcp_f32_e32 v73, v72
	v_mul_f32_e32 v72, 0xbfb8aa3b, v104
	v_rcp_f32_e32 v79, v78
	v_mul_f32_e32 v78, 0xbfb8aa3b, v102
	v_rcp_f32_e32 v83, v82
	v_mul_f32_e32 v82, 0xbfb8aa3b, v96
	v_add_f32_e32 v88, 1.0, v88
	v_add_f32_e32 v80, 1.0, v80
	v_add_f32_e32 v76, 1.0, v76
	v_exp_f32_e32 v64, v64
	v_exp_f32_e32 v66, v66
	v_exp_f32_e32 v72, v72
	v_exp_f32_e32 v78, v78
	v_exp_f32_e32 v82, v82
	v_exp_f32_e32 v84, v84
	v_rcp_f32_e32 v89, v88
	v_mul_f32_e32 v88, 0xbfb8aa3b, v52
	v_rcp_f32_e32 v81, v80
	v_mul_f32_e32 v80, 0xbfb8aa3b, v50
	v_rcp_f32_e32 v77, v76
	v_mul_f32_e32 v76, 0xbfb8aa3b, v48
	v_exp_f32_e32 v88, v88
	v_exp_f32_e32 v80, v80
	v_exp_f32_e32 v76, v76
	v_add_f32_e32 v64, 1.0, v64
	v_add_f32_e32 v66, 1.0, v66
	v_add_f32_e32 v72, 1.0, v72
	v_add_f32_e32 v78, 1.0, v78
	v_add_f32_e32 v82, 1.0, v82
	v_add_f32_e32 v84, 1.0, v84
	v_rcp_f32_e32 v64, v64
	v_rcp_f32_e32 v66, v66
	v_rcp_f32_e32 v72, v72
	v_rcp_f32_e32 v78, v78
	v_rcp_f32_e32 v82, v82
	v_rcp_f32_e32 v84, v84
	v_add_f32_e32 v88, 1.0, v88
	v_add_f32_e32 v80, 1.0, v80
	v_add_f32_e32 v76, 1.0, v76
	v_rcp_f32_e32 v88, v88
	v_rcp_f32_e32 v80, v80
	v_rcp_f32_e32 v76, v76
	v_fma_f32 v74, v92, v64, v90
	v_fma_f32 v75, v92, v65, v90
	v_fma_f32 v86, v92, v66, v90
	v_fma_f32 v87, v92, v67, v90
	v_fma_f32 v98, v92, v72, v90
	v_fma_f32 v99, v92, v73, v90
	v_fma_f32 v100, v92, v78, v90
	v_fma_f32 v101, v92, v79, v90
	v_fma_f32 v106, v92, v82, v90
	v_fma_f32 v107, v92, v83, v90
	v_fma_f32 v108, v92, v84, v90
	v_fma_f32 v109, v92, v85, v90
	v_add_f32_e64 v64, -v74, 1.0
	v_add_f32_e64 v65, -v75, 1.0
	v_add_f32_e64 v66, -v86, 1.0
	v_add_f32_e64 v67, -v87, 1.0
	v_add_f32_e64 v72, -v98, 1.0
	v_add_f32_e64 v73, -v99, 1.0
	v_add_f32_e64 v78, -v100, 1.0
	v_add_f32_e64 v79, -v101, 1.0
	v_add_f32_e64 v82, -v106, 1.0
	v_add_f32_e64 v83, -v107, 1.0
	v_add_f32_e64 v84, -v108, 1.0
	v_add_f32_e64 v85, -v109, 1.0
	v_mul_f32_e32 v52, v88, v52
	v_mul_f32_e32 v53, v89, v53
	v_add_f32_e64 v94, -v112, 1.0
	v_add_f32_e64 v95, -v113, 1.0
	v_mul_f32_e32 v50, v80, v50
	v_mul_f32_e32 v51, v81, v51
	v_add_f32_e64 v90, -v116, 1.0
	v_add_f32_e64 v91, -v117, 1.0
	v_mul_f32_e32 v48, v76, v48
	v_mul_f32_e32 v49, v77, v49
	v_mov_b32_e32 v118, v117
.LBB0_435:
	v_mul_f32_e32 v122, v74, v75
	v_mul_f32_e32 v123, v75, v74
	s_nop 0
	v_mul_f32_e32 v120, v87, v122
	v_mul_f32_e32 v121, v86, v123
	v_mul_f32_e32 v114, v86, v120
	v_mul_f32_e32 v115, v87, v121
	s_nop 0
	v_mul_f32_e32 v110, v99, v114
	v_mul_f32_e32 v111, v98, v115
	v_mul_f32_e32 v104, v98, v110
	v_mul_f32_e32 v105, v99, v111
	s_nop 0
	v_mul_f32_e32 v102, v101, v104
	v_mul_f32_e32 v103, v100, v105
	v_mul_f32_e32 v100, v100, v102
	v_mul_f32_e32 v101, v101, v103
	s_nop 0
	v_mul_f32_e32 v98, v107, v100
	v_mul_f32_e32 v99, v106, v101
	v_mul_f32_e32 v96, v106, v98
	v_mul_f32_e32 v97, v107, v99
	s_nop 0
	v_mul_f32_e32 v92, v109, v96
	v_mul_f32_e32 v93, v108, v97
	v_mul_f32_e32 v88, v108, v92
	v_mul_f32_e32 v89, v109, v93
	s_nop 0
	v_mul_f32_e32 v86, v113, v88
	v_mul_f32_e32 v87, v112, v89
	v_mul_f32_e32 v80, v112, v86
	v_mul_f32_e32 v81, v113, v87
	s_nop 0
	v_mul_f32_e32 v76, v118, v80
	v_mul_f32_e32 v77, v118, v81
	v_lshlrev_b32_e32 v77, 16, v170
	v_or_b32_sdwa v106, v77, v166 dst_sel:DWORD dst_unused:UNUSED_PAD src0_sel:DWORD src1_sel:WORD_0
	s_waitcnt lgkmcnt(12)
	v_lshlrev_b32_e32 v77, 16, v171
	v_or_b32_sdwa v107, v77, v167 dst_sel:DWORD dst_unused:UNUSED_PAD src0_sel:DWORD src1_sel:WORD_0
	s_waitcnt lgkmcnt(10)
	v_lshlrev_b32_e32 v77, 16, v172
	v_or_b32_sdwa v108, v77, v168 dst_sel:DWORD dst_unused:UNUSED_PAD src0_sel:DWORD src1_sel:WORD_0
	s_waitcnt lgkmcnt(8)
	v_lshlrev_b32_e32 v77, 16, v173
	v_mul_f32_e32 v74, v116, v76
	v_or_b32_sdwa v109, v77, v169 dst_sel:DWORD dst_unused:UNUSED_PAD src0_sel:DWORD src1_sel:WORD_0
	s_waitcnt lgkmcnt(6)
	v_lshlrev_b32_e32 v77, 16, v162
	ds_write_b32 v137, v74
	ds_write_b128 v145, v[106:109] offset:55296
	v_or_b32_sdwa v106, v77, v71 dst_sel:DWORD dst_unused:UNUSED_PAD src0_sel:DWORD src1_sel:WORD_0
	s_waitcnt lgkmcnt(6)
	v_lshlrev_b32_e32 v71, 16, v163
	v_or_b32_sdwa v107, v71, v159 dst_sel:DWORD dst_unused:UNUSED_PAD src0_sel:DWORD src1_sel:WORD_0
	s_waitcnt lgkmcnt(4)
	v_lshlrev_b32_e32 v71, 16, v164
	v_or_b32_sdwa v108, v71, v160 dst_sel:DWORD dst_unused:UNUSED_PAD src0_sel:DWORD src1_sel:WORD_0
	s_waitcnt lgkmcnt(2)
	v_lshlrev_b32_e32 v71, 16, v165
	v_or_b32_sdwa v109, v71, v161 dst_sel:DWORD dst_unused:UNUSED_PAD src0_sel:DWORD src1_sel:WORD_0
	ds_write_b128 v145, v[106:109] offset:55312
	s_waitcnt lgkmcnt(0)
	s_barrier
	v_mov_b32_e32 v71, 1.0
	s_and_saveexec_b64 s[70:71], s[6:7]
	s_cbranch_execnz .LBB0_442
	s_or_b64 exec, exec, s[70:71]
	s_and_saveexec_b64 s[70:71], s[8:9]
	s_cbranch_execnz .LBB0_443

.LBB0_450:
	s_or_b64 exec, exec, s[68:69]
	s_waitcnt lgkmcnt(0)
	ds_read_b128 v[84:87], v147
	ds_read_b128 v[88:91], v147 offset:64
	ds_read_b128 v[92:95], v147 offset:128
	s_and_b32 s68, s3, 0x1fc0
	s_add_u32 s64, s64, 1
	s_waitcnt lgkmcnt(2)
	v_mul_f32_e32 v30, v30, v86
	v_mul_f32_e32 v31, v31, v87
	s_waitcnt lgkmcnt(1)
	v_mul_f32_e32 v26, v26, v90
	v_mul_f32_e32 v27, v27, v91
	v_mul_f32_e32 v24, v24, v88
	v_mul_f32_e32 v25, v25, v89
	ds_read_b128 v[88:91], v164
	v_mul_f32_e32 v28, v28, v84
	v_mul_f32_e32 v29, v29, v85
	ds_read_b128 v[84:87], v147 offset:192
	s_waitcnt lgkmcnt(2)
	v_mul_f32_e32 v22, v22, v94
	v_mul_f32_e32 v23, v23, v95
	v_mul_f32_e32 v20, v20, v92
	v_mul_f32_e32 v21, v21, v93
	ds_read_b128 v[92:95], v148 offset:55296
	s_addc_u32 s65, s65, 0
	s_waitcnt lgkmcnt(1)
	v_mul_f32_e32 v18, v18, v86
	v_mul_f32_e32 v19, v19, v87
	v_mul_f32_e32 v16, v16, v84
	v_mul_f32_e32 v17, v17, v85
	ds_read_b128 v[84:87], v164 offset:2560
	ds_read_b128 v[96:99], v148 offset:55360
	ds_read_b128 v[100:103], v164 offset:64
	s_waitcnt lgkmcnt(3)
	v_mfma_f32_16x16x32_bf16 v[28:31], v[88:91], v[92:95], v[28:31]
	ds_read_b128 v[88:91], v164 offset:5120
	ds_read_b128 v[104:107], v147 offset:256
	ds_read_b128 v[108:111], v147 offset:320
	ds_read_b128 v[112:115], v164 offset:7680
	ds_read_b128 v[116:119], v164 offset:2624
	s_add_i32 s3, s3, 64
	s_waitcnt lgkmcnt(3)
	v_mul_f32_e32 v14, v14, v106
	v_mul_f32_e32 v15, v15, v107
	v_mfma_f32_16x16x32_bf16 v[24:27], v[84:87], v[92:95], v[24:27]
	ds_read_b128 v[84:87], v164 offset:10240
	ds_read_b128 v[120:123], v164 offset:5184
	v_mul_f32_e32 v12, v12, v104
	v_mul_f32_e32 v13, v13, v105
	ds_read_b128 v[104:107], v164 offset:12800
	v_mfma_f32_16x16x32_bf16 v[20:23], v[88:91], v[92:95], v[20:23]
	ds_read_b128 v[88:91], v164 offset:7744
	s_waitcnt lgkmcnt(6)
	v_mul_f32_e32 v10, v10, v110
	v_mul_f32_e32 v11, v11, v111
	v_mul_f32_e32 v8, v8, v108
	v_mul_f32_e32 v9, v9, v109
	s_waitcnt lgkmcnt(5)
	v_mfma_f32_16x16x32_bf16 v[16:19], v[112:115], v[92:95], v[16:19]
	ds_read_b128 v[108:111], v164 offset:10304
	s_cmp_eq_u32 s64, 16
	s_waitcnt vmcnt(0)
	v_mov_b32_e32 v184, v167
	s_waitcnt lgkmcnt(4)
	v_mfma_f32_16x16x32_bf16 v[12:15], v[84:87], v[92:95], v[12:15]
	ds_read_b128 v[84:87], v164 offset:15360
	ds_read_b128 v[112:115], v147 offset:384
	ds_read_b128 v[124:127], v147 offset:448
	ds_read_b128 v[132:135], v164 offset:17920
	ds_read_b128 v[168:171], v164 offset:12864
	v_mov_b32_e32 v185, v166
	s_waitcnt lgkmcnt(3)
	v_mul_f32_e32 v2, v2, v114
	v_mul_f32_e32 v3, v3, v115
	v_mul_f32_e32 v0, v0, v112
	v_mul_f32_e32 v1, v1, v113
	v_mfma_f32_16x16x32_bf16 v[8:11], v[104:107], v[92:95], v[8:11]
	ds_read_b128 v[104:107], v164 offset:15424
	s_waitcnt lgkmcnt(3)
	v_mul_f32_e32 v6, v6, v126
	v_mul_f32_e32 v7, v7, v127
	v_mul_f32_e32 v4, v4, v124
	v_mul_f32_e32 v5, v5, v125
	v_mfma_f32_16x16x32_bf16 v[0:3], v[84:87], v[92:95], v[0:3]
	ds_read_b128 v[84:87], v164 offset:17984
	s_waitcnt lgkmcnt(0)
	s_barrier
	v_mfma_f32_16x16x32_bf16 v[16:19], v[88:91], v[96:99], v[16:19]
	ds_read2st64_b32 v[88:89], v141 offset1:1
	s_waitcnt lgkmcnt(0)
	v_add_f32_e32 v88, v88, v89
	v_mfma_f32_16x16x32_bf16 v[4:7], v[132:135], v[92:95], v[4:7]
	v_fmamk_f32 v88, v88, 0x3c000000, v165
	v_mul_f32_e32 v89, 0x4b800000, v88
	v_cmp_gt_f32_e32 vcc, s76, v88
	v_mfma_f32_16x16x32_bf16 v[4:7], v[84:87], v[96:99], v[4:7]
	s_nop 0
	v_cndmask_b32_e32 v88, v88, v89, vcc
	v_rsq_f32_e32 v90, v88
	ds_read2_b64 v[86:89], v152 offset1:4
	v_mfma_f32_16x16x32_bf16 v[28:31], v[100:103], v[96:99], v[28:31]
	v_mul_f32_e32 v84, 0x45800000, v90
	v_cndmask_b32_e32 v84, v90, v84, vcc
	s_waitcnt lgkmcnt(0)
	v_lshlrev_b32_e32 v100, 16, v86
	v_and_b32_e32 v101, 0xffff0000, v86
	v_mul_f32_e32 v85, 0xbfb8aa3b, v100
	v_exp_f32_e32 v85, v85
	v_mul_f32_e32 v86, 0xbfb8aa3b, v101
	v_exp_f32_e32 v86, v86
	v_or_b32_e32 v90, s68, v153
	v_ashrrev_i32_e32 v91, 31, v90
	v_add_f32_e32 v85, 1.0, v85
	v_mfma_f32_16x16x32_bf16 v[24:27], v[116:119], v[96:99], v[24:27]
	v_rcp_f32_e32 v102, v85
	v_add_f32_e32 v85, 1.0, v86
	v_rcp_f32_e32 v103, v85
	v_mfma_f32_16x16x32_bf16 v[20:23], v[120:123], v[96:99], v[20:23]
	v_lshlrev_b32_e32 v86, 16, v87
	v_mul_f32_e32 v76, v76, v84
	v_mul_f32_e32 v77, v77, v84
	v_and_b32_e32 v87, 0xffff0000, v87
	v_mfma_f32_16x16x32_bf16 v[12:15], v[108:111], v[96:99], v[12:15]
	v_mul_f32_e32 v85, 0xbfb8aa3b, v86
	v_exp_f32_e32 v85, v85
	v_mfma_f32_16x16x32_bf16 v[8:11], v[168:171], v[96:99], v[8:11]
	v_add_f32_e32 v85, 1.0, v85
	v_mfma_f32_16x16x32_bf16 v[0:3], v[104:107], v[96:99], v[0:3]
	v_lshlrev_b64 v[98:99], 11, v[90:91]
	ds_read_b128 v[90:93], v151
	ds_read_b128 v[94:97], v151 offset:64
	s_waitcnt lgkmcnt(1)
	v_mul_f32_e32 v76, v90, v76
	v_mul_f32_e32 v77, v91, v77
	v_mul_f32_e32 v90, v102, v100
	v_mul_f32_e32 v91, v103, v101
	v_mul_f32_e32 v100, 0xbfb8aa3b, v87
	v_exp_f32_e32 v100, v100
	v_mul_f32_e32 v76, v76, v90
	v_mul_f32_e32 v77, v77, v91
	v_rcp_f32_e32 v90, v85
	v_cvt_pk_bf16_f32 v76, v76, v77
	v_add_f32_e32 v85, 1.0, v100
	v_rcp_f32_e32 v91, v85
	v_mul_f32_e32 v78, v78, v84
	v_mul_f32_e32 v79, v79, v84
	v_mul_f32_e32 v86, v90, v86
	v_mul_f32_e32 v87, v91, v87
	v_mul_f32_e32 v78, v92, v78
	v_mul_f32_e32 v79, v93, v79
	v_lshl_add_u64 v[90:91], v[82:83], 0, v[98:99]
	v_mul_f32_e32 v78, v78, v86
	v_mul_f32_e32 v79, v79, v87
	s_nop 0
	v_cvt_pk_bf16_f32 v77, v78, v79
	v_lshlrev_b32_e32 v78, 16, v88
	v_and_b32_e32 v79, 0xffff0000, v88
	v_mul_f32_e32 v85, 0xbfb8aa3b, v78
	v_exp_f32_e32 v85, v85
	v_mul_f32_e32 v86, 0xbfb8aa3b, v79
	v_exp_f32_e32 v87, v86
	global_store_dwordx2 v[90:91], v[76:77], off
	v_add_f32_e32 v85, 1.0, v85
	v_rcp_f32_e32 v86, v85
	v_add_f32_e32 v85, 1.0, v87
	v_rcp_f32_e32 v87, v85
	v_mul_f32_e32 v72, v72, v84
	v_mul_f32_e32 v73, v73, v84
	v_mul_f32_e32 v76, v86, v78
	v_mul_f32_e32 v77, v87, v79
	s_waitcnt lgkmcnt(0)
	v_mul_f32_e32 v72, v94, v72
	v_mul_f32_e32 v73, v95, v73
	s_nop 0
	v_mul_f32_e32 v72, v72, v76
	v_mul_f32_e32 v73, v73, v77
	v_lshlrev_b32_e32 v76, 16, v89
	v_and_b32_e32 v77, 0xffff0000, v89
	v_mul_f32_e32 v78, 0xbfb8aa3b, v76
	v_exp_f32_e32 v79, v78
	v_mul_f32_e32 v78, 0xbfb8aa3b, v77
	v_exp_f32_e32 v85, v78
	v_cvt_pk_bf16_f32 v78, v72, v73
	v_add_f32_e32 v72, 1.0, v79
	v_rcp_f32_e32 v86, v72
	v_add_f32_e32 v72, 1.0, v85
	v_rcp_f32_e32 v87, v72
	v_mul_f32_e32 v72, v74, v84
	v_mul_f32_e32 v73, v75, v84
	v_mul_f32_e32 v76, v86, v76
	v_mul_f32_e32 v77, v87, v77
	v_mul_f32_e32 v88, v96, v72
	v_mul_f32_e32 v89, v97, v73
	ds_read2_b64 v[72:75], v152 offset0:8 offset1:12
	v_mul_f32_e32 v76, v88, v76
	v_mul_f32_e32 v77, v89, v77
	ds_read_b128 v[86:89], v151 offset:192
	v_cvt_pk_bf16_f32 v79, v76, v77
	global_store_dwordx2 v[90:91], v[78:79], off offset:32
	s_waitcnt lgkmcnt(1)
	v_lshlrev_b32_e32 v92, 16, v72
	v_and_b32_e32 v93, 0xffff0000, v72
	v_mul_f32_e32 v72, 0xbfb8aa3b, v92
	v_exp_f32_e32 v72, v72
	v_mul_f32_e32 v76, 0xbfb8aa3b, v93
	v_exp_f32_e32 v85, v76
	ds_read_b128 v[76:79], v151 offset:128
	v_add_f32_e32 v72, 1.0, v72
	v_rcp_f32_e32 v94, v72
	v_add_f32_e32 v72, 1.0, v85
	v_rcp_f32_e32 v95, v72
	v_mul_f32_e32 v68, v68, v84
	v_mul_f32_e32 v69, v69, v84
	v_lshlrev_b32_e32 v72, 16, v73
	v_and_b32_e32 v73, 0xffff0000, v73
	s_waitcnt lgkmcnt(0)
	v_mul_f32_e32 v68, v76, v68
	v_mul_f32_e32 v69, v77, v69
	v_mul_f32_e32 v76, v94, v92
	v_mul_f32_e32 v77, v95, v93
	v_mul_f32_e32 v85, 0xbfb8aa3b, v72
	v_mul_f32_e32 v92, 0xbfb8aa3b, v73
	v_exp_f32_e32 v85, v85
	v_exp_f32_e32 v92, v92
	v_mul_f32_e32 v68, v68, v76
	v_mul_f32_e32 v69, v69, v77
	v_add_f32_e32 v76, 1.0, v85
	v_add_f32_e32 v77, 1.0, v92
	v_rcp_f32_e32 v76, v76
	v_rcp_f32_e32 v77, v77
	v_mul_f32_e32 v70, v70, v84
	v_mul_f32_e32 v71, v71, v84
	v_cvt_pk_bf16_f32 v68, v68, v69
	v_mul_f32_e32 v70, v78, v70
	v_mul_f32_e32 v71, v79, v71
	v_mul_f32_e32 v72, v76, v72
	v_mul_f32_e32 v73, v77, v73
	v_mul_f32_e32 v64, v64, v84
	v_mul_f32_e32 v65, v65, v84
	v_mul_f32_e32 v70, v70, v72
	v_mul_f32_e32 v71, v71, v73
	v_lshlrev_b32_e32 v72, 16, v74
	v_and_b32_e32 v73, 0xffff0000, v74
	v_mul_f32_e32 v69, 0xbfb8aa3b, v72
	v_exp_f32_e32 v74, v69
	v_mul_f32_e32 v69, 0xbfb8aa3b, v73
	v_exp_f32_e32 v76, v69
	v_cvt_pk_bf16_f32 v69, v70, v71
	v_add_f32_e32 v70, 1.0, v74
	v_rcp_f32_e32 v70, v70
	v_add_f32_e32 v71, 1.0, v76
	v_rcp_f32_e32 v71, v71
	global_store_dwordx2 v[90:91], v[68:69], off offset:64
	v_mul_f32_e32 v64, v64, v86
	v_mul_f32_e32 v65, v65, v87
	v_mul_f32_e32 v66, v66, v84
	v_mul_f32_e32 v67, v67, v84
	v_mul_f32_e32 v68, v70, v72
	v_mul_f32_e32 v69, v71, v73
	v_lshlrev_b32_e32 v70, 16, v75
	v_and_b32_e32 v71, 0xffff0000, v75
	v_mul_f32_e32 v72, 0xbfb8aa3b, v70
	v_mul_f32_e32 v73, 0xbfb8aa3b, v71
	v_exp_f32_e32 v72, v72
	v_exp_f32_e32 v73, v73
	v_mul_f32_e32 v64, v64, v68
	v_mul_f32_e32 v65, v65, v69
	v_mul_f32_e32 v66, v66, v88
	v_mul_f32_e32 v67, v67, v89
	v_add_f32_e32 v68, 1.0, v72
	v_add_f32_e32 v69, 1.0, v73
	v_rcp_f32_e32 v68, v68
	v_rcp_f32_e32 v69, v69
	v_cvt_pk_bf16_f32 v64, v64, v65
	v_mul_f32_e32 v68, v68, v70
	v_mul_f32_e32 v69, v69, v71
	s_nop 0
	v_mul_f32_e32 v66, v66, v68
	v_mul_f32_e32 v67, v67, v69
	s_nop 0
	v_cvt_pk_bf16_f32 v65, v66, v67
	global_store_dwordx2 v[90:91], v[64:65], off offset:96
	s_waitcnt lgkmcnt(0)
	s_barrier
	ds_write_b128 v137, v[32:35]
	ds_write_b128 v137, v[36:39] offset:18432
	ds_write_b128 v137, v[40:43] offset:36864
	ds_write_b128 v139, v[44:47]
	ds_write_b128 v138, v[48:51]
	ds_write_b128 v138, v[52:55] offset:18432
	ds_write_b128 v138, v[56:59] offset:36864
	ds_write_b128 v140, v[60:63]
	s_waitcnt lgkmcnt(0)
	s_barrier
	s_cbranch_scc1 .LBB0_463
.LBB0_451:
	s_cmp_lg_u32 s64, 15
	s_cselect_b64 s[68:69], -1, 0
	s_cmp_lg_u64 s[68:69], 0
	s_addc_u32 s82, s56, s64
	v_cndmask_b32_e64 v32, 0, 1, s[68:69]
	s_add_u32 s68, s56, s64
	v_mov_b32_e32 v33, s81
	s_addc_u32 s69, s57, s65
	v_lshl_add_u64 v[32:33], s[68:69], 0, v[32:33]
	v_lshlrev_b64 v[32:33], 16, v[32:33]
	v_lshl_add_u64 v[32:33], s[54:55], 0, v[32:33]
	v_lshl_add_u64 v[60:61], v[32:33], 0, v[80:81]
	v_add_co_u32_e32 v36, vcc, s67, v60
	s_and_b32 s82, s82, 0x180
	s_nop 0
	v_addc_co_u32_e32 v37, vcc, 0, v61, vcc
	v_add_co_u32_e32 v40, vcc, s70, v60
	v_or_b32_e32 v64, s82, v136
	s_nop 0
	v_addc_co_u32_e32 v41, vcc, 0, v61, vcc
	v_add_co_u32_e32 v44, vcc, s71, v60
	v_readfirstlane_b32 s68, v32
	s_nop 0
	v_addc_co_u32_e32 v45, vcc, 0, v61, vcc
	v_add_co_u32_e32 v48, vcc, s77, v60
	v_readfirstlane_b32 s69, v33
	s_nop 0
	v_addc_co_u32_e32 v49, vcc, 0, v61, vcc
	v_add_co_u32_e32 v52, vcc, s78, v60
	v_lshlrev_b32_e32 v64, 2, v64
	s_nop 0
	v_addc_co_u32_e32 v53, vcc, 0, v61, vcc
	v_add_co_u32_e32 v56, vcc, s79, v60
	global_load_dwordx4 v[32:35], v80, s[68:69]
	s_nop 0
	v_addc_co_u32_e32 v57, vcc, 0, v61, vcc
	v_add_co_u32_e32 v60, vcc, s80, v60
	global_load_dwordx4 v[36:39], v[36:37], off
	s_nop 0
	global_load_dwordx4 v[40:43], v[40:41], off
	v_addc_co_u32_e32 v61, vcc, 0, v61, vcc
	global_load_dwordx4 v[44:47], v[44:45], off
	s_nop 0
	global_load_dwordx4 v[48:51], v[48:49], off
	s_nop 0
	global_load_dwordx4 v[52:55], v[52:53], off
	s_nop 0
	global_load_dwordx4 v[56:59], v[56:57], off
	s_and_b64 vcc, exec, s[60:61]
	global_load_dwordx4 v[60:63], v[60:61], off
	s_nop 0
	global_load_dword v166, v64, s[62:63]
	global_load_dword v167, v64, s[62:63] offset:2048
	ds_read_u16 v64, v154
	ds_read_u16 v65, v154 offset:288
	ds_read_u16 v66, v154 offset:576
	ds_read_u16 v67, v154 offset:864
	ds_read_u16 v68, v154 offset:1152
	ds_read_u16 v69, v154 offset:1440
	ds_read_u16 v70, v154 offset:1728
	ds_read_u16 v71, v154 offset:2016
	ds_read_u16 v84, v154 offset:2304
	ds_read_u16 v85, v154 offset:2592
	ds_read_u16 v86, v154 offset:2880
	ds_read_u16 v87, v154 offset:3168
	ds_read_u16 v88, v154 offset:3456
	ds_read_u16 v89, v154 offset:3744
	ds_read_u16 v90, v154 offset:4032
	ds_read_u16 v91, v154 offset:4320
	ds_read_u16 v72, v154 offset:18432
	ds_read_u16 v73, v154 offset:18720
	ds_read_u16 v74, v154 offset:19008
	ds_read_u16 v75, v154 offset:19296
	ds_read_u16 v76, v154 offset:19584
	ds_read_u16 v77, v154 offset:19872
	ds_read_u16 v78, v154 offset:20160
	ds_read_u16 v79, v154 offset:20448
	ds_read_u16 v92, v154 offset:20736
	ds_read_u16 v93, v154 offset:21024
	ds_read_u16 v94, v154 offset:21312
	ds_read_u16 v95, v154 offset:21600
	ds_read_u16 v96, v154 offset:21888
	ds_read_u16 v97, v154 offset:22176
	ds_read_u16 v98, v154 offset:22464
	ds_read_u16 v99, v154 offset:22752
	ds_read_u16 v176, v154 offset:36864
	ds_read_u16 v180, v154 offset:37152
	ds_read_u16 v177, v154 offset:37440
	ds_read_u16 v181, v154 offset:37728
	ds_read_u16 v178, v154 offset:38016
	ds_read_u16 v182, v154 offset:38304
	ds_read_u16 v179, v154 offset:38592
	ds_read_u16 v183, v154 offset:38880
	ds_read_u16 v168, v154 offset:39168
	ds_read_u16 v172, v154 offset:39456
	ds_read_u16 v169, v154 offset:39744
	ds_read_u16 v173, v154 offset:40032
	ds_read_u16 v170, v154 offset:40320
	ds_read_u16 v174, v154 offset:40608
	ds_read_u16 v171, v154 offset:40896
	ds_read_u16 v175, v154 offset:41184
	s_waitcnt lgkmcnt(0)
	s_barrier
	s_waitcnt lgkmcnt(14)
	v_lshlrev_b32_e32 v123, 16, v74
	v_lshlrev_b32_e32 v122, 16, v72
	v_lshlrev_b32_e32 v121, 16, v75
	v_lshlrev_b32_e32 v120, 16, v73
	v_lshlrev_b32_e32 v115, 16, v78
	v_lshlrev_b32_e32 v114, 16, v76
	v_lshlrev_b32_e32 v113, 16, v79
	v_lshlrev_b32_e32 v112, 16, v77
	v_lshlrev_b32_e32 v109, 16, v94
	v_lshlrev_b32_e32 v108, 16, v92
	v_lshlrev_b32_e32 v107, 16, v95
	v_lshlrev_b32_e32 v106, 16, v93
	v_lshlrev_b32_e32 v105, 16, v98
	v_lshlrev_b32_e32 v104, 16, v96
	v_lshlrev_b32_e32 v103, 16, v99
	v_lshlrev_b32_e32 v102, 16, v97
	v_lshlrev_b32_e32 v79, 16, v64
	v_lshlrev_b32_e32 v78, 16, v65
	v_lshlrev_b32_e32 v77, 16, v66
	v_lshlrev_b32_e32 v76, 16, v67
	v_lshlrev_b32_e32 v75, 16, v68
	v_lshlrev_b32_e32 v74, 16, v69
	v_lshlrev_b32_e32 v73, 16, v70
	v_lshlrev_b32_e32 v72, 16, v71
	v_lshlrev_b32_e32 v71, 16, v84
	v_lshlrev_b32_e32 v70, 16, v85
	v_lshlrev_b32_e32 v69, 16, v86
	v_lshlrev_b32_e32 v68, 16, v87
	v_lshlrev_b32_e32 v67, 16, v88
	v_lshlrev_b32_e32 v66, 16, v89
	v_lshlrev_b32_e32 v65, 16, v90
	v_lshlrev_b32_e32 v64, 16, v91
	s_mov_b64 s[68:69], -1
	s_cbranch_vccz .LBB0_453
	v_mul_f32_e32 v84, s66, v122
	v_mul_f32_e32 v85, s66, v123
	v_mul_f32_e32 v86, s66, v120
	v_mul_f32_e32 v87, s66, v121
	v_mul_f32_e32 v88, s66, v114
	v_mul_f32_e32 v89, s66, v115
	v_mul_f32_e32 v90, s66, v112
	v_mul_f32_e32 v91, s66, v113
	v_mul_f32_e32 v92, s66, v108
	v_mul_f32_e32 v93, s66, v109
	v_mul_f32_e32 v94, s66, v106
	v_mul_f32_e32 v95, s66, v107
	v_mul_f32_e32 v98, s66, v104
	v_mul_f32_e32 v99, s66, v105
	v_mul_f32_e32 v96, s66, v102
	v_mul_f32_e32 v97, s66, v103
	s_mov_b64 s[68:69], 0
.LBB0_453:
	s_andn2_b64 vcc, exec, s[68:69]
	v_mov_b32_e32 v135, v142
	v_mov_b32_e32 v133, v142
	v_mov_b32_e32 v134, v142
	v_mov_b32_e32 v132, v142
	v_mov_b32_e32 v127, v142
	v_mov_b32_e32 v125, v142
	v_mov_b32_e32 v126, v142
	v_mov_b32_e32 v124, v142
	v_mov_b32_e32 v119, v142
	v_mov_b32_e32 v117, v142
	v_mov_b32_e32 v118, v142
	v_mov_b32_e32 v116, v142
	v_mov_b32_e32 v111, v142
	v_mov_b32_e32 v101, v142
	v_mov_b32_e32 v110, v142
	v_mov_b32_e32 v100, v142
	s_cbranch_vccnz .LBB0_455
	v_max_f32_e32 v84, v184, v184
	v_max_f32_e32 v85, v185, v185
	v_max_f32_e32 v84, v85, v84
	v_sub_f32_e32 v85, v185, v84
	v_sub_f32_e32 v84, v184, v84
	v_mul_f32_e32 v85, 0x3fb8aa3b, v85
	v_mul_f32_e32 v84, 0x3fb8aa3b, v84
	v_exp_f32_e32 v85, v85
	v_exp_f32_e32 v84, v84
	v_mul_f32_e32 v91, 0xbfb8aa3b, v112
	v_exp_f32_e32 v91, v91
	v_mul_f32_e32 v92, 0xbfb8aa3b, v75
	v_add_f32_e32 v84, v85, v84
	v_div_scale_f32 v86, s[68:69], v84, v84, v85
	v_rcp_f32_e32 v87, v86
	v_exp_f32_e32 v93, v92
	v_mul_f32_e32 v92, 0xbfb8aa3b, v74
	v_exp_f32_e32 v94, v92
	v_fma_f32 v88, -v86, v87, 1.0
	v_fmac_f32_e32 v87, v88, v87
	v_div_scale_f32 v88, vcc, v85, v84, v85
	v_mul_f32_e32 v89, v88, v87
	v_fma_f32 v90, -v86, v89, v88
	v_fmac_f32_e32 v89, v90, v87
	v_fma_f32 v86, -v86, v89, v88
	v_div_fmas_f32 v86, v86, v87, v89
	v_mul_f32_e32 v87, 0xbfb8aa3b, v122
	v_exp_f32_e32 v87, v87
	v_mul_f32_e32 v88, 0xbfb8aa3b, v120
	v_exp_f32_e32 v88, v88
	v_div_fixup_f32 v96, v86, v84, v85
	v_mul_f32_e32 v86, 0xbfb8aa3b, v79
	v_add_f32_e32 v84, 1.0, v87
	v_exp_f32_e32 v87, v86
	v_mul_f32_e32 v86, 0xbfb8aa3b, v78
	v_add_f32_e32 v85, 1.0, v88
	v_exp_f32_e32 v88, v86
	v_rcp_f32_e32 v86, v85
	v_add_f32_e32 v85, 1.0, v87
	v_rcp_f32_e32 v89, v85
	v_add_f32_e32 v85, 1.0, v88
	v_mul_f32_e32 v87, 0xbfb8aa3b, v123
	v_mul_f32_e32 v88, 0xbfb8aa3b, v121
	v_exp_f32_e32 v87, v87
	v_exp_f32_e32 v90, v88
	v_rcp_f32_e32 v88, v85
	v_sub_f32_e32 v98, 1.0, v96
	v_add_f32_e32 v85, 1.0, v87
	v_add_f32_e32 v87, 1.0, v90
	v_rcp_f32_e32 v87, v87
	v_mul_f32_e32 v78, v88, v78
	v_mul_f32_e32 v79, v89, v79
	v_rcp_f32_e32 v84, v84
	v_rcp_f32_e32 v85, v85
	v_fma_f32 v110, v98, v86, v96
	v_fma_f32 v111, v98, v87, v96
	v_mul_f32_e32 v86, 0xbfb8aa3b, v77
	v_exp_f32_e32 v88, v86
	v_mul_f32_e32 v86, 0xbfb8aa3b, v76
	v_exp_f32_e32 v90, v86
	v_add_f32_e32 v91, 1.0, v91
	v_add_f32_e32 v88, 1.0, v88
	v_rcp_f32_e32 v89, v88
	v_add_f32_e32 v88, 1.0, v90
	v_mul_f32_e32 v90, 0xbfb8aa3b, v114
	v_rcp_f32_e32 v92, v91
	v_add_f32_e32 v91, 1.0, v93
	v_mul_f32_e32 v93, 0xbfb8aa3b, v115
	v_exp_f32_e32 v90, v90
	v_rcp_f32_e32 v95, v91
	v_add_f32_e32 v91, 1.0, v94
	v_exp_f32_e32 v93, v93
	v_mul_f32_e32 v94, 0xbfb8aa3b, v113
	v_fma_f32 v100, v98, v84, v96
	v_fma_f32 v101, v98, v85, v96
	v_exp_f32_e32 v97, v94
	v_add_f32_e32 v90, 1.0, v90
	v_rcp_f32_e32 v94, v91
	v_add_f32_e32 v91, 1.0, v93
	v_rcp_f32_e32 v90, v90
	v_rcp_f32_e32 v91, v91
	v_add_f32_e32 v93, 1.0, v97
	v_rcp_f32_e32 v93, v93
	v_mul_f32_e32 v74, v94, v74
	v_mul_f32_e32 v75, v95, v75
	v_fma_f32 v116, v98, v90, v96
	v_fma_f32 v117, v98, v91, v96
	v_mul_f32_e32 v90, 0xbfb8aa3b, v73
	v_mul_f32_e32 v95, 0xbfb8aa3b, v106
	v_fma_f32 v118, v98, v92, v96
	v_fma_f32 v119, v98, v93, v96
	v_exp_f32_e32 v92, v90
	v_mul_f32_e32 v90, 0xbfb8aa3b, v72
	v_exp_f32_e32 v95, v95
	v_mul_f32_e32 v97, 0xbfb8aa3b, v71
	v_exp_f32_e32 v94, v90
	v_exp_f32_e32 v97, v97
	v_mul_f32_e32 v99, 0xbfb8aa3b, v70
	v_exp_f32_e32 v99, v99
	v_add_f32_e32 v92, 1.0, v92
	v_add_f32_e32 v95, 1.0, v95
	v_rcp_f32_e32 v93, v92
	v_add_f32_e32 v92, 1.0, v94
	v_mul_f32_e32 v94, 0xbfb8aa3b, v108
	v_rcp_f32_e32 v106, v95
	v_add_f32_e32 v95, 1.0, v97
	v_mul_f32_e32 v97, 0xbfb8aa3b, v109
	v_exp_f32_e32 v94, v94
	v_rcp_f32_e32 v113, v95
	v_add_f32_e32 v95, 1.0, v99
	v_exp_f32_e32 v97, v97
	v_mul_f32_e32 v99, 0xbfb8aa3b, v107
	v_exp_f32_e32 v99, v99
	v_add_f32_e32 v94, 1.0, v94
	v_rcp_f32_e32 v112, v95
	v_add_f32_e32 v95, 1.0, v97
	v_rcp_f32_e32 v94, v94
	v_rcp_f32_e32 v95, v95
	v_add_f32_e32 v97, 1.0, v99
	v_rcp_f32_e32 v107, v97
	v_rcp_f32_e32 v88, v88
	v_fma_f32 v124, v98, v94, v96
	v_fma_f32 v125, v98, v95, v96
	v_mul_f32_e32 v94, 0xbfb8aa3b, v69
	v_fma_f32 v126, v98, v106, v96
	v_fma_f32 v127, v98, v107, v96
	v_exp_f32_e32 v97, v94
	v_mul_f32_e32 v94, 0xbfb8aa3b, v68
	v_exp_f32_e32 v99, v94
	v_rcp_f32_e32 v92, v92
	v_add_f32_e32 v97, 1.0, v97
	v_rcp_f32_e32 v107, v97
	v_add_f32_e32 v97, 1.0, v99
	v_rcp_f32_e32 v106, v97
	v_mul_f32_e32 v97, 0xbfb8aa3b, v104
	v_exp_f32_e32 v97, v97
	v_mul_f32_e32 v99, 0xbfb8aa3b, v102
	v_exp_f32_e32 v99, v99
	v_mul_f32_e32 v104, 0xbfb8aa3b, v66
	v_add_f32_e32 v97, 1.0, v97
	v_rcp_f32_e32 v102, v97
	v_add_f32_e32 v97, 1.0, v99
	v_mul_f32_e32 v99, 0xbfb8aa3b, v67
	v_exp_f32_e32 v99, v99
	v_mul_f32_e32 v68, v106, v68
	v_mul_f32_e32 v69, v107, v69
	v_exp_f32_e32 v106, v104
	v_rcp_f32_e32 v104, v97
	v_add_f32_e32 v97, 1.0, v99
	v_rcp_f32_e32 v107, v97
	v_add_f32_e32 v97, 1.0, v106
	v_rcp_f32_e32 v106, v97
	v_mul_f32_e32 v97, 0xbfb8aa3b, v105
	v_exp_f32_e32 v97, v97
	v_mul_f32_e32 v99, 0xbfb8aa3b, v103
	v_exp_f32_e32 v99, v99
	v_add_f32_e64 v84, -v100, 1.0
	v_add_f32_e64 v85, -v101, 1.0
	v_add_f32_e32 v97, 1.0, v97
	v_rcp_f32_e32 v103, v97
	v_add_f32_e32 v97, 1.0, v99
	v_rcp_f32_e32 v105, v97
	v_mul_f32_e32 v97, 0xbfb8aa3b, v65
	v_mul_f32_e32 v99, 0xbfb8aa3b, v64
	v_exp_f32_e32 v97, v97
	v_exp_f32_e32 v99, v99
	v_add_f32_e64 v86, -v110, 1.0
	v_add_f32_e64 v87, -v111, 1.0
	v_mul_f32_e32 v76, v88, v76
	v_mul_f32_e32 v77, v89, v77
	v_add_f32_e64 v88, -v116, 1.0
	v_add_f32_e64 v89, -v117, 1.0
	v_fma_f32 v132, v98, v102, v96
	v_fma_f32 v133, v98, v103, v96
	v_add_f32_e32 v97, 1.0, v97
	v_rcp_f32_e32 v103, v97
	v_add_f32_e32 v97, 1.0, v99
	v_rcp_f32_e32 v102, v97
	v_fma_f32 v134, v98, v104, v96
	v_fma_f32 v135, v98, v105, v96
	v_add_f32_e64 v90, -v118, 1.0
	v_add_f32_e64 v91, -v119, 1.0
	v_mul_f32_e32 v72, v92, v72
	v_mul_f32_e32 v73, v93, v73
	v_mul_f32_e32 v70, v112, v70
	v_mul_f32_e32 v71, v113, v71
	v_add_f32_e64 v92, -v124, 1.0
	v_add_f32_e64 v93, -v125, 1.0
	v_add_f32_e64 v94, -v126, 1.0
	v_add_f32_e64 v95, -v127, 1.0
	v_mul_f32_e32 v66, v106, v66
	v_mul_f32_e32 v67, v107, v67
	v_add_f32_e64 v98, -v132, 1.0
	v_add_f32_e64 v99, -v133, 1.0
	v_add_f32_e64 v96, -v134, 1.0
	v_add_f32_e64 v97, -v135, 1.0
	v_mul_f32_e32 v64, v102, v64
	v_mul_f32_e32 v65, v103, v65

.LBB0_459:
	s_or_b64 exec, exec, s[68:69]
	ds_read2st64_b32 v[118:119], v144 offset1:4
	ds_read_b32 v123, v144 offset:1536
	s_waitcnt lgkmcnt(1)
	v_mul_f32_e32 v117, v116, v119
	v_mov_b32_e32 v122, v118
	v_mov_b32_e32 v103, v119
	v_cndmask_b32_e64 v118, v116, v117, s[12:13]
	s_waitcnt lgkmcnt(0)
	v_mul_f32_e32 v116, v122, v102
	v_mul_f32_e32 v117, v123, v103
	v_mul_f32_e32 v102, v118, v123
	v_rcp_f32_e32 v123, v116
	v_cndmask_b32_e64 v122, v118, v102, s[14:15]
	v_mul_f32_e32 v100, v100, v122
	v_mul_f32_e32 v79, v79, v100
	v_rcp_f32_e32 v118, v100
	v_mul_f32_e32 v100, v123, v79
	v_cvt_pk_bf16_f32 v79, v79, s0
	v_cvt_pk_bf16_f32 v100, v100, s0
	ds_write_b16 v149, v79 offset:36864
	v_mul_f32_e32 v79, v121, v122
	ds_write_b16 v149, v100
	v_mul_f32_e32 v100, v78, v79
	v_rcp_f32_e32 v78, v79
	v_mul_f32_e32 v79, v123, v100
	v_mul_f32_e32 v102, v116, v117
	v_mul_f32_e32 v103, v117, v116
	v_cvt_pk_bf16_f32 v117, v79, s0
	v_mul_f32_e32 v79, v120, v122
	v_mul_f32_e32 v77, v77, v79
	v_rcp_f32_e32 v119, v79
	v_mul_f32_e32 v79, v123, v77
	v_cvt_pk_bf16_f32 v121, v77, s0
	v_mul_f32_e32 v77, v115, v122
	v_cvt_pk_bf16_f32 v120, v79, s0
	v_mul_f32_e32 v76, v76, v77
	v_rcp_f32_e32 v79, v77
	v_mul_f32_e32 v77, v123, v76
	v_cvt_pk_bf16_f32 v115, v77, s0
	v_cvt_pk_bf16_f32 v124, v76, s0
	v_mul_f32_e32 v76, v84, v118
	v_mul_f32_e32 v77, v85, v119
	v_mul_f32_e32 v78, v86, v78
	v_mul_f32_e32 v79, v87, v79
	v_mul_f32_e32 v84, v116, v76
	v_cvt_pk_bf16_f32 v84, v84, s0
	ds_write_b16 v149, v84 offset:18432
	ds_write_b16 v150, v117 offset:288
	v_mul_f32_e32 v84, v116, v78
	v_cvt_pk_bf16_f32 v84, v84, s0
	v_cvt_pk_bf16_f32 v100, v100, s0
	ds_write_b16 v150, v84 offset:18720
	ds_write_b16 v150, v100 offset:37152
	ds_write_b16 v150, v120 offset:576
	v_mul_f32_e32 v84, v116, v77
	v_cvt_pk_bf16_f32 v84, v84, s0
	v_mul_f32_e32 v76, v102, v76
	v_mul_f32_e32 v77, v102, v77
	ds_write_b16 v150, v84 offset:19008
	ds_write_b16 v150, v121 offset:37440
	v_cvt_pk_bf16_f32 v84, v76, v77
	v_mul_f32_e32 v76, v116, v79
	v_cvt_pk_bf16_f32 v76, v76, s0
	ds_write_b16 v150, v115 offset:864
	ds_write_b16 v150, v76 offset:19296
	ds_write_b16 v150, v124 offset:37728
	v_mul_f32_e32 v76, v102, v78
	v_mul_f32_e32 v77, v102, v79
	v_mul_f32_e32 v78, v114, v122
	v_mul_f32_e32 v75, v75, v78
	v_mul_f32_e32 v79, v123, v75
	v_cvt_pk_bf16_f32 v75, v75, s0
	v_cvt_pk_bf16_f32 v79, v79, s0
	ds_write_b16 v150, v75 offset:38016
	v_mul_f32_e32 v75, v113, v122
	v_cvt_pk_bf16_f32 v76, v76, v77
	ds_write_b16 v150, v79 offset:1152
	v_mul_f32_e32 v79, v74, v75
	v_and_b32_e32 v77, 0xffff0000, v76
	v_lshlrev_b32_e32 v76, 16, v76
	v_rcp_f32_e32 v74, v75
	v_mul_f32_e32 v75, v123, v79
	v_or_b32_sdwa v77, v77, v84 dst_sel:DWORD dst_unused:UNUSED_PAD src0_sel:DWORD src1_sel:WORD_1
	v_or_b32_sdwa v76, v76, v84 dst_sel:DWORD dst_unused:UNUSED_PAD src0_sel:DWORD src1_sel:WORD_0
	v_cvt_pk_bf16_f32 v84, v75, s0
	v_mul_f32_e32 v75, v112, v122
	v_rcp_f32_e32 v78, v78
	v_cvt_pk_bf16_f32 v85, v79, s0
	v_mul_f32_e32 v73, v73, v75
	v_rcp_f32_e32 v79, v75
	v_mul_f32_e32 v75, v123, v73
	v_cvt_pk_bf16_f32 v87, v73, s0
	v_mul_f32_e32 v73, v111, v122
	v_cvt_pk_bf16_f32 v86, v75, s0
	v_mul_f32_e32 v72, v72, v73
	v_rcp_f32_e32 v75, v73
	v_mul_f32_e32 v73, v123, v72
	v_cvt_pk_bf16_f32 v100, v73, s0
	v_cvt_pk_bf16_f32 v111, v72, s0
	v_mul_f32_e32 v72, v88, v78
	v_mul_f32_e32 v73, v89, v79
	v_mul_f32_e32 v74, v90, v74
	v_mul_f32_e32 v75, v91, v75
	v_mul_f32_e32 v78, v116, v72
	v_cvt_pk_bf16_f32 v78, v78, s0
	ds_write_b16 v150, v78 offset:19584
	ds_write_b16 v150, v84 offset:1440
	v_mul_f32_e32 v78, v116, v74
	v_cvt_pk_bf16_f32 v78, v78, s0
	ds_write_b16 v150, v78 offset:19872
	ds_write_b16 v150, v85 offset:38304
	ds_write_b16 v150, v86 offset:1728
	v_mul_f32_e32 v78, v116, v73
	v_cvt_pk_bf16_f32 v78, v78, s0
	v_mul_f32_e32 v72, v102, v72
	v_mul_f32_e32 v73, v102, v73
	ds_write_b16 v150, v78 offset:20160
	ds_write_b16 v150, v87 offset:38592
	v_cvt_pk_bf16_f32 v78, v72, v73
	v_mul_f32_e32 v72, v116, v75
	v_cvt_pk_bf16_f32 v72, v72, s0
	ds_write_b16 v150, v100 offset:2016
	ds_write_b16 v150, v72 offset:20448
	ds_write_b16 v150, v111 offset:38880
	v_mul_f32_e32 v72, v102, v74
	v_mul_f32_e32 v73, v102, v75
	v_cvt_pk_bf16_f32 v72, v72, v73
	v_and_b32_e32 v73, 0xffff0000, v72
	v_lshlrev_b32_e32 v72, 16, v72
	v_or_b32_sdwa v79, v73, v78 dst_sel:DWORD dst_unused:UNUSED_PAD src0_sel:DWORD src1_sel:WORD_1
	v_or_b32_sdwa v78, v72, v78 dst_sel:DWORD dst_unused:UNUSED_PAD src0_sel:DWORD src1_sel:WORD_0
	v_mul_f32_e32 v72, v110, v122
	v_mul_f32_e32 v71, v71, v72
	v_mul_f32_e32 v73, v123, v71
	v_cvt_pk_bf16_f32 v71, v71, s0
	v_cvt_pk_bf16_f32 v73, v73, s0
	ds_write_b16 v150, v71 offset:39168
	v_mul_f32_e32 v71, v109, v122
	ds_write_b16 v150, v73 offset:2304
	v_mul_f32_e32 v73, v70, v71
	v_rcp_f32_e32 v70, v71
	v_mul_f32_e32 v71, v123, v73
	v_cvt_pk_bf16_f32 v74, v71, s0
	v_mul_f32_e32 v71, v108, v122
	v_rcp_f32_e32 v72, v72
	v_cvt_pk_bf16_f32 v75, v73, s0
	v_mul_f32_e32 v69, v69, v71
	v_rcp_f32_e32 v73, v71
	v_mul_f32_e32 v71, v123, v69
	v_cvt_pk_bf16_f32 v85, v69, s0
	v_mul_f32_e32 v69, v107, v122
	v_cvt_pk_bf16_f32 v84, v71, s0
	v_mul_f32_e32 v68, v68, v69
	v_rcp_f32_e32 v71, v69
	v_mul_f32_e32 v69, v123, v68
	v_cvt_pk_bf16_f32 v86, v69, s0
	v_cvt_pk_bf16_f32 v87, v68, s0
	v_mul_f32_e32 v68, v92, v72
	v_mul_f32_e32 v69, v93, v73
	v_mul_f32_e32 v70, v94, v70
	v_mul_f32_e32 v71, v95, v71
	v_mul_f32_e32 v72, v116, v68
	v_cvt_pk_bf16_f32 v72, v72, s0
	ds_write_b16 v150, v72 offset:20736
	ds_write_b16 v150, v74 offset:2592
	v_mul_f32_e32 v72, v116, v70
	v_cvt_pk_bf16_f32 v72, v72, s0
	ds_write_b16 v150, v72 offset:21024
	ds_write_b16 v150, v75 offset:39456
	ds_write_b16 v150, v84 offset:2880
	v_mul_f32_e32 v72, v116, v69
	v_cvt_pk_bf16_f32 v72, v72, s0
	v_mul_f32_e32 v68, v102, v68
	v_mul_f32_e32 v69, v102, v69
	ds_write_b16 v150, v72 offset:21312
	ds_write_b16 v150, v85 offset:39744
	v_cvt_pk_bf16_f32 v72, v68, v69
	v_mul_f32_e32 v68, v116, v71
	v_cvt_pk_bf16_f32 v68, v68, s0
	ds_write_b16 v150, v86 offset:3168
	ds_write_b16 v150, v68 offset:21600
	ds_write_b16 v150, v87 offset:40032
	v_mul_f32_e32 v68, v102, v70
	v_mul_f32_e32 v69, v102, v71
	v_mul_f32_e32 v70, v106, v122
	v_mul_f32_e32 v67, v67, v70
	v_mul_f32_e32 v71, v123, v67
	v_cvt_pk_bf16_f32 v67, v67, s0
	v_cvt_pk_bf16_f32 v71, v71, s0
	ds_write_b16 v150, v67 offset:40320
	v_mul_f32_e32 v67, v105, v122
	v_cvt_pk_bf16_f32 v68, v68, v69
	ds_write_b16 v150, v71 offset:3456
	v_mul_f32_e32 v71, v66, v67
	v_and_b32_e32 v69, 0xffff0000, v68
	v_lshlrev_b32_e32 v68, 16, v68
	v_rcp_f32_e32 v66, v67
	v_mul_f32_e32 v67, v123, v71
	v_or_b32_sdwa v69, v69, v72 dst_sel:DWORD dst_unused:UNUSED_PAD src0_sel:DWORD src1_sel:WORD_1
	v_or_b32_sdwa v68, v68, v72 dst_sel:DWORD dst_unused:UNUSED_PAD src0_sel:DWORD src1_sel:WORD_0
	v_cvt_pk_bf16_f32 v72, v67, s0
	v_mul_f32_e32 v67, v104, v122
	v_rcp_f32_e32 v70, v70
	v_cvt_pk_bf16_f32 v73, v71, s0
	v_mul_f32_e32 v65, v65, v67
	v_rcp_f32_e32 v71, v67
	v_mul_f32_e32 v67, v123, v65
	v_cvt_pk_bf16_f32 v75, v65, s0
	v_mul_f32_e32 v65, v101, v122
	v_cvt_pk_bf16_f32 v74, v67, s0
	v_mul_f32_e32 v64, v64, v65
	v_rcp_f32_e32 v67, v65
	v_mul_f32_e32 v65, v123, v64
	v_cvt_pk_bf16_f32 v84, v65, s0
	v_cvt_pk_bf16_f32 v85, v64, s0
	v_mul_f32_e32 v64, v98, v70
	v_mul_f32_e32 v65, v99, v71
	v_mul_f32_e32 v66, v96, v66
	v_mul_f32_e32 v67, v97, v67
	v_mul_f32_e32 v70, v116, v64
	v_cvt_pk_bf16_f32 v70, v70, s0
	ds_write_b16 v150, v70 offset:21888
	ds_write_b16 v150, v72 offset:3744
	v_mul_f32_e32 v70, v116, v66
	v_cvt_pk_bf16_f32 v70, v70, s0
	ds_write_b16 v150, v70 offset:22176
	ds_write_b16 v150, v73 offset:40608
	ds_write_b16 v150, v74 offset:4032
	v_mul_f32_e32 v70, v116, v65
	v_cvt_pk_bf16_f32 v70, v70, s0
	v_mul_f32_e32 v64, v102, v64
	v_mul_f32_e32 v65, v102, v65
	ds_write_b16 v150, v70 offset:22464
	ds_write_b16 v150, v75 offset:40896
	v_cvt_pk_bf16_f32 v70, v64, v65
	v_mul_f32_e32 v64, v116, v67
	v_cvt_pk_bf16_f32 v64, v64, s0
	ds_write_b16 v150, v84 offset:4320
	ds_write_b16 v150, v64 offset:22752
	ds_write_b16 v150, v85 offset:41184
	v_mul_f32_e32 v64, v102, v66
	v_mul_f32_e32 v65, v102, v67
	v_cvt_pk_bf16_f32 v64, v64, v65
	v_and_b32_e32 v65, 0xffff0000, v64
	v_lshlrev_b32_e32 v64, 16, v64
	v_or_b32_sdwa v71, v65, v70 dst_sel:DWORD dst_unused:UNUSED_PAD src0_sel:DWORD src1_sel:WORD_1
	v_or_b32_sdwa v70, v64, v70 dst_sel:DWORD dst_unused:UNUSED_PAD src0_sel:DWORD src1_sel:WORD_0
	ds_write_b128 v157, v[76:79]
	ds_write_b128 v157, v[68:71] offset:16
	s_and_saveexec_b64 s[68:69], s[4:5]
	ds_write_b32 v145, v102
	s_or_b64 exec, exec, s[68:69]
	s_waitcnt lgkmcnt(0)
	s_barrier
	ds_read_b128 v[64:67], v159 offset:18432
	ds_read_b128 v[68:71], v146
	ds_read_b128 v[72:75], v146 offset:64
	ds_read_b128 v[76:79], v159 offset:18496
	s_waitcnt lgkmcnt(2)
	v_mfma_f32_16x16x32_bf16 v[64:67], v[64:67], v[68:71], 0
	ds_read_b128 v[84:87], v159 offset:23040
	ds_read_b128 v[88:91], v159 offset:23104
	ds_read_b128 v[92:95], v159 offset:27648
	ds_read_b128 v[96:99], v159 offset:27712
	s_waitcnt lgkmcnt(4)
	v_mfma_f32_16x16x32_bf16 v[64:67], v[76:79], v[72:75], v[64:67]
	ds_read_b128 v[76:79], v159 offset:18560
	s_waitcnt lgkmcnt(4)
	v_mfma_f32_16x16x32_bf16 v[84:87], v[84:87], v[68:71], 0
	s_waitcnt lgkmcnt(3)
	v_mfma_f32_16x16x32_bf16 v[84:87], v[88:91], v[72:75], v[84:87]
	ds_read_b128 v[88:91], v159 offset:32256
	ds_read_b128 v[100:103], v159 offset:32320
	ds_read_b128 v[104:107], v146 offset:128
	ds_read_b128 v[108:111], v159 offset:18624
	s_waitcnt lgkmcnt(6)
	v_mfma_f32_16x16x32_bf16 v[92:95], v[92:95], v[68:71], 0
	s_waitcnt lgkmcnt(1)
	v_mfma_f32_16x16x32_bf16 v[64:67], v[76:79], v[104:107], v[64:67]
	v_mfma_f32_16x16x32_bf16 v[92:95], v[96:99], v[72:75], v[92:95]
	ds_read_b128 v[96:99], v146 offset:192
	ds_read_b128 v[112:115], v159 offset:23168
	ds_read_b128 v[116:119], v159 offset:23232
	ds_read_b128 v[76:79], v159 offset:27776
	ds_read_b128 v[120:123], v159 offset:27840
	ds_read_b128 v[124:127], v159 offset:32384
	ds_read_b128 v[132:135], v159 offset:32448
	s_waitcnt lgkmcnt(6)
	v_mfma_f32_16x16x32_bf16 v[64:67], v[108:111], v[96:99], v[64:67]
	v_mov_b32_e32 v108, s81
	s_waitcnt lgkmcnt(5)
	v_mfma_f32_16x16x32_bf16 v[84:87], v[112:115], v[104:107], v[84:87]
	s_waitcnt lgkmcnt(3)
	v_mfma_f32_16x16x32_bf16 v[76:79], v[76:79], v[104:107], v[92:95]
	s_nop 2
	v_cndmask_b32_e64 v108, v64, v108, s[16:17]
	v_cndmask_b32_e64 v108, v108, v64, s[18:19]
	v_cndmask_b32_e64 v109, 0, v65, s[18:19]
	v_cndmask_b32_e64 v110, v66, 0, s[20:21]
	v_cndmask_b32_e64 v111, v67, 0, s[22:23]
	v_mfma_f32_16x16x32_bf16 v[64:67], v[116:119], v[96:99], v[84:87]
	s_waitcnt lgkmcnt(2)
	v_mfma_f32_16x16x32_bf16 v[76:79], v[120:123], v[96:99], v[76:79]
	s_nop 0
	v_mov_b32_e32 v84, s81
	s_nop 3
	v_cndmask_b32_e64 v84, v64, v84, s[24:25]
	v_mov_b32_e32 v64, s81
	v_cndmask_b32_e64 v85, v65, 0, s[26:27]
	v_cndmask_b32_e64 v92, v66, 0, s[28:29]
	v_cndmask_b32_e64 v93, v67, 0, s[30:31]
	v_cndmask_b32_e64 v112, v76, v64, s[34:35]
	v_mfma_f32_16x16x32_bf16 v[64:67], v[88:91], v[68:71], 0
	v_add_u32_e32 v69, 0xd800, v160
	v_cndmask_b32_e64 v113, v77, 0, s[36:37]
	v_cvt_pk_bf16_f32 v70, v108, v109
	v_mfma_f32_16x16x32_bf16 v[64:67], v[100:103], v[72:75], v[64:67]
	ds_read2_b64 v[74:77], v69 offset1:4
	v_add_u32_e32 v100, 0xe000, v160
	v_cvt_pk_bf16_f32 v72, v84, v85
	s_waitcnt lgkmcnt(2)
	v_mfma_f32_16x16x32_bf16 v[64:67], v[124:127], v[104:107], v[64:67]
	v_add_u32_e32 v104, 0xe800, v160
	v_add_u32_e32 v106, 0xf000, v160
	ds_read2_b64 v[84:87], v100 offset0:64 offset1:68
	s_waitcnt lgkmcnt(2)
	v_mfma_f32_16x16x32_bf16 v[64:67], v[132:135], v[96:99], v[64:67]
	v_cvt_pk_bf16_f32 v73, v92, v93
	ds_read2_b64 v[88:91], v104 offset0:128 offset1:132
	ds_read2_b64 v[92:95], v106 offset0:192 offset1:196
	ds_read2_b64 v[96:99], v69 offset0:8 offset1:12
	v_cvt_pk_bf16_f32 v71, v110, v111
	v_mov_b32_e32 v68, s81
	v_cndmask_b32_e64 v78, v78, 0, s[38:39]
	s_waitcnt lgkmcnt(4)
	v_mfma_f32_16x16x32_bf16 v[74:77], v[74:77], v[70:73], 0
	v_cndmask_b32_e64 v79, v79, 0, s[40:41]
	v_cndmask_b32_e64 v105, v64, v68, s[42:43]
	v_cndmask_b32_e64 v107, v65, 0, s[44:45]
	v_cndmask_b32_e64 v108, v66, 0, s[46:47]
	v_cndmask_b32_e64 v67, v67, 0, s[48:49]
	v_cvt_pk_bf16_f32 v64, v112, v113
	v_cvt_pk_bf16_f32 v65, v78, v79
	v_cvt_pk_bf16_f32 v66, v105, v107
	v_cvt_pk_bf16_f32 v67, v108, v67
	s_waitcnt lgkmcnt(3)
	v_mfma_f32_16x16x32_bf16 v[84:87], v[84:87], v[70:73], 0
	ds_read2_b64 v[100:103], v100 offset0:72 offset1:76
	s_waitcnt lgkmcnt(3)
	v_mfma_f32_16x16x32_bf16 v[88:91], v[88:91], v[70:73], 0
	s_waitcnt lgkmcnt(2)
	v_mfma_f32_16x16x32_bf16 v[68:71], v[92:95], v[70:73], 0
	ds_read2_b64 v[92:95], v106 offset0:200 offset1:204
	s_waitcnt lgkmcnt(2)
	v_mfma_f32_16x16x32_bf16 v[72:75], v[96:99], v[64:67], v[74:77]
	s_nop 2
	ds_read2_b64 v[76:79], v104 offset0:136 offset1:140
	s_waitcnt lgkmcnt(0)
	v_mfma_f32_16x16x32_bf16 v[76:79], v[76:79], v[64:67], v[88:91]
	s_nop 2
	ds_read_b128 v[88:91], v161
	v_mfma_f32_16x16x32_bf16 v[84:87], v[100:103], v[64:67], v[84:87]
	v_mfma_f32_16x16x32_bf16 v[64:67], v[92:95], v[64:67], v[68:71]
	s_nop 2
	ds_read_b128 v[68:71], v146 offset:36864
	ds_read_b128 v[92:95], v146 offset:36928
	ds_read_b128 v[96:99], v161 offset:64
	s_waitcnt lgkmcnt(2)
	v_mfma_f32_16x16x32_bf16 v[72:75], v[88:91], v[68:71], v[72:75]
	ds_read_b128 v[88:91], v161 offset:4608
	ds_read_b128 v[100:103], v161 offset:4672
	s_waitcnt lgkmcnt(1)
	v_mfma_f32_16x16x32_bf16 v[84:87], v[88:91], v[68:71], v[84:87]
	ds_read_b128 v[88:91], v161 offset:9216
	ds_read_b128 v[104:107], v161 offset:9280
	s_waitcnt lgkmcnt(1)
	v_mfma_f32_16x16x32_bf16 v[76:79], v[88:91], v[68:71], v[76:79]
	ds_read_b128 v[88:91], v161 offset:13824
	ds_read_b128 v[108:111], v161 offset:13888
	s_waitcnt lgkmcnt(1)
	v_mfma_f32_16x16x32_bf16 v[64:67], v[88:91], v[68:71], v[64:67]
	v_mfma_f32_16x16x32_bf16 v[68:71], v[96:99], v[92:95], v[72:75]
	v_mfma_f32_16x16x32_bf16 v[72:75], v[100:103], v[92:95], v[84:87]
	v_mfma_f32_16x16x32_bf16 v[84:87], v[104:107], v[92:95], v[76:79]
	s_nop 2
	ds_read_b128 v[76:79], v161 offset:128
	ds_read_b128 v[88:91], v146 offset:36992
	s_waitcnt lgkmcnt(2)
	v_mfma_f32_16x16x32_bf16 v[64:67], v[108:111], v[92:95], v[64:67]
	ds_read_b128 v[92:95], v161 offset:192
	ds_read_b128 v[96:99], v146 offset:37056
	ds_read_b128 v[100:103], v161 offset:4736
	ds_read_b128 v[104:107], v161 offset:4800
	ds_read_b128 v[108:111], v161 offset:9344
	ds_read_b128 v[112:115], v161 offset:9408
	s_waitcnt lgkmcnt(6)
	v_mfma_f32_16x16x32_bf16 v[68:71], v[76:79], v[88:91], v[68:71]
	s_waitcnt lgkmcnt(4)
	v_mfma_f32_16x16x32_bf16 v[76:79], v[92:95], v[96:99], v[68:71]
	ds_read_b128 v[92:95], v161 offset:13952
	ds_read_b128 v[116:119], v161 offset:14016
	s_waitcnt lgkmcnt(5)
	v_mfma_f32_16x16x32_bf16 v[68:71], v[100:103], v[88:91], v[72:75]
	s_nop 3
	v_mul_f32_e32 v120, v77, v77
	v_fmac_f32_e32 v120, v76, v76
	v_mul_f32_e32 v72, v79, v79
	v_fmac_f32_e32 v72, v78, v78
	v_add_f32_e32 v100, v120, v72
	s_waitcnt lgkmcnt(4)
	v_mfma_f32_16x16x32_bf16 v[72:75], v[104:107], v[96:99], v[68:71]
	s_waitcnt lgkmcnt(3)
	v_mfma_f32_16x16x32_bf16 v[68:71], v[108:111], v[88:91], v[84:87]
	s_waitcnt lgkmcnt(1)
	v_mfma_f32_16x16x32_bf16 v[64:67], v[92:95], v[88:91], v[64:67]
	s_nop 3
	v_mul_f32_e32 v101, v73, v73
	v_mul_f32_e32 v102, v75, v75
	v_fmac_f32_e32 v101, v72, v72
	v_mfma_f32_16x16x32_bf16 v[68:71], v[112:115], v[96:99], v[68:71]
	v_fmac_f32_e32 v102, v74, v74
	v_add_f32_e32 v84, v101, v102
	v_add_f32_e32 v84, v100, v84
	s_waitcnt lgkmcnt(0)
	v_mfma_f32_16x16x32_bf16 v[64:67], v[116:119], v[96:99], v[64:67]
	s_nop 2
	v_mul_f32_e32 v85, v69, v69
	v_mul_f32_e32 v86, v71, v71
	v_fmac_f32_e32 v85, v68, v68
	v_fmac_f32_e32 v86, v70, v70
	v_add_f32_e32 v85, v85, v86
	v_add_f32_e32 v84, v84, v85
	v_mul_f32_e32 v85, v65, v65
	v_mul_f32_e32 v86, v67, v67
	v_fmac_f32_e32 v85, v64, v64
	v_fmac_f32_e32 v86, v66, v66
	v_add_f32_e32 v85, v85, v86
	v_and_b32_e32 v86, 64, v162
	v_add_f32_e32 v84, v84, v85
	v_xor_b32_e32 v85, 16, v162
	v_add_u32_e32 v86, 64, v86
	v_cmp_lt_i32_e32 vcc, v85, v86
	s_nop 1
	v_cndmask_b32_e32 v85, v162, v85, vcc
	v_lshlrev_b32_e32 v85, 2, v85
	v_mov_b32_e32 v85, v84
	s_nop 1
	v_permlane16_swap_b32_e32 v84, v85
	s_waitcnt lgkmcnt(0)
	v_add_f32_e32 v84, v84, v85
	v_xor_b32_e32 v85, 32, v162
	v_cmp_lt_i32_e32 vcc, v85, v86
	s_nop 1
	v_cndmask_b32_e32 v85, v162, v85, vcc
	v_lshlrev_b32_e32 v85, 2, v85
	v_mov_b32_e32 v85, v84
	s_nop 1
	v_permlane32_swap_b32_e32 v84, v85
	s_and_saveexec_b64 s[68:69], s[8:9]
	s_cbranch_execz .LBB0_450
	s_waitcnt lgkmcnt(0)
	v_add_f32_e32 v84, v84, v85
	ds_write_b32 v163, v84
	s_branch .LBB0_450

.LBB0_986:
	s_waitcnt vmcnt(2)
	v_lshlrev_b32_e32 v33, 16, v145
	v_mul_f32_e32 v33, 0xbfb8aa3b, v33
	v_exp_f32_e32 v33, v33
	v_lshlrev_b32_e32 v32, 16, v183
	v_mul_f32_e32 v32, 0xbfb8aa3b, v32
	v_exp_f32_e32 v32, v32
	v_add_f32_e32 v33, 1.0, v33
	v_rcp_f32_e32 v33, v33
	v_mov_b64_e32 v[58:59], v[54:55]
	v_add_f32_e32 v32, 1.0, v32
	v_rcp_f32_e32 v32, v32
	v_div_scale_f32 v34, s[0:1], v80, v80, v33
	v_rcp_f32_e32 v35, v34
	v_div_scale_f32 v36, vcc, v33, v80, v33
	v_mul_f32_e32 v32, v32, v135
	v_fma_f32 v37, -v34, v35, 1.0
	v_fmac_f32_e32 v35, v37, v35
	v_mul_f32_e32 v37, v36, v35
	v_fma_f32 v38, -v34, v37, v36
	v_fmac_f32_e32 v37, v38, v35
	v_fma_f32 v34, -v34, v37, v36
	v_div_fmas_f32 v34, v34, v35, v37
	v_div_fixup_f32 v33, v34, v80, v33
	v_cmp_lt_f32_e32 vcc, 0, v80
	v_alignbit_b32 v37, v185, v133, 16
	v_mov_b64_e32 v[62:63], v[50:51]
	v_cndmask_b32_e32 v34, 0, v33, vcc
	v_mul_f32_e32 v0, v0, v34
	v_mul_f32_e32 v1, v1, v34
	v_mul_f32_e32 v2, v2, v34
	v_mul_f32_e32 v3, v3, v34
	v_mul_f32_e32 v4, v4, v34
	v_mul_f32_e32 v5, v5, v34
	v_mul_f32_e32 v6, v6, v34
	v_mul_f32_e32 v7, v7, v34
	v_mul_f32_e32 v8, v8, v34
	v_mul_f32_e32 v9, v9, v34
	v_fma_f32 v0, v72, v32, v0
	v_fma_f32 v1, v73, v32, v1
	v_fma_f32 v2, v74, v32, v2
	v_fma_f32 v3, v75, v32, v3
	v_fma_f32 v4, v76, v32, v4
	v_fma_f32 v5, v77, v32, v5
	v_fma_f32 v6, v78, v32, v6
	v_fma_f32 v7, v79, v32, v7
	v_fma_f32 v8, v68, v32, v8
	v_fma_f32 v9, v69, v32, v9
	v_and_b32_e32 v33, 0xffff0000, v145
	v_mul_f32_e32 v33, 0xbfb8aa3b, v33
	v_exp_f32_e32 v33, v33
	v_mul_f32_e32 v10, v10, v34
	v_mul_f32_e32 v11, v11, v34
	v_mul_f32_e32 v12, v12, v34
	v_mul_f32_e32 v13, v13, v34
	v_ashrrev_i32_e32 v145, 31, v144
	v_fma_f32 v10, v70, v32, v10
	v_fma_f32 v11, v71, v32, v11
	v_fma_f32 v12, v64, v32, v12
	v_fma_f32 v13, v65, v32, v13
	v_add_f32_e32 v33, 1.0, v33
	v_rcp_f32_e32 v35, v33
	v_mov_b64_e32 v[56:57], v[52:53]
	v_mov_b64_e32 v[60:61], v[48:49]
	v_mov_b32_e32 v183, v133
	v_mul_f32_e32 v14, v14, v34
	v_mul_f32_e32 v15, v15, v34
	v_div_scale_f32 v34, s[0:1], v82, v82, v35
	v_rcp_f32_e32 v36, v34
	v_fma_f32 v14, v66, v32, v14
	v_fma_f32 v15, v67, v32, v15
	v_lshl_add_u64 v[32:33], v[144:145], 0, s[40:41]
	s_mov_b32 s22, s73
	v_fma_f32 v38, -v34, v36, 1.0
	v_fmac_f32_e32 v36, v38, v36
	v_div_scale_f32 v38, vcc, v35, v82, v35
	v_mul_f32_e32 v39, v38, v36
	s_waitcnt vmcnt(0)
	v_fma_f32 v40, -v34, v39, v38
	v_fmac_f32_e32 v39, v40, v36
	v_fma_f32 v34, -v34, v39, v38
	v_div_fmas_f32 v34, v34, v36, v39
	v_div_fixup_f32 v34, v34, v82, v35
	v_cmp_lt_f32_e32 vcc, 0, v82
	v_mov_b32_e32 v145, v37
	s_nop 0
	v_cndmask_b32_e32 v34, 0, v34, vcc
	v_fma_f32 v0, v16, v34, v0
	v_fma_f32 v1, v17, v34, v1
	v_lshlrev_b64 v[16:17], 11, v[32:33]
	v_fma_f32 v2, v18, v34, v2
	v_fma_f32 v3, v19, v34, v3
	v_lshl_add_u64 v[16:17], s[38:39], 0, v[16:17]
	v_lshlrev_b32_e32 v18, 7, v184
	v_mov_b32_e32 v19, v123
	v_lshl_add_u64 v[16:17], v[16:17], 0, v[18:19]
	v_lshlrev_b32_e32 v18, 1, v124
	v_fma_f32 v4, v20, v34, v4
	v_fma_f32 v5, v21, v34, v5
	v_fma_f32 v6, v22, v34, v6
	v_fma_f32 v7, v23, v34, v7
	v_lshl_add_u64 v[16:17], v[16:17], 0, v[18:19]
	v_cvt_pk_bf16_f32 v0, v0, v1
	v_cvt_pk_bf16_f32 v1, v2, v3
	v_fma_f32 v8, v24, v34, v8
	v_fma_f32 v9, v25, v34, v9
	v_fma_f32 v10, v26, v34, v10
	v_fma_f32 v11, v27, v34, v11
	global_store_dwordx2 v[16:17], v[0:1], off
	v_cvt_pk_bf16_f32 v0, v4, v5
	v_cvt_pk_bf16_f32 v1, v6, v7
	v_fma_f32 v12, v28, v34, v12
	v_fma_f32 v13, v29, v34, v13
	v_fma_f32 v14, v30, v34, v14
	v_fma_f32 v15, v31, v34, v15
	global_store_dwordx2 v[16:17], v[0:1], off offset:32
	v_cvt_pk_bf16_f32 v0, v8, v9
	v_cvt_pk_bf16_f32 v1, v10, v11
	global_store_dwordx2 v[16:17], v[0:1], off offset:64
	v_cvt_pk_bf16_f32 v0, v12, v13
	v_cvt_pk_bf16_f32 v1, v14, v15
	s_andn2_b64 vcc, exec, s[48:49]
	global_store_dwordx2 v[16:17], v[0:1], off offset:96
	s_cbranch_vccz .LBB0_1074

.LBB0_1010:
	s_add_i32 s0, s23, 0xffffff40
	s_and_b32 s0, s0, 0x80
	s_mulk_i32 s0, 0xa0
	s_waitcnt lgkmcnt(6)
	v_add_u32_e32 v92, s0, v153
	ds_read_b128 v[16:19], v92
	ds_read_b128 v[20:23], v92 offset:64
	ds_read_b128 v[24:27], v92 offset:2560
	ds_read_b128 v[28:31], v92 offset:2624
	ds_read_b128 v[32:35], v92 offset:5120
	ds_read_b128 v[36:39], v92 offset:5184
	ds_read_b128 v[40:43], v92 offset:7680
	s_waitcnt lgkmcnt(12)
	ds_read_b128 v[94:97], v92 offset:7744
	s_setprio 1
	s_waitcnt lgkmcnt(7)
	v_mfma_f32_16x16x32_bf16 v[16:19], v[16:19], v[60:63], 0
	s_waitcnt lgkmcnt(6)
	v_mfma_f32_16x16x32_bf16 v[106:109], v[20:23], v[56:59], v[16:19]
	s_waitcnt lgkmcnt(5)
	v_mfma_f32_16x16x32_bf16 v[16:19], v[24:27], v[60:63], 0
	s_waitcnt lgkmcnt(4)
	v_mfma_f32_16x16x32_bf16 v[24:27], v[28:31], v[56:59], v[16:19]
	s_waitcnt lgkmcnt(3)
	v_mfma_f32_16x16x32_bf16 v[16:19], v[32:35], v[60:63], 0
	s_waitcnt lgkmcnt(2)
	v_mfma_f32_16x16x32_bf16 v[20:23], v[36:39], v[56:59], v[16:19]
	s_waitcnt lgkmcnt(1)
	v_mfma_f32_16x16x32_bf16 v[16:19], v[40:43], v[60:63], 0
	s_waitcnt lgkmcnt(0)
	v_mfma_f32_16x16x32_bf16 v[16:19], v[94:97], v[56:59], v[16:19]
	s_setprio 0
	v_add_u32_e32 v101, 0x330, v89
	v_cvt_f32_i32_e32 v28, v101
	s_add_i32 s0, s23, 0xffffff7f
	s_cmp_gt_i32 s0, s22
	s_mov_b64 s[0:1], -1
	v_mul_f32_e32 v29, v146, v28
	v_fma_f32 v28, -v146, v28, v85
	v_fmamk_f32 v105, v106, 0x3e38aa3b, v28
	v_add_f32_e32 v102, v82, v28
	v_add_f32_e32 v103, v83, v28
	v_add_f32_e32 v104, v84, v28
	v_sub_f32_e32 v28, v86, v29
	v_sub_f32_e32 v30, v87, v29
	v_sub_f32_e32 v29, v88, v29
	v_fmac_f32_e32 v102, 0x3e38aa3b, v107
	v_fmac_f32_e32 v103, 0x3e38aa3b, v108
	v_fmac_f32_e32 v104, 0x3e38aa3b, v109
	v_fmamk_f32 v100, v24, 0x3e38aa3b, v28
	v_add_f32_e32 v99, v82, v28
	v_add_f32_e32 v98, v83, v28
	v_add_f32_e32 v97, v84, v28
	v_fmamk_f32 v96, v20, 0x3e38aa3b, v30
	v_add_f32_e32 v95, v82, v30
	v_add_f32_e32 v94, v83, v30
	v_add_f32_e32 v93, v84, v30
	v_fmamk_f32 v91, v16, 0x3e38aa3b, v29
	v_add_f32_e32 v24, v82, v29
	v_add_f32_e32 v20, v83, v29
	v_add_f32_e32 v16, v84, v29
	s_cbranch_scc1 .LBB0_1012
	v_mov_b32_e32 v28, v105
	v_mov_b32_e32 v29, v102
	v_mov_b32_e32 v30, v103
	v_mov_b32_e32 v31, v104
	v_exp_f32_e32 v28, v28
	v_exp_f32_e32 v29, v29
	v_fmamk_f32 v33, v25, 0x3e38aa3b, v99
	v_mov_b32_e32 v32, v100
	v_exp_f32_e32 v30, v30
	v_exp_f32_e32 v31, v31
	v_fmamk_f32 v34, v26, 0x3e38aa3b, v98
	v_fmamk_f32 v35, v27, 0x3e38aa3b, v97
	v_add_f32_e32 v106, 0, v28
	v_add_f32_e32 v107, 0, v29
	v_exp_f32_e32 v32, v32
	v_exp_f32_e32 v33, v33
	v_fmamk_f32 v37, v21, 0x3e38aa3b, v95
	v_mov_b32_e32 v36, v96
	v_add_f32_e32 v106, v106, v30
	v_add_f32_e32 v107, v107, v31
	v_exp_f32_e32 v34, v34
	v_exp_f32_e32 v35, v35
	v_fmamk_f32 v38, v22, 0x3e38aa3b, v94
	v_fmamk_f32 v39, v23, 0x3e38aa3b, v93
	v_add_f32_e32 v106, v106, v32
	v_add_f32_e32 v107, v107, v33
	v_exp_f32_e32 v36, v36
	v_exp_f32_e32 v37, v37
	v_fmamk_f32 v41, v17, 0x3e38aa3b, v24
	v_mov_b32_e32 v40, v91
	v_add_f32_e32 v106, v106, v34
	v_add_f32_e32 v107, v107, v35
	v_exp_f32_e32 v38, v38
	v_exp_f32_e32 v39, v39
	v_fmamk_f32 v42, v18, 0x3e38aa3b, v20
	v_fmamk_f32 v43, v19, 0x3e38aa3b, v16
	v_add_f32_e32 v106, v106, v36
	v_add_f32_e32 v107, v107, v37
	v_exp_f32_e32 v40, v40
	v_exp_f32_e32 v41, v41
	v_add_f32_e32 v106, v106, v38
	v_add_f32_e32 v107, v107, v39
	v_exp_f32_e32 v42, v42
	v_exp_f32_e32 v43, v43
	s_mov_b64 s[0:1], 0
	v_add_f32_e32 v106, v106, v40
	v_add_f32_e32 v107, v107, v41
	s_nop 0
	v_add_f32_e32 v106, v106, v42
	v_add_f32_e32 v107, v107, v43
	s_nop 0
	v_add_f32_e32 v90, v106, v107
.LBB0_1012:
	s_andn2_b64 vcc, exec, s[0:1]
	s_cbranch_vccnz .LBB0_1014
	v_cmp_gt_u32_e32 vcc, s70, v101
	v_add_u32_e32 v29, 0x320, v89
	v_add_u32_e32 v30, 0x310, v89
	v_cndmask_b32_e32 v28, v179, v105, vcc
	v_cmp_gt_u32_e32 vcc, s70, v29
	v_add_u32_e32 v31, 0x300, v89
	v_fmac_f32_e32 v99, 0x3e38aa3b, v25
	v_cndmask_b32_e32 v29, v179, v102, vcc
	v_cmp_gt_u32_e32 vcc, s70, v30
	v_add_u32_e32 v25, 0x230, v89
	v_fmac_f32_e32 v98, 0x3e38aa3b, v26
	v_cndmask_b32_e32 v30, v179, v103, vcc
	v_cmp_gt_u32_e32 vcc, s70, v31
	v_add_u32_e32 v26, 0x220, v89
	v_fmac_f32_e32 v97, 0x3e38aa3b, v27
	v_cndmask_b32_e32 v31, v179, v104, vcc
	v_cmp_gt_u32_e32 vcc, s70, v25
	v_add_u32_e32 v27, 0x210, v89
	v_add_u32_e32 v32, 0x200, v89
	v_cndmask_b32_e32 v25, v179, v100, vcc
	v_cmp_gt_u32_e32 vcc, s70, v26
	v_fmac_f32_e32 v95, 0x3e38aa3b, v21
	v_add_u32_e32 v21, 0x130, v89
	v_cndmask_b32_e32 v26, v179, v99, vcc
	v_cmp_gt_u32_e32 vcc, s70, v27
	v_fmac_f32_e32 v94, 0x3e38aa3b, v22
	v_add_u32_e32 v22, 0x120, v89
	v_cndmask_b32_e32 v27, v179, v98, vcc
	v_cmp_gt_u32_e32 vcc, s70, v32
	v_fmac_f32_e32 v93, 0x3e38aa3b, v23
	v_add_u32_e32 v23, 0x110, v89
	v_cndmask_b32_e32 v35, v179, v97, vcc
	v_cmp_gt_u32_e32 vcc, s70, v21
	v_exp_f32_e32 v32, v25
	v_add_u32_e32 v25, 0x100, v89
	v_cndmask_b32_e32 v21, v179, v96, vcc
	v_cmp_gt_u32_e32 vcc, s70, v22
	v_fmac_f32_e32 v24, 0x3e38aa3b, v17
	v_add_u32_e32 v17, 48, v89
	v_cndmask_b32_e32 v22, v179, v95, vcc
	v_cmp_gt_u32_e32 vcc, s70, v23
	v_fmac_f32_e32 v20, 0x3e38aa3b, v18
	v_add_u32_e32 v18, 32, v89
	v_cndmask_b32_e32 v23, v179, v94, vcc
	v_cmp_gt_u32_e32 vcc, s70, v25
	v_fmac_f32_e32 v16, 0x3e38aa3b, v19
	v_add_u32_e32 v19, 16, v89
	v_cndmask_b32_e32 v25, v179, v93, vcc
	v_cmp_gt_u32_e32 vcc, s70, v17
	v_exp_f32_e32 v28, v28
	v_exp_f32_e32 v29, v29
	v_cndmask_b32_e32 v17, v179, v91, vcc
	v_cmp_gt_u32_e32 vcc, s70, v18
	v_exp_f32_e32 v30, v30
	v_exp_f32_e32 v31, v31
	v_cndmask_b32_e32 v18, v179, v24, vcc
	v_cmp_gt_u32_e32 vcc, s70, v19
	v_exp_f32_e32 v40, v17
	s_nop 0
	v_cndmask_b32_e32 v19, v179, v20, vcc
	v_cmp_gt_u32_e32 vcc, s70, v89
	v_exp_f32_e32 v33, v26
	v_exp_f32_e32 v34, v27
	v_cndmask_b32_e32 v16, v179, v16, vcc
	v_exp_f32_e32 v43, v16
	v_add_f32_e32 v16, 0, v28
	v_add_f32_e32 v17, 0, v29
	v_exp_f32_e32 v35, v35
	v_add_f32_e32 v16, v16, v30
	v_add_f32_e32 v17, v17, v31
	v_exp_f32_e32 v36, v21
	v_add_f32_e32 v16, v16, v32
	v_add_f32_e32 v17, v17, v33
	v_exp_f32_e32 v37, v22
	v_add_f32_e32 v16, v16, v34
	v_add_f32_e32 v17, v17, v35
	v_exp_f32_e32 v38, v23
	v_exp_f32_e32 v39, v25
	v_exp_f32_e32 v41, v18
	v_add_f32_e32 v16, v16, v36
	v_add_f32_e32 v17, v17, v37
	v_exp_f32_e32 v42, v19
	v_add_f32_e32 v16, v16, v38
	v_add_f32_e32 v17, v17, v39
	s_nop 0
	v_add_f32_e32 v16, v16, v40
	v_add_f32_e32 v17, v17, v41
	s_nop 0
	v_add_f32_e32 v16, v16, v42
	v_add_f32_e32 v17, v17, v43
	s_nop 0
	v_add_f32_e32 v90, v16, v17
.LBB0_1014:
	v_mul_f32_e32 v16, 0.5, v31
	ds_bpermute_b32 v16, v181, v16
	v_add_f32_e32 v18, v28, v29
	v_fma_f32 v19, 0.5, v31, v30
	v_add_f32_e32 v18, v18, v19
	v_add_u32_e32 v91, s23, v170
	s_waitcnt lgkmcnt(0)
	v_cndmask_b32_e64 v19, v16, v81, s[4:5]
	v_add_f32_e32 v18, v18, v19
	v_mul_f32_e32 v19, 0.5, v35
	v_add_u32_e32 v17, 0x13f40, v91
	ds_bpermute_b32 v19, v181, v19
	ds_write_b32 v17, v18
	v_add_f32_e32 v17, v32, v33
	v_fma_f32 v18, 0.5, v35, v34
	v_add_f32_e32 v17, v17, v18
	v_mul_f32_e32 v18, 0.5, v39
	ds_bpermute_b32 v18, v181, v18
	s_waitcnt lgkmcnt(2)
	v_cndmask_b32_e64 v16, v19, v16, s[4:5]
	v_add_f32_e32 v16, v17, v16
	v_add_u32_e32 v17, 0x13f50, v91
	ds_write_b32 v17, v16
	v_add_f32_e32 v16, v36, v37
	v_fma_f32 v17, 0.5, v39, v38
	v_add_f32_e32 v16, v16, v17
	s_waitcnt lgkmcnt(1)
	v_cndmask_b32_e64 v17, v18, v19, s[4:5]
	v_mul_f32_e32 v19, 0.5, v43
	ds_bpermute_b32 v81, v181, v19
	v_add_f32_e32 v16, v16, v17
	v_add_u32_e32 v17, 0x13f60, v91
	ds_write_b32 v17, v16
	v_add_f32_e32 v16, v40, v41
	v_fma_f32 v17, 0.5, v43, v42
	v_add_f32_e32 v16, v16, v17
	s_waitcnt lgkmcnt(1)
	v_cndmask_b32_e64 v17, v81, v18, s[4:5]
	v_add_f32_e32 v16, v16, v17
	v_add_u32_e32 v17, 0x13f70, v91
	ds_write_b32 v17, v16
	ds_read_b128 v[16:19], v92 offset:40960
	ds_read_b128 v[20:23], v92 offset:43520
	ds_read_b128 v[24:27], v92 offset:46080
	ds_read_b128 v[94:97], v92 offset:48640
	v_cvt_pk_bf16_f32 v28, v28, v29
	v_cvt_pk_bf16_f32 v29, v30, v31
	v_cvt_pk_bf16_f32 v30, v32, v33
	v_cvt_pk_bf16_f32 v31, v34, v35
	s_setprio 1
	s_waitcnt lgkmcnt(3)
	v_mfma_f32_16x16x32_bf16 v[16:19], v[16:19], v[28:31], v[72:75]
	s_waitcnt lgkmcnt(2)
	v_mfma_f32_16x16x32_bf16 v[20:23], v[20:23], v[28:31], v[76:79]
	s_waitcnt lgkmcnt(1)
	v_mfma_f32_16x16x32_bf16 v[24:27], v[24:27], v[28:31], v[68:71]
	s_waitcnt lgkmcnt(0)
	v_mfma_f32_16x16x32_bf16 v[28:31], v[94:97], v[28:31], v[64:67]
	s_setprio 0
	ds_read_b128 v[32:35], v92 offset:41024
	s_nop 0
	ds_read_b128 v[64:67], v92 offset:43584
	ds_read_b128 v[68:71], v92 offset:46144
	ds_read_b128 v[72:75], v92 offset:48704
	v_cvt_pk_bf16_f32 v36, v36, v37
	v_cvt_pk_bf16_f32 v37, v38, v39
	v_cvt_pk_bf16_f32 v38, v40, v41
	v_cvt_pk_bf16_f32 v39, v42, v43
	s_setprio 1
	s_waitcnt lgkmcnt(3)
	v_mfma_f32_16x16x32_bf16 v[16:19], v[32:35], v[36:39], v[16:19]
	s_waitcnt lgkmcnt(2)
	v_mfma_f32_16x16x32_bf16 v[20:23], v[64:67], v[36:39], v[20:23]
	s_waitcnt lgkmcnt(1)
	v_mfma_f32_16x16x32_bf16 v[24:27], v[68:71], v[36:39], v[24:27]
	s_waitcnt lgkmcnt(0)
	v_mfma_f32_16x16x32_bf16 v[28:31], v[72:75], v[36:39], v[28:31]
	s_setprio 0
	s_add_i32 s0, s23, 0xffffff80
	s_and_b32 s0, s0, 0xc0
	s_mulk_i32 s0, 0xa0
	v_add_u32_e32 v92, s0, v153
	ds_read_b128 v[32:35], v92
	ds_read_b128 v[36:39], v92 offset:64
	ds_read_b128 v[40:43], v92 offset:2560
	ds_read_b128 v[64:67], v92 offset:2624
	ds_read_b128 v[68:71], v92 offset:5120
	ds_read_b128 v[72:75], v92 offset:5184
	ds_read_b128 v[76:79], v92 offset:7680
	ds_read_b128 v[94:97], v92 offset:7744
	s_setprio 1
	s_waitcnt lgkmcnt(7)
	v_mfma_f32_16x16x32_bf16 v[32:35], v[32:35], v[60:63], 0
	s_waitcnt lgkmcnt(6)
	v_mfma_f32_16x16x32_bf16 v[98:101], v[36:39], v[56:59], v[32:35]
	s_waitcnt lgkmcnt(5)
	v_mfma_f32_16x16x32_bf16 v[32:35], v[40:43], v[60:63], 0
	s_waitcnt lgkmcnt(4)
	v_mfma_f32_16x16x32_bf16 v[40:43], v[64:67], v[56:59], v[32:35]
	s_waitcnt lgkmcnt(3)
	v_mfma_f32_16x16x32_bf16 v[32:35], v[68:71], v[60:63], 0
	s_waitcnt lgkmcnt(2)
	v_mfma_f32_16x16x32_bf16 v[36:39], v[72:75], v[56:59], v[32:35]
	s_waitcnt lgkmcnt(1)
	v_mfma_f32_16x16x32_bf16 v[32:35], v[76:79], v[60:63], 0
	s_waitcnt lgkmcnt(0)
	v_mfma_f32_16x16x32_bf16 v[32:35], v[94:97], v[56:59], v[32:35]
	s_setprio 0
	v_add_u32_e32 v102, 0xffffff30, v89
	v_cvt_f32_i32_e32 v64, v102
	s_add_i32 s0, s23, 0xffffffbf
	s_cmp_gt_i32 s0, s22
	s_mov_b64 s[0:1], -1
	v_mul_f32_e32 v65, v146, v64
	v_fma_f32 v64, -v146, v64, v85
	v_fmamk_f32 v106, v98, 0x3e38aa3b, v64
	v_add_f32_e32 v103, v82, v64
	v_add_f32_e32 v104, v83, v64
	v_add_f32_e32 v105, v84, v64
	v_sub_f32_e32 v64, v86, v65
	v_sub_f32_e32 v66, v87, v65
	v_sub_f32_e32 v65, v88, v65
	v_fmac_f32_e32 v103, 0x3e38aa3b, v99
	v_fmac_f32_e32 v104, 0x3e38aa3b, v100
	v_fmac_f32_e32 v105, 0x3e38aa3b, v101
	v_fmamk_f32 v101, v40, 0x3e38aa3b, v64
	v_add_f32_e32 v100, v82, v64
	v_add_f32_e32 v99, v83, v64
	v_add_f32_e32 v98, v84, v64
	v_fmamk_f32 v97, v36, 0x3e38aa3b, v66
	v_add_f32_e32 v96, v82, v66
	v_add_f32_e32 v95, v83, v66
	v_add_f32_e32 v94, v84, v66
	v_fmamk_f32 v93, v32, 0x3e38aa3b, v65
	v_add_f32_e32 v40, v82, v65
	v_add_f32_e32 v36, v83, v65
	v_add_f32_e32 v32, v84, v65
	s_cbranch_scc1 .LBB0_1016
	v_mov_b32_e32 v64, v106
	v_mov_b32_e32 v65, v103
	v_mov_b32_e32 v66, v104
	v_mov_b32_e32 v67, v105
	v_exp_f32_e32 v64, v64
	v_exp_f32_e32 v65, v65
	v_fmamk_f32 v69, v41, 0x3e38aa3b, v100
	v_mov_b32_e32 v68, v101
	v_exp_f32_e32 v66, v66
	v_exp_f32_e32 v67, v67
	v_fmamk_f32 v70, v42, 0x3e38aa3b, v99
	v_fmamk_f32 v71, v43, 0x3e38aa3b, v98
	v_add_f32_e32 v108, 0, v64
	v_add_f32_e32 v109, 0, v65
	v_exp_f32_e32 v68, v68
	v_exp_f32_e32 v69, v69
	v_fmamk_f32 v73, v37, 0x3e38aa3b, v96
	v_mov_b32_e32 v72, v97
	v_add_f32_e32 v108, v108, v66
	v_add_f32_e32 v109, v109, v67
	v_exp_f32_e32 v70, v70
	v_exp_f32_e32 v71, v71
	v_fmamk_f32 v74, v38, 0x3e38aa3b, v95
	v_fmamk_f32 v75, v39, 0x3e38aa3b, v94
	v_add_f32_e32 v108, v108, v68
	v_add_f32_e32 v109, v109, v69
	v_exp_f32_e32 v72, v72
	v_exp_f32_e32 v73, v73
	v_fmamk_f32 v77, v33, 0x3e38aa3b, v40
	v_mov_b32_e32 v76, v93
	v_add_f32_e32 v108, v108, v70
	v_add_f32_e32 v109, v109, v71
	v_exp_f32_e32 v74, v74
	v_exp_f32_e32 v75, v75
	v_fmamk_f32 v78, v34, 0x3e38aa3b, v36
	v_fmamk_f32 v79, v35, 0x3e38aa3b, v32
	v_add_f32_e32 v108, v108, v72
	v_add_f32_e32 v109, v109, v73
	v_exp_f32_e32 v76, v76
	v_exp_f32_e32 v77, v77
	v_add_f32_e32 v108, v108, v74
	v_add_f32_e32 v109, v109, v75
	v_exp_f32_e32 v78, v78
	v_exp_f32_e32 v79, v79
	s_mov_b64 s[0:1], 0
	v_add_f32_e32 v108, v108, v76
	v_add_f32_e32 v109, v109, v77
	s_nop 0
	v_add_f32_e32 v108, v108, v78
	v_add_f32_e32 v109, v109, v79
	s_nop 0
	v_add_f32_e32 v107, v108, v109
.LBB0_1016:
	s_andn2_b64 vcc, exec, s[0:1]
	s_cbranch_vccnz .LBB0_1018
	v_cmp_gt_u32_e32 vcc, s70, v102
	v_add_u32_e32 v65, 0xffffff20, v89
	v_add_u32_e32 v66, 0xffffff10, v89
	v_cndmask_b32_e32 v64, v179, v106, vcc
	v_cmp_gt_u32_e32 vcc, s70, v65
	v_add_u32_e32 v67, 0xffffff00, v89
	v_fmac_f32_e32 v100, 0x3e38aa3b, v41
	v_cndmask_b32_e32 v65, v179, v103, vcc
	v_cmp_gt_u32_e32 vcc, s70, v66
	v_add_u32_e32 v41, 0xfffffe30, v89
	v_fmac_f32_e32 v99, 0x3e38aa3b, v42
	v_cndmask_b32_e32 v66, v179, v104, vcc
	v_cmp_gt_u32_e32 vcc, s70, v67
	v_add_u32_e32 v42, 0xfffffe20, v89
	v_fmac_f32_e32 v98, 0x3e38aa3b, v43
	v_cndmask_b32_e32 v67, v179, v105, vcc
	v_cmp_gt_u32_e32 vcc, s70, v41
	v_add_u32_e32 v43, 0xfffffe10, v89
	v_add_u32_e32 v68, 0xfffffe00, v89
	v_cndmask_b32_e32 v41, v179, v101, vcc
	v_cmp_gt_u32_e32 vcc, s70, v42
	v_fmac_f32_e32 v96, 0x3e38aa3b, v37
	v_add_u32_e32 v37, 0xfffffd30, v89
	v_cndmask_b32_e32 v42, v179, v100, vcc
	v_cmp_gt_u32_e32 vcc, s70, v43
	v_fmac_f32_e32 v95, 0x3e38aa3b, v38
	v_add_u32_e32 v38, 0xfffffd20, v89
	v_cndmask_b32_e32 v43, v179, v99, vcc
	v_cmp_gt_u32_e32 vcc, s70, v68
	v_fmac_f32_e32 v94, 0x3e38aa3b, v39
	v_add_u32_e32 v39, 0xfffffd10, v89
	v_cndmask_b32_e32 v71, v179, v98, vcc
	v_cmp_gt_u32_e32 vcc, s70, v37
	v_exp_f32_e32 v68, v41
	v_add_u32_e32 v41, 0xfffffd00, v89
	v_cndmask_b32_e32 v37, v179, v97, vcc
	v_cmp_gt_u32_e32 vcc, s70, v38
	v_fmac_f32_e32 v40, 0x3e38aa3b, v33
	v_add_u32_e32 v33, 0xfffffc30, v89
	v_cndmask_b32_e32 v38, v179, v96, vcc
	v_cmp_gt_u32_e32 vcc, s70, v39
	v_fmac_f32_e32 v36, 0x3e38aa3b, v34
	v_add_u32_e32 v34, 0xfffffc20, v89
	v_cndmask_b32_e32 v39, v179, v95, vcc
	v_cmp_gt_u32_e32 vcc, s70, v41
	v_fmac_f32_e32 v32, 0x3e38aa3b, v35
	v_add_u32_e32 v35, 0xfffffc10, v89
	v_cndmask_b32_e32 v41, v179, v94, vcc
	v_cmp_gt_u32_e32 vcc, s70, v33
	v_exp_f32_e32 v64, v64
	v_exp_f32_e32 v65, v65
	v_cndmask_b32_e32 v33, v179, v93, vcc
	v_cmp_gt_u32_e32 vcc, s70, v34
	v_exp_f32_e32 v66, v66
	v_exp_f32_e32 v67, v67
	v_cndmask_b32_e32 v34, v179, v40, vcc
	v_cmp_gt_u32_e32 vcc, s70, v35
	v_exp_f32_e32 v76, v33
	s_nop 0
	v_cndmask_b32_e32 v35, v179, v36, vcc
	v_add_u32_e32 v36, 0xfffffc00, v89
	v_cmp_gt_u32_e32 vcc, s70, v36
	v_exp_f32_e32 v69, v42
	v_exp_f32_e32 v70, v43
	v_cndmask_b32_e32 v32, v179, v32, vcc
	v_exp_f32_e32 v79, v32
	v_add_f32_e32 v32, 0, v64
	v_add_f32_e32 v33, 0, v65
	v_exp_f32_e32 v71, v71
	v_add_f32_e32 v32, v32, v66
	v_add_f32_e32 v33, v33, v67
	v_exp_f32_e32 v72, v37
	v_add_f32_e32 v32, v32, v68
	v_add_f32_e32 v33, v33, v69
	v_exp_f32_e32 v73, v38
	v_add_f32_e32 v32, v32, v70
	v_add_f32_e32 v33, v33, v71
	v_exp_f32_e32 v74, v39
	v_exp_f32_e32 v75, v41
	v_exp_f32_e32 v77, v34
	v_add_f32_e32 v32, v32, v72
	v_add_f32_e32 v33, v33, v73
	v_exp_f32_e32 v78, v35
	v_add_f32_e32 v32, v32, v74
	v_add_f32_e32 v33, v33, v75
	s_nop 0
	v_add_f32_e32 v32, v32, v76
	v_add_f32_e32 v33, v33, v77
	s_nop 0
	v_add_f32_e32 v32, v32, v78
	v_add_f32_e32 v33, v33, v79
	s_nop 0
	v_add_f32_e32 v107, v32, v33

.LBB0_1021:
	s_cmp_ge_i32 s0, s20
	s_cbranch_scc1 .LBB0_1027
	s_lshl_b32 s21, s0, 6
	s_and_b32 s1, s21, 0x80
	s_mulk_i32 s1, 0xa0
	v_add_u32_e32 v28, s1, v153
	s_waitcnt vmcnt(2)
	ds_read_b128 v[0:3], v28
	ds_read_b128 v[4:7], v28 offset:64
	s_waitcnt vmcnt(0)
	ds_read_b128 v[8:11], v28 offset:2560
	ds_read_b128 v[12:15], v28 offset:2624
	ds_read_b128 v[16:19], v28 offset:5120
	ds_read_b128 v[20:23], v28 offset:5184
	ds_read_b128 v[24:27], v28 offset:7680
	ds_read_b128 v[30:33], v28 offset:7744
	v_sub_u32_e32 v29, v144, v150
	s_setprio 1
	s_waitcnt lgkmcnt(7)
	v_mfma_f32_16x16x32_bf16 v[0:3], v[0:3], v[60:63], 0
	s_waitcnt lgkmcnt(6)
	v_mfma_f32_16x16x32_bf16 v[34:37], v[4:7], v[56:59], v[0:3]
	s_waitcnt lgkmcnt(5)
	v_mfma_f32_16x16x32_bf16 v[0:3], v[8:11], v[60:63], 0
	s_waitcnt lgkmcnt(4)
	v_mfma_f32_16x16x32_bf16 v[8:11], v[12:15], v[56:59], v[0:3]
	s_waitcnt lgkmcnt(3)
	v_mfma_f32_16x16x32_bf16 v[0:3], v[16:19], v[60:63], 0
	s_waitcnt lgkmcnt(2)
	v_mfma_f32_16x16x32_bf16 v[4:7], v[20:23], v[56:59], v[0:3]
	s_waitcnt lgkmcnt(1)
	v_mfma_f32_16x16x32_bf16 v[0:3], v[24:27], v[60:63], 0
	s_waitcnt lgkmcnt(0)
	v_mfma_f32_16x16x32_bf16 v[0:3], v[30:33], v[56:59], v[0:3]
	s_setprio 0
	s_lshl_b32 s0, s0, 10
	v_subrev_u32_e32 v12, s0, v29
	v_subrev_u32_e32 v29, 31, v12
	v_cvt_f32_i32_e32 v12, v29
	s_or_b32 s0, s21, 63
	s_add_i32 s1, s75, -2
	v_mul_f32_e32 v13, 0x41800000, v146
	v_mul_f32_e32 v12, v146, v12
	v_fma_f32 v39, v146, 0, -v12
	v_mul_f32_e32 v14, 0x42000000, v146
	v_mul_f32_e32 v15, 0x42400000, v146
	v_fmamk_f32 v42, v34, 0x3e38aa3b, v39
	v_fmamk_f32 v40, v146, 0x41800000, v39
	v_fmamk_f32 v41, v146, 0x42000000, v39
	v_fmac_f32_e32 v39, 0x42400000, v146
	v_fma_f32 v16, v146, s67, -v12
	v_fma_f32 v17, v146, s68, -v12
	v_fma_f32 v12, v146, s69, -v12
	s_cmp_gt_i32 s0, s1
	v_fmac_f32_e32 v40, 0x3e38aa3b, v35
	v_fmac_f32_e32 v41, 0x3e38aa3b, v36
	v_fmac_f32_e32 v39, 0x3e38aa3b, v37
	s_mov_b64 s[0:1], -1
	v_fmamk_f32 v38, v8, 0x3e38aa3b, v16
	v_add_f32_e32 v37, v13, v16
	v_add_f32_e32 v36, v14, v16
	v_add_f32_e32 v35, v15, v16
	v_fmamk_f32 v34, v4, 0x3e38aa3b, v17
	v_add_f32_e32 v33, v13, v17
	v_add_f32_e32 v32, v14, v17
	v_add_f32_e32 v31, v15, v17
	v_fmamk_f32 v30, v0, 0x3e38aa3b, v12
	v_add_f32_e32 v8, v13, v12
	v_add_f32_e32 v4, v14, v12
	v_add_f32_e32 v0, v15, v12
	s_cbranch_scc1 .LBB0_1024
	v_mov_b32_e32 v12, v42
	v_mov_b32_e32 v13, v40
	v_mov_b32_e32 v14, v41
	v_mov_b32_e32 v15, v39
	v_exp_f32_e32 v12, v12
	v_exp_f32_e32 v13, v13
	v_fmamk_f32 v17, v9, 0x3e38aa3b, v37
	v_mov_b32_e32 v16, v38
	v_exp_f32_e32 v14, v14
	v_exp_f32_e32 v15, v15
	v_fmamk_f32 v18, v10, 0x3e38aa3b, v36
	v_fmamk_f32 v19, v11, 0x3e38aa3b, v35
	v_add_f32_e32 v44, 0, v12
	v_add_f32_e32 v45, 0, v13
	v_exp_f32_e32 v16, v16
	v_exp_f32_e32 v17, v17
	v_fmamk_f32 v21, v5, 0x3e38aa3b, v33
	v_mov_b32_e32 v20, v34
	v_add_f32_e32 v44, v44, v14
	v_add_f32_e32 v45, v45, v15
	v_exp_f32_e32 v18, v18
	v_exp_f32_e32 v19, v19
	v_fmamk_f32 v22, v6, 0x3e38aa3b, v32
	v_fmamk_f32 v23, v7, 0x3e38aa3b, v31
	v_add_f32_e32 v44, v44, v16
	v_add_f32_e32 v45, v45, v17
	v_exp_f32_e32 v20, v20
	v_exp_f32_e32 v21, v21
	v_fmamk_f32 v25, v1, 0x3e38aa3b, v8
	v_mov_b32_e32 v24, v30
	v_add_f32_e32 v44, v44, v18
	v_add_f32_e32 v45, v45, v19
	v_exp_f32_e32 v22, v22
	v_exp_f32_e32 v23, v23
	v_fmamk_f32 v26, v2, 0x3e38aa3b, v4
	v_fmamk_f32 v27, v3, 0x3e38aa3b, v0
	v_add_f32_e32 v44, v44, v20
	v_add_f32_e32 v45, v45, v21
	v_exp_f32_e32 v24, v24
	v_exp_f32_e32 v25, v25
	v_add_f32_e32 v44, v44, v22
	v_add_f32_e32 v45, v45, v23
	v_exp_f32_e32 v26, v26
	v_exp_f32_e32 v27, v27
	s_mov_b64 s[0:1], 0
	v_add_f32_e32 v44, v44, v24
	v_add_f32_e32 v45, v45, v25
	s_nop 0
	v_add_f32_e32 v44, v44, v26
	v_add_f32_e32 v45, v45, v27
	s_nop 0
	v_add_f32_e32 v43, v44, v45
.LBB0_1024:
	s_andn2_b64 vcc, exec, s[0:1]
	s_cbranch_vccnz .LBB0_1026
	v_cmp_gt_u32_e32 vcc, s70, v29
	v_add_u32_e32 v13, -16, v29
	v_subrev_u32_e32 v14, 32, v29
	v_cndmask_b32_e32 v12, v179, v42, vcc
	v_cmp_gt_u32_e32 vcc, s70, v13
	v_subrev_u32_e32 v15, 48, v29
	v_fmac_f32_e32 v37, 0x3e38aa3b, v9
	v_cndmask_b32_e32 v13, v179, v40, vcc
	v_cmp_gt_u32_e32 vcc, s70, v14
	v_add_u32_e32 v9, 0xffffff00, v29
	v_fmac_f32_e32 v36, 0x3e38aa3b, v10
	v_cndmask_b32_e32 v14, v179, v41, vcc
	v_cmp_gt_u32_e32 vcc, s70, v15
	v_add_u32_e32 v10, 0xfffffef0, v29
	v_fmac_f32_e32 v35, 0x3e38aa3b, v11
	v_cndmask_b32_e32 v15, v179, v39, vcc
	v_cmp_gt_u32_e32 vcc, s70, v9
	v_add_u32_e32 v11, 0xfffffee0, v29
	v_add_u32_e32 v16, 0xfffffed0, v29
	v_cndmask_b32_e32 v9, v179, v38, vcc
	v_cmp_gt_u32_e32 vcc, s70, v10
	v_fmac_f32_e32 v33, 0x3e38aa3b, v5
	v_add_u32_e32 v5, 0xfffffe00, v29
	v_cndmask_b32_e32 v10, v179, v37, vcc
	v_cmp_gt_u32_e32 vcc, s70, v11
	v_fmac_f32_e32 v32, 0x3e38aa3b, v6
	v_add_u32_e32 v6, 0xfffffdf0, v29
	v_cndmask_b32_e32 v11, v179, v36, vcc
	v_cmp_gt_u32_e32 vcc, s70, v16
	v_fmac_f32_e32 v31, 0x3e38aa3b, v7
	v_add_u32_e32 v7, 0xfffffde0, v29
	v_cndmask_b32_e32 v19, v179, v35, vcc
	v_cmp_gt_u32_e32 vcc, s70, v5
	v_exp_f32_e32 v16, v9
	v_add_u32_e32 v9, 0xfffffdd0, v29
	v_cndmask_b32_e32 v5, v179, v34, vcc
	v_cmp_gt_u32_e32 vcc, s70, v6
	v_fmac_f32_e32 v8, 0x3e38aa3b, v1
	v_add_u32_e32 v1, 0xfffffd00, v29
	v_cndmask_b32_e32 v6, v179, v33, vcc
	v_cmp_gt_u32_e32 vcc, s70, v7
	v_fmac_f32_e32 v4, 0x3e38aa3b, v2
	v_add_u32_e32 v2, 0xfffffcf0, v29
	v_cndmask_b32_e32 v7, v179, v32, vcc
	v_cmp_gt_u32_e32 vcc, s70, v9
	v_fmac_f32_e32 v0, 0x3e38aa3b, v3
	v_add_u32_e32 v3, 0xfffffce0, v29
	v_cndmask_b32_e32 v9, v179, v31, vcc
	v_cmp_gt_u32_e32 vcc, s70, v1
	v_exp_f32_e32 v12, v12
	v_exp_f32_e32 v13, v13
	v_cndmask_b32_e32 v1, v179, v30, vcc
	v_cmp_gt_u32_e32 vcc, s70, v2
	v_exp_f32_e32 v14, v14
	v_exp_f32_e32 v15, v15
	v_cndmask_b32_e32 v2, v179, v8, vcc
	v_cmp_gt_u32_e32 vcc, s70, v3
	v_exp_f32_e32 v24, v1
	s_nop 0
	v_cndmask_b32_e32 v3, v179, v4, vcc
	v_add_u32_e32 v4, 0xfffffcd0, v29
	v_cmp_gt_u32_e32 vcc, s70, v4
	v_exp_f32_e32 v17, v10
	v_exp_f32_e32 v18, v11
	v_cndmask_b32_e32 v0, v179, v0, vcc
	v_exp_f32_e32 v27, v0
	v_add_f32_e32 v0, 0, v12
	v_add_f32_e32 v1, 0, v13
	v_exp_f32_e32 v19, v19
	v_add_f32_e32 v0, v0, v14
	v_add_f32_e32 v1, v1, v15
	v_exp_f32_e32 v20, v5
	v_add_f32_e32 v0, v0, v16
	v_add_f32_e32 v1, v1, v17
	v_exp_f32_e32 v21, v6
	v_add_f32_e32 v0, v0, v18
	v_add_f32_e32 v1, v1, v19
	v_exp_f32_e32 v22, v7
	v_exp_f32_e32 v23, v9
	v_exp_f32_e32 v25, v2
	v_add_f32_e32 v0, v0, v20
	v_add_f32_e32 v1, v1, v21
	v_exp_f32_e32 v26, v3
	v_add_f32_e32 v0, v0, v22
	v_add_f32_e32 v1, v1, v23
	s_nop 0
	v_add_f32_e32 v0, v0, v24
	v_add_f32_e32 v1, v1, v25
	s_nop 0
	v_add_f32_e32 v0, v0, v26
	v_add_f32_e32 v1, v1, v27
	s_nop 0
	v_add_f32_e32 v43, v0, v1

.LBB0_1029:
	s_or_b64 exec, exec, s[0:1]
	s_waitcnt lgkmcnt(0)
	s_barrier
	ds_read2st64_b32 v[0:1], v173 offset1:1
	v_add_u32_e32 v7, 0xf0, v174
	ds_read_b64 v[2:3], v161
	ds_read_b64 v[8:9], v162
	ds_read_b64 v[10:11], v163
	ds_read_b64 v[12:13], v164
	ds_read2st64_b32 v[14:15], v174 offset1:1
	ds_read2st64_b32 v[16:17], v174 offset0:33 offset1:34
	ds_read2st64_b32 v[18:19], v174 offset0:66 offset1:67
	ds_read2st64_b32 v[20:21], v174 offset0:99 offset1:100
	ds_read2st64_b32 v[22:23], v7 offset0:30 offset1:31
	ds_read2st64_b32 v[24:25], v7 offset0:63 offset1:64
	ds_read2st64_b32 v[26:27], v7 offset0:96 offset1:97
	ds_read2st64_b32 v[28:29], v7 offset0:129 offset1:130
	ds_read_b64 v[30:31], v165
	ds_read_b64 v[32:33], v166
	ds_read_b64 v[34:35], v167
	ds_read_b64 v[36:37], v168
	ds_read2st64_b32 v[38:39], v7 offset0:162 offset1:163
	ds_read2st64_b32 v[40:41], v7 offset0:195 offset1:196
	ds_read2st64_b32 v[42:43], v7 offset0:228 offset1:229
	ds_read2st64_b32 v[44:45], v174 offset0:132 offset1:133
	ds_read2st64_b32 v[46:47], v174 offset0:165 offset1:166
	ds_read2st64_b32 v[80:81], v174 offset0:198 offset1:199
	ds_read2st64_b32 v[82:83], v174 offset0:231 offset1:232
	s_ashr_i32 s30, s75, 2
	s_add_i32 s31, s30, -1
	s_max_i32 s31, s31, 0
	s_lshl_b32 s98, s40, 25
	s_add_u32 s98, s36, s98
	s_addc_u32 s99, s37, 0
	s_lshl_b32 s20, s29, 7
	s_add_u32 s98, s98, s20
	s_addc_u32 s99, s99, 0
	s_lshl_b32 s20, s47, 20
	s_add_u32 s100, s55, s20
	s_addc_u32 s101, s56, 0
	v_mov_b32_e32 v198, v138
	v_mov_b32_e32 v199, 0
	v_mov_b32_e32 v200, v140
	v_mov_b32_e32 v201, 0
	s_lshl_b32 s22, s30, 18
	s_add_u32 s22, s98, s22
	s_addc_u32 s23, s99, 0
	s_lshl_b32 s24, s30, 7
	s_add_u32 s24, s100, s24
	s_addc_u32 s25, s101, 0
	v_lshl_add_u64 v[194:195], s[22:23], 0, v[198:199]
	v_lshl_add_u64 v[196:197], s[24:25], 0, v[200:201]
	v_lshl_add_u64 v[194:195], v[194:195], 0, v[122:123]
	v_lshl_add_u64 v[196:197], v[196:197], 0, v[122:123]
	global_load_dwordx4 v[240:243], v[194:195], off offset:2560
	global_load_dwordx4 v[244:247], v[196:197], off
	s_lshl_b32 s22, s31, 18
	s_add_u32 s22, s98, s22
	s_addc_u32 s23, s99, 0
	s_lshl_b32 s24, s31, 7
	s_add_u32 s24, s100, s24
	s_addc_u32 s25, s101, 0
	v_lshl_add_u64 v[194:195], s[22:23], 0, v[198:199]
	v_lshl_add_u64 v[196:197], s[24:25], 0, v[200:201]
	v_lshl_add_u64 v[194:195], v[194:195], 0, v[122:123]
	v_lshl_add_u64 v[196:197], v[196:197], 0, v[122:123]
	global_load_dwordx4 v[248:251], v[194:195], off offset:2560
	global_load_dwordx4 v[252:255], v[196:197], off
	s_ashr_i32 s76, s75, 2
	v_cmp_eq_u32_e64 s[0:1], s76, v128
	s_waitcnt lgkmcnt(14)
	v_mov_b32_e32 v84, v1
	v_mov_b32_e32 v85, v0
	v_fma_f32 v0, v2, v84, 0
	v_fma_f32 v1, v2, v85, 0
	v_mov_b32_e32 v84, v23
	v_mov_b32_e32 v85, v22
	v_fma_f32 v0, v8, v84, v0
	v_fma_f32 v1, v8, v85, v1
	s_waitcnt lgkmcnt(13)
	v_mov_b32_e32 v22, v25
	v_mov_b32_e32 v23, v24
	v_fma_f32 v0, v10, v22, v0
	v_fma_f32 v1, v10, v23, v1
	s_waitcnt lgkmcnt(12)
	v_mov_b32_e32 v22, v27
	v_mov_b32_e32 v23, v26
	v_fma_f32 v0, v12, v22, v0
	v_fma_f32 v1, v12, v23, v1
	s_waitcnt lgkmcnt(11)
	v_mov_b32_e32 v22, v29
	v_mov_b32_e32 v23, v28
	s_waitcnt lgkmcnt(10)
	v_fma_f32 v0, v30, v22, v0
	v_fma_f32 v1, v30, v23, v1
	s_waitcnt lgkmcnt(6)
	v_mov_b32_e32 v22, v39
	v_mov_b32_e32 v23, v38
	v_fma_f32 v0, v32, v22, v0
	v_fma_f32 v1, v32, v23, v1
	s_waitcnt lgkmcnt(5)
	v_mov_b32_e32 v22, v41
	v_mov_b32_e32 v23, v40
	v_fma_f32 v0, v34, v22, v0
	v_fma_f32 v1, v34, v23, v1
	s_waitcnt lgkmcnt(4)
	v_mov_b32_e32 v22, v43
	v_mov_b32_e32 v23, v42
	v_fma_f32 v0, v36, v22, v0
	v_fma_f32 v1, v36, v23, v1
	v_mov_b32_e32 v22, v15
	v_mov_b32_e32 v23, v14
	v_fma_f32 v2, v3, v22, 0
	v_fma_f32 v3, v3, v23, 0
	v_mov_b32_e32 v14, v17
	v_mov_b32_e32 v15, v16
	v_fma_f32 v2, v9, v14, v2
	v_fma_f32 v3, v9, v15, v3
	v_mov_b32_e32 v8, v19
	v_mov_b32_e32 v9, v18
	v_fma_f32 v2, v11, v8, v2
	v_fma_f32 v3, v11, v9, v3
	v_mov_b32_e32 v8, v21
	v_mov_b32_e32 v9, v20
	v_fma_f32 v2, v13, v8, v2
	v_fma_f32 v3, v13, v9, v3
	s_waitcnt lgkmcnt(3)
	v_mov_b32_e32 v8, v45
	v_mov_b32_e32 v9, v44
	v_fma_f32 v2, v31, v8, v2
	v_fma_f32 v3, v31, v9, v3
	s_waitcnt lgkmcnt(2)
	v_mov_b32_e32 v8, v47
	v_mov_b32_e32 v9, v46
	s_add_i32 s24, s76, 0xffffffbf
	s_add_i32 s22, s76, -1
	v_fma_f32 v2, v33, v8, v2
	v_fma_f32 v3, v33, v9, v3
	s_waitcnt lgkmcnt(1)
	v_mov_b32_e32 v8, v81
	v_mov_b32_e32 v9, v80
	s_or_b64 s[26:27], s[6:7], s[0:1]
	v_cmp_eq_u32_e64 s[0:1], s76, v156
	v_fma_f32 v2, v35, v8, v2
	v_fma_f32 v3, v35, v9, v3
	s_waitcnt lgkmcnt(0)
	v_mov_b32_e32 v8, v83
	v_mov_b32_e32 v9, v82
	v_cmp_eq_u32_e64 s[22:23], s22, v127
	v_cmp_eq_u32_e64 s[24:25], s24, v128
	v_fma_f32 v8, v37, v8, v2
	v_fma_f32 v9, v37, v9, v3
	s_or_b64 s[22:23], s[26:27], s[22:23]
	s_or_b64 s[0:1], s[0:1], s[24:25]
	v_cmp_ge_i32_e64 s[20:21], s76, v128
	v_cmp_ge_i32_e32 vcc, s76, v156
	v_cndmask_b32_e64 v3, v1, v182, s[22:23]
	v_cndmask_b32_e64 v2, v0, v182, s[0:1]
	v_cndmask_b32_e64 v1, v9, v182, s[22:23]
	v_cndmask_b32_e64 v0, v8, v182, s[0:1]
	s_mov_b32 s77, 30
	s_mov_b32 s31, 0
	s_mov_b32 s30, 0
	s_mov_b32 s98, 64
	s_mov_b32 s100, 64
	s_cmp_lt_i32 s76, 16
	s_cbranch_scc1 .Lradix_done
	v_cndmask_b32_e64 v8, 0, v3, s[20:21]
	v_cndmask_b32_e32 v9, 0, v2, vcc
	v_cndmask_b32_e64 v10, 0, v1, s[20:21]
	v_cndmask_b32_e32 v11, 0, v0, vcc

.LBB0_1054:
	s_lshl_b32 s20, s20, 6
	s_and_b32 s20, s20, 0x80
	s_mulk_i32 s20, 0xa0
	v_add_u32_e32 v104, s20, v153
	ds_read_b128 v[84:87], v104
	ds_read_b128 v[88:91], v104 offset:64
	ds_read_b128 v[92:95], v104 offset:2560
	ds_read_b128 v[96:99], v104 offset:2624
	ds_read_b128 v[32:35], v104 offset:5120
	ds_read_b128 v[36:39], v104 offset:5184
	ds_read_b128 v[40:43], v104 offset:7680
	ds_read_b128 v[44:47], v104 offset:7744
	v_lshl_or_b32 v16, s21, 6, v124
	v_sub_u32_e32 v16, v144, v16
	s_cmp_ge_i32 s21, s76
	s_setprio 1
	v_cvt_f32_i32_e32 v143, v16
	s_cbranch_scc0 .LBB0_1056
	s_waitcnt lgkmcnt(7)
	v_mfma_f32_16x16x32_bf16 v[18:21], v[84:87], v[60:63], 0
	s_waitcnt vmcnt(0) lgkmcnt(5)
	v_mfma_f32_16x16x32_bf16 v[22:25], v[92:95], v[60:63], 0
	s_waitcnt lgkmcnt(3)
	v_mfma_f32_16x16x32_bf16 v[26:29], v[32:35], v[60:63], 0
	s_waitcnt lgkmcnt(1)
	v_mfma_f32_16x16x32_bf16 v[100:103], v[40:43], v[60:63], 0
	v_mfma_f32_16x16x32_bf16 v[18:21], v[88:91], v[56:59], v[18:21]
	v_mfma_f32_16x16x32_bf16 v[22:25], v[96:99], v[56:59], v[22:25]
	v_mfma_f32_16x16x32_bf16 v[26:29], v[36:39], v[56:59], v[26:29]
	s_waitcnt lgkmcnt(0)
	v_mfma_f32_16x16x32_bf16 v[100:103], v[44:47], v[56:59], v[100:103]
	s_setprio 0
	v_add_u32_e32 v17, -2, v16
	v_cmp_gt_u32_e64 s[20:21], s70, v17
	v_add_u32_e32 v17, -3, v16
	v_mul_f32_e32 v30, v146, v142
	v_mul_f32_e32 v31, v146, v143
	v_cmp_gt_u32_e64 s[22:23], s70, v17
	v_fma_f32 v17, v146, 0, -v31
	v_cmp_gt_u32_e32 vcc, s70, v16
	v_fmamk_f32 v18, v18, 0x3e38aa3b, v17
	v_cmp_lt_i32_e64 s[0:1], 0, v16
	v_add_f32_e32 v105, v146, v17
	s_and_b64 vcc, vcc, s[26:27]
	v_fmac_f32_e32 v105, 0x3e38aa3b, v19
	v_cndmask_b32_e32 v18, v179, v18, vcc
	s_and_b64 vcc, s[0:1], s[26:27]
	v_mov_b32_e32 v147, v24
	v_cndmask_b32_e32 v19, v179, v105, vcc
	v_exp_f32_e32 v105, v18
	v_exp_f32_e32 v106, v19
	v_sub_f32_e32 v30, v30, v31
	v_mul_f32_e32 v18, s44, v146
	v_mul_f32_e32 v19, s45, v147
	v_fmamk_f32 v107, v22, 0x3e38aa3b, v30
	v_add_f32_e32 v22, v18, v17
	v_fmac_f32_e32 v22, 0x3e38aa3b, v20
	v_add_f32_e32 v108, v146, v30
	s_and_b64 vcc, s[26:27], s[20:21]
	v_mov_b32_e32 v147, v25
	s_mov_b32 s47, s45
	v_fmac_f32_e32 v108, 0x3e38aa3b, v23
	v_cndmask_b32_e32 v20, v179, v22, vcc
	v_mul_f32_e32 v22, s46, v146
	v_mul_f32_e32 v23, s47, v147
	v_exp_f32_e32 v109, v20
	v_add_f32_e32 v17, v22, v17
	v_add_f32_e32 v20, v18, v30
	v_fmac_f32_e32 v17, 0x3e38aa3b, v21
	v_add_f32_e32 v19, v20, v19
	s_and_b64 vcc, s[26:27], s[22:23]
	v_add_u32_e32 v20, -16, v16
	v_cndmask_b32_e32 v17, v179, v17, vcc
	v_cmp_gt_u32_e32 vcc, s70, v20
	s_and_b64 vcc, s[26:27], vcc
	v_subrev_u32_e32 v21, 17, v16
	v_exp_f32_e32 v110, v17
	v_add_f32_e32 v17, v22, v30
	v_add_f32_e32 v17, v17, v23
	v_cndmask_b32_e32 v20, v179, v107, vcc
	v_cmp_gt_u32_e32 vcc, s70, v21
	s_and_b64 vcc, vcc, s[26:27]
	v_subrev_u32_e32 v23, 18, v16
	v_exp_f32_e32 v107, v20
	v_cndmask_b32_e32 v21, v179, v108, vcc
	v_cmp_gt_u32_e32 vcc, s70, v23
	s_and_b64 vcc, s[26:27], vcc
	v_subrev_u32_e32 v23, 19, v16
	v_cndmask_b32_e32 v19, v179, v19, vcc
	v_cmp_gt_u32_e32 vcc, s70, v23
	s_and_b64 vcc, s[26:27], vcc
	v_subrev_u32_e32 v23, 32, v16
	v_cndmask_b32_e32 v17, v179, v17, vcc
	v_exp_f32_e32 v112, v17
	v_fma_f32 v17, v146, s65, -v31
	v_exp_f32_e32 v111, v19
	v_fmamk_f32 v19, v26, 0x3e38aa3b, v17
	v_cmp_gt_u32_e32 vcc, s70, v23
	v_add_f32_e32 v20, v146, v17
	s_and_b64 vcc, s[26:27], vcc
	v_subrev_u32_e32 v23, 33, v16
	v_fmac_f32_e32 v20, 0x3e38aa3b, v27
	v_cndmask_b32_e32 v19, v179, v19, vcc
	v_cmp_gt_u32_e32 vcc, s70, v23
	v_exp_f32_e32 v108, v21
	v_add_f32_e32 v21, v18, v17
	s_and_b64 vcc, vcc, s[26:27]
	v_subrev_u32_e32 v23, 34, v16
	v_fmac_f32_e32 v21, 0x3e38aa3b, v28
	v_cndmask_b32_e32 v20, v179, v20, vcc
	v_cmp_gt_u32_e32 vcc, s70, v23
	v_add_f32_e32 v17, v22, v17
	s_and_b64 vcc, s[26:27], vcc
	v_subrev_u32_e32 v23, 35, v16
	v_fmac_f32_e32 v17, 0x3e38aa3b, v29
	v_cndmask_b32_e32 v21, v179, v21, vcc
	v_cmp_gt_u32_e32 vcc, s70, v23
	s_and_b64 vcc, s[26:27], vcc
	v_exp_f32_e32 v139, v21
	v_cndmask_b32_e32 v17, v179, v17, vcc
	v_exp_f32_e32 v141, v17
	v_fma_f32 v17, v146, s66, -v31
	v_subrev_u32_e32 v21, 48, v16
	v_exp_f32_e32 v118, v19
	v_fmamk_f32 v19, v100, 0x3e38aa3b, v17
	v_cmp_gt_u32_e32 vcc, s70, v21
	v_exp_f32_e32 v119, v20
	v_add_f32_e32 v20, v146, v17
	s_and_b64 vcc, s[26:27], vcc
	v_subrev_u32_e32 v21, 49, v16
	v_fmac_f32_e32 v20, 0x3e38aa3b, v101
	v_cndmask_b32_e32 v19, v179, v19, vcc
	v_cmp_gt_u32_e32 vcc, s70, v21
	v_add_f32_e32 v18, v18, v17
	s_and_b64 vcc, vcc, s[26:27]
	v_subrev_u32_e32 v21, 50, v16
	v_fmac_f32_e32 v18, 0x3e38aa3b, v102
	v_cndmask_b32_e32 v20, v179, v20, vcc
	v_cmp_gt_u32_e32 vcc, s70, v21
	s_and_b64 vcc, s[26:27], vcc
	v_subrev_u32_e32 v16, 51, v16
	v_add_f32_e32 v17, v22, v17
	v_cndmask_b32_e32 v18, v179, v18, vcc
	v_cmp_gt_u32_e32 vcc, s70, v16
	v_fmac_f32_e32 v17, 0x3e38aa3b, v103
	s_and_b64 vcc, s[26:27], vcc
	v_exp_f32_e32 v147, v19
	v_cndmask_b32_e32 v16, v179, v17, vcc
	v_exp_f32_e32 v148, v20
	v_exp_f32_e32 v149, v18
	v_exp_f32_e32 v193, v16
	ds_read_b128 v[16:19], v104 offset:40960
	ds_read_b128 v[20:23], v104 offset:43520
	ds_read_b128 v[24:27], v104 offset:46080
	ds_read_b128 v[28:31], v104 offset:48640
	s_nop 0
	v_cvt_pk_bf16_f32 v100, v105, v106
	v_cvt_pk_bf16_f32 v101, v109, v110
	v_cvt_pk_bf16_f32 v102, v107, v108
	v_cvt_pk_bf16_f32 v103, v111, v112
	s_setprio 1
	s_mov_b32 s30, s28
	s_mov_b32 s31, s28
	s_mov_b32 s29, s28
	v_mov_b64_e32 v[108:109], s[30:31]
	v_mov_b64_e32 v[106:107], s[28:29]
	s_waitcnt lgkmcnt(3)
	v_mfma_f32_16x16x32_bf16 v[16:19], v[16:19], v[100:103], v[0:3]
	s_waitcnt lgkmcnt(2)
	v_mfma_f32_16x16x32_bf16 v[20:23], v[20:23], v[100:103], v[4:7]
	s_waitcnt lgkmcnt(1)
	v_mfma_f32_16x16x32_bf16 v[24:27], v[24:27], v[100:103], v[8:11]
	s_waitcnt lgkmcnt(0)
	v_mfma_f32_16x16x32_bf16 v[28:31], v[28:31], v[100:103], v[12:15]
	v_mfma_f32_16x16x32_bf16 v[100:103], v[106:109], v[100:103], v[80:83]
	s_setprio 0
	ds_read_b128 v[110:113], v104 offset:41024
	ds_read_b128 v[114:117], v104 offset:43584
	ds_read_b128 v[194:197], v104 offset:46144
	ds_read_b128 v[198:201], v104 offset:48704
	v_cvt_pk_bf16_f32 v202, v118, v119
	v_cvt_pk_bf16_f32 v203, v139, v141
	v_cvt_pk_bf16_f32 v204, v147, v148
	v_cvt_pk_bf16_f32 v205, v149, v193
	s_setprio 1
	s_waitcnt lgkmcnt(3)
	v_mfma_f32_16x16x32_bf16 v[16:19], v[110:113], v[202:205], v[16:19]
	s_mov_b64 s[0:1], 0
	s_waitcnt lgkmcnt(2)
	v_mfma_f32_16x16x32_bf16 v[20:23], v[114:117], v[202:205], v[20:23]
	s_waitcnt lgkmcnt(1)
	v_mfma_f32_16x16x32_bf16 v[24:27], v[194:197], v[202:205], v[24:27]
	s_waitcnt lgkmcnt(0)
	v_mfma_f32_16x16x32_bf16 v[28:31], v[198:201], v[202:205], v[28:31]
	v_mfma_f32_16x16x32_bf16 v[100:103], v[106:109], v[202:205], v[100:103]
.LBB0_1056:
	s_andn2_b64 vcc, exec, s[0:1]
	s_cbranch_vccnz .LBB0_1058
	s_waitcnt lgkmcnt(7)
	v_mfma_f32_16x16x32_bf16 v[16:19], v[84:87], v[60:63], 0
	s_waitcnt lgkmcnt(5)
	v_mfma_f32_16x16x32_bf16 v[20:23], v[92:95], v[60:63], 0
	s_waitcnt vmcnt(0) lgkmcnt(3)
	v_mfma_f32_16x16x32_bf16 v[24:27], v[32:35], v[60:63], 0
	s_waitcnt lgkmcnt(1)
	v_mfma_f32_16x16x32_bf16 v[28:31], v[40:43], v[60:63], 0
	v_mfma_f32_16x16x32_bf16 v[16:19], v[88:91], v[56:59], v[16:19]
	v_mfma_f32_16x16x32_bf16 v[20:23], v[96:99], v[56:59], v[20:23]
	v_mfma_f32_16x16x32_bf16 v[24:27], v[36:39], v[56:59], v[24:27]
	s_waitcnt lgkmcnt(0)
	v_mfma_f32_16x16x32_bf16 v[28:31], v[44:47], v[56:59], v[28:31]
	s_setprio 0
	v_mul_f32_e64 v32, -v146, v143
	v_cndmask_b32_e64 v32, v179, v32, s[26:27]
	v_fma_f32 v33, 0, v146, v32
	v_fmamk_f32 v16, v16, 0x3e38aa3b, v33
	v_add_f32_e32 v34, v146, v33
	v_mov_b32_e32 v147, v22
	v_fmac_f32_e32 v34, 0x3e38aa3b, v17
	v_exp_f32_e32 v35, v16
	v_fmamk_f32 v36, v146, 0x41800000, v32
	v_mul_f32_e32 v16, s44, v146
	v_mul_f32_e32 v17, s45, v147
	v_fmamk_f32 v37, v20, 0x3e38aa3b, v36
	v_add_f32_e32 v20, v16, v33
	v_fmac_f32_e32 v20, 0x3e38aa3b, v18
	v_add_f32_e32 v38, v146, v36
	v_mov_b32_e32 v147, v23
	s_mov_b32 s47, s45
	v_fmac_f32_e32 v38, 0x3e38aa3b, v21
	v_exp_f32_e32 v39, v20
	v_add_f32_e32 v18, v16, v36
	v_mul_f32_e32 v20, s46, v146
	v_mul_f32_e32 v21, s47, v147
	v_add_f32_e32 v17, v18, v17
	v_add_f32_e32 v18, v20, v33
	v_fmac_f32_e32 v18, 0x3e38aa3b, v19
	s_nop 0
	v_exp_f32_e32 v33, v18
	v_add_f32_e32 v18, v20, v36
	v_add_f32_e32 v18, v18, v21
	v_exp_f32_e32 v36, v37
	v_exp_f32_e32 v37, v38
	v_exp_f32_e32 v38, v17
	v_fmamk_f32 v17, v146, 0x42000000, v32
	v_add_f32_e32 v19, v146, v17
	v_exp_f32_e32 v40, v18
	v_fmamk_f32 v18, v24, 0x3e38aa3b, v17
	v_fmac_f32_e32 v19, 0x3e38aa3b, v25
	v_add_f32_e32 v21, v16, v17
	v_add_f32_e32 v17, v20, v17
	v_fmac_f32_e32 v17, 0x3e38aa3b, v27
	v_fmac_f32_e32 v32, 0x42400000, v146
	v_exp_f32_e32 v41, v18
	v_exp_f32_e32 v42, v19
	v_add_f32_e32 v18, v146, v32
	v_add_f32_e32 v16, v16, v32
	v_add_f32_e32 v19, v20, v32
	v_fmac_f32_e32 v21, 0x3e38aa3b, v26
	v_exp_f32_e32 v44, v17
	v_fmamk_f32 v17, v28, 0x3e38aa3b, v32
	v_fmac_f32_e32 v18, 0x3e38aa3b, v29
	v_fmac_f32_e32 v16, 0x3e38aa3b, v30
	v_fmac_f32_e32 v19, 0x3e38aa3b, v31
	v_exp_f32_e32 v34, v34
	v_exp_f32_e32 v43, v21
	v_exp_f32_e32 v45, v17
	v_exp_f32_e32 v46, v18
	v_exp_f32_e32 v47, v16
	v_exp_f32_e32 v84, v19
	ds_read_b128 v[16:19], v104 offset:40960
	ds_read_b128 v[20:23], v104 offset:43520
	ds_read_b128 v[24:27], v104 offset:46080
	ds_read_b128 v[28:31], v104 offset:48640
	s_nop 0
	v_cvt_pk_bf16_f32 v32, v35, v34
	v_cvt_pk_bf16_f32 v33, v39, v33
	v_cvt_pk_bf16_f32 v34, v36, v37
	v_cvt_pk_bf16_f32 v35, v38, v40
	s_setprio 1
	s_mov_b32 s30, s28
	s_mov_b32 s31, s28
	s_mov_b32 s29, s28
	v_mov_b64_e32 v[38:39], s[30:31]
	v_mov_b64_e32 v[36:37], s[28:29]
	s_waitcnt lgkmcnt(3)
	v_mfma_f32_16x16x32_bf16 v[0:3], v[16:19], v[32:35], v[0:3]
	s_waitcnt lgkmcnt(2)
	v_mfma_f32_16x16x32_bf16 v[4:7], v[20:23], v[32:35], v[4:7]
	s_waitcnt lgkmcnt(1)
	v_mfma_f32_16x16x32_bf16 v[8:11], v[24:27], v[32:35], v[8:11]
	s_waitcnt lgkmcnt(0)
	v_mfma_f32_16x16x32_bf16 v[12:15], v[28:31], v[32:35], v[12:15]
	v_mfma_f32_16x16x32_bf16 v[32:35], v[36:39], v[32:35], v[80:83]
	s_setprio 0
	ds_read_b128 v[16:19], v104 offset:41024
	ds_read_b128 v[20:23], v104 offset:43584
	ds_read_b128 v[24:27], v104 offset:46144
	ds_read_b128 v[28:31], v104 offset:48704
	v_cvt_pk_bf16_f32 v40, v41, v42
	v_cvt_pk_bf16_f32 v41, v43, v44
	v_cvt_pk_bf16_f32 v42, v45, v46
	v_cvt_pk_bf16_f32 v43, v47, v84
	s_setprio 1
	s_waitcnt lgkmcnt(3)
	v_mfma_f32_16x16x32_bf16 v[16:19], v[16:19], v[40:43], v[0:3]
	s_waitcnt lgkmcnt(2)
	v_mfma_f32_16x16x32_bf16 v[20:23], v[20:23], v[40:43], v[4:7]
	s_waitcnt lgkmcnt(1)
	v_mfma_f32_16x16x32_bf16 v[24:27], v[24:27], v[40:43], v[8:11]
	s_waitcnt lgkmcnt(0)
	v_mfma_f32_16x16x32_bf16 v[28:31], v[28:31], v[40:43], v[12:15]
	v_mfma_f32_16x16x32_bf16 v[100:103], v[36:39], v[40:43], v[32:35]

.LBB0_1069:
	s_cmp_gt_i32 s23, s21
	s_cbranch_scc1 .LBB0_986
	s_lshl_b32 s22, s23, 6
	s_add_i32 s23, s22, s20
	s_or_b32 s0, s23, 63
	s_cmp_gt_i32 s0, s74
	s_cselect_b64 s[0:1], -1, 0
	s_addk_i32 s74, 0xfe10
	s_cmp_lt_i32 s23, s74
	s_cselect_b64 s[20:21], -1, 0
	s_and_b32 s22, s22, 0x80
	s_mulk_i32 s22, 0xa0
	v_add_u32_e32 v81, s22, v153
	ds_read_b128 v[102:105], v81
	ds_read_b128 v[106:109], v81 offset:64
	ds_read_b128 v[110:113], v81 offset:2560
	ds_read_b128 v[114:117], v81 offset:2624
	ds_read_b128 v[86:89], v81 offset:5120
	ds_read_b128 v[90:93], v81 offset:5184
	ds_read_b128 v[94:97], v81 offset:7680
	ds_read_b128 v[98:101], v81 offset:7744
	s_waitcnt vmcnt(2)
	v_or_b32_e32 v32, s23, v124
	v_sub_u32_e32 v137, v144, v32
	s_or_b64 s[20:21], s[0:1], s[20:21]
	s_setprio 1
	v_cvt_f32_i32_e32 v143, v137
	s_mov_b64 s[0:1], -1
	s_and_b64 vcc, exec, s[20:21]
	s_cbranch_vccnz .LBB0_1072
	s_waitcnt lgkmcnt(7)
	v_mfma_f32_16x16x32_bf16 v[32:35], v[102:105], v[60:63], 0
	s_waitcnt lgkmcnt(5)
	v_mfma_f32_16x16x32_bf16 v[36:39], v[110:113], v[60:63], 0
	s_waitcnt vmcnt(0) lgkmcnt(3)
	v_mfma_f32_16x16x32_bf16 v[40:43], v[86:89], v[60:63], 0
	s_waitcnt lgkmcnt(1)
	v_mfma_f32_16x16x32_bf16 v[44:47], v[94:97], v[60:63], 0
	v_mfma_f32_16x16x32_bf16 v[32:35], v[106:109], v[56:59], v[32:35]
	v_mfma_f32_16x16x32_bf16 v[36:39], v[114:117], v[56:59], v[36:39]
	v_mfma_f32_16x16x32_bf16 v[40:43], v[90:93], v[56:59], v[40:43]
	s_waitcnt lgkmcnt(0)
	v_mfma_f32_16x16x32_bf16 v[44:47], v[98:101], v[56:59], v[44:47]
	s_setprio 0
	v_mul_f32_e32 v118, v146, v142
	v_mul_f32_e64 v119, -v146, v143
	v_fma_f32 v120, 0, v146, v119
	s_nop 0
	v_fmamk_f32 v32, v32, 0x3e38aa3b, v120
	v_add_f32_e32 v121, v146, v120
	v_mov_b32_e32 v147, v38
	v_fmac_f32_e32 v121, 0x3e38aa3b, v33
	v_exp_f32_e32 v139, v32
	v_add_f32_e32 v118, v118, v119
	v_mul_f32_e32 v32, s44, v146
	v_mul_f32_e32 v33, s45, v147
	v_fmamk_f32 v141, v36, 0x3e38aa3b, v118
	v_add_f32_e32 v36, v32, v120
	v_fmac_f32_e32 v36, 0x3e38aa3b, v34
	v_add_f32_e32 v148, v146, v118
	v_mov_b32_e32 v147, v39
	s_mov_b32 s47, s45
	v_fmac_f32_e32 v148, 0x3e38aa3b, v37
	v_exp_f32_e32 v149, v36
	v_add_f32_e32 v34, v32, v118
	v_mul_f32_e32 v36, s46, v146
	v_mul_f32_e32 v37, s47, v147
	v_add_f32_e32 v33, v34, v33
	v_add_f32_e32 v34, v36, v120
	v_fmac_f32_e32 v34, 0x3e38aa3b, v35
	s_nop 0
	v_exp_f32_e32 v120, v34
	v_add_f32_e32 v34, v36, v118
	v_add_f32_e32 v34, v34, v37
	v_exp_f32_e32 v147, v148
	v_exp_f32_e32 v148, v33
	v_fmamk_f32 v33, v146, 0x42000000, v119
	v_add_f32_e32 v35, v146, v33
	v_exp_f32_e32 v186, v34
	v_fmamk_f32 v34, v40, 0x3e38aa3b, v33
	v_fmac_f32_e32 v35, 0x3e38aa3b, v41
	v_add_f32_e32 v37, v32, v33
	v_add_f32_e32 v33, v36, v33
	v_fmac_f32_e32 v33, 0x3e38aa3b, v43
	v_fmac_f32_e32 v119, 0x42400000, v146
	v_exp_f32_e32 v206, v34
	v_exp_f32_e32 v207, v35
	v_add_f32_e32 v34, v146, v119
	v_add_f32_e32 v32, v32, v119
	v_add_f32_e32 v35, v36, v119
	v_fmac_f32_e32 v37, 0x3e38aa3b, v42
	v_exp_f32_e32 v209, v33
	v_fmamk_f32 v33, v44, 0x3e38aa3b, v119
	v_fmac_f32_e32 v34, 0x3e38aa3b, v45
	v_fmac_f32_e32 v32, 0x3e38aa3b, v46
	v_fmac_f32_e32 v35, 0x3e38aa3b, v47
	v_exp_f32_e32 v121, v121
	v_exp_f32_e32 v208, v37
	v_exp_f32_e32 v210, v33
	v_exp_f32_e32 v211, v34
	v_exp_f32_e32 v212, v32
	v_exp_f32_e32 v213, v35
	ds_read_b128 v[32:35], v81 offset:40960
	ds_read_b128 v[36:39], v81 offset:43520
	ds_read_b128 v[40:43], v81 offset:46080
	ds_read_b128 v[44:47], v81 offset:48640
	v_exp_f32_e32 v141, v141
	v_cvt_pk_bf16_f32 v118, v139, v121
	v_cvt_pk_bf16_f32 v119, v149, v120
	v_cvt_pk_bf16_f32 v120, v141, v147
	v_cvt_pk_bf16_f32 v121, v148, v186
	s_setprio 1
	s_mov_b32 s30, s28
	s_mov_b32 s31, s28
	s_mov_b32 s29, s28
	v_mov_b64_e32 v[188:189], s[30:31]
	v_mov_b64_e32 v[186:187], s[28:29]
	s_waitcnt lgkmcnt(3)
	v_mfma_f32_16x16x32_bf16 v[32:35], v[32:35], v[118:121], v[16:19]
	s_waitcnt lgkmcnt(2)
	v_mfma_f32_16x16x32_bf16 v[36:39], v[36:39], v[118:121], v[20:23]
	s_waitcnt lgkmcnt(1)
	v_mfma_f32_16x16x32_bf16 v[40:43], v[40:43], v[118:121], v[24:27]
	s_waitcnt lgkmcnt(0)
	v_mfma_f32_16x16x32_bf16 v[44:47], v[44:47], v[118:121], v[28:31]
	v_mfma_f32_16x16x32_bf16 v[118:121], v[186:189], v[118:121], v[82:85]
	s_setprio 0
	ds_read_b128 v[190:193], v81 offset:41024
	ds_read_b128 v[194:197], v81 offset:43584
	ds_read_b128 v[198:201], v81 offset:46144
	ds_read_b128 v[202:205], v81 offset:48704
	v_cvt_pk_bf16_f32 v206, v206, v207
	v_cvt_pk_bf16_f32 v207, v208, v209
	v_cvt_pk_bf16_f32 v208, v210, v211
	v_cvt_pk_bf16_f32 v209, v212, v213
	s_setprio 1
	s_waitcnt lgkmcnt(3)
	v_mfma_f32_16x16x32_bf16 v[32:35], v[190:193], v[206:209], v[32:35]
	s_mov_b64 s[0:1], 0
	s_waitcnt lgkmcnt(2)
	v_mfma_f32_16x16x32_bf16 v[36:39], v[194:197], v[206:209], v[36:39]
	s_waitcnt lgkmcnt(1)
	v_mfma_f32_16x16x32_bf16 v[40:43], v[198:201], v[206:209], v[40:43]
	s_waitcnt lgkmcnt(0)
	v_mfma_f32_16x16x32_bf16 v[44:47], v[202:205], v[206:209], v[44:47]
	v_mfma_f32_16x16x32_bf16 v[118:121], v[186:189], v[206:209], v[118:121]
.LBB0_1072:
	s_andn2_b64 vcc, exec, s[0:1]
	s_cbranch_vccnz .LBB0_985
	s_waitcnt lgkmcnt(7)
	v_mfma_f32_16x16x32_bf16 v[32:35], v[102:105], v[60:63], 0
	s_waitcnt lgkmcnt(5)
	v_mfma_f32_16x16x32_bf16 v[36:39], v[110:113], v[60:63], 0
	s_waitcnt vmcnt(0) lgkmcnt(3)
	v_mfma_f32_16x16x32_bf16 v[40:43], v[86:89], v[60:63], 0
	s_waitcnt lgkmcnt(1)
	v_mfma_f32_16x16x32_bf16 v[44:47], v[94:97], v[60:63], 0
	v_mfma_f32_16x16x32_bf16 v[32:35], v[106:109], v[56:59], v[32:35]
	v_mfma_f32_16x16x32_bf16 v[36:39], v[114:117], v[56:59], v[36:39]
	v_mfma_f32_16x16x32_bf16 v[40:43], v[90:93], v[56:59], v[40:43]
	s_waitcnt lgkmcnt(0)
	v_mfma_f32_16x16x32_bf16 v[44:47], v[98:101], v[56:59], v[44:47]
	s_setprio 0
	v_mul_f32_e32 v56, v146, v142
	v_mul_f32_e32 v57, v146, v143
	v_fma_f32 v61, v146, 0, -v57
	s_nop 0
	v_fmamk_f32 v32, v32, 0x3e38aa3b, v61
	v_add_u32_e32 v58, -1, v137
	v_add_f32_e32 v62, v146, v61
	v_cmp_gt_u32_e32 vcc, s71, v137
	v_fmac_f32_e32 v62, 0x3e38aa3b, v33
	v_mov_b32_e32 v147, v38
	v_cndmask_b32_e32 v32, v179, v32, vcc
	v_cmp_gt_u32_e32 vcc, s71, v58
	v_exp_f32_e32 v58, v32
	v_sub_f32_e32 v56, v56, v57
	v_cndmask_b32_e32 v33, v179, v62, vcc
	v_exp_f32_e32 v62, v33
	v_mul_f32_e32 v32, s44, v146
	v_mul_f32_e32 v33, s45, v147
	v_add_u32_e32 v59, -2, v137
	v_fmamk_f32 v63, v36, 0x3e38aa3b, v56
	v_add_f32_e32 v36, v32, v61
	v_fmac_f32_e32 v36, 0x3e38aa3b, v34
	v_cmp_gt_u32_e32 vcc, s71, v59
	v_add_f32_e32 v86, v146, v56
	v_mov_b32_e32 v147, v39
	v_cndmask_b32_e32 v34, v179, v36, vcc
	s_mov_b32 s47, s45
	v_fmac_f32_e32 v86, 0x3e38aa3b, v37
	v_exp_f32_e32 v59, v34
	v_add_f32_e32 v34, v32, v56
	v_mul_f32_e32 v36, s46, v146
	v_mul_f32_e32 v37, s47, v147
	v_add_f32_e32 v33, v34, v33
	v_add_f32_e32 v34, v36, v61
	v_add_u32_e32 v60, -3, v137
	v_fmac_f32_e32 v34, 0x3e38aa3b, v35
	v_cmp_gt_u32_e32 vcc, s71, v60
	v_add_u32_e32 v35, -16, v137
	v_subrev_u32_e32 v38, 18, v137
	v_cndmask_b32_e32 v34, v179, v34, vcc
	v_exp_f32_e32 v60, v34
	v_add_f32_e32 v34, v36, v56
	v_add_f32_e32 v34, v34, v37
	v_cmp_gt_u32_e32 vcc, s71, v35
	v_subrev_u32_e32 v37, 17, v137
	s_nop 0
	v_cndmask_b32_e32 v35, v179, v63, vcc
	v_cmp_gt_u32_e32 vcc, s71, v37
	v_exp_f32_e32 v61, v35
	s_nop 0
	v_cndmask_b32_e32 v37, v179, v86, vcc
	v_cmp_gt_u32_e32 vcc, s71, v38
	v_subrev_u32_e32 v38, 19, v137
	v_exp_f32_e32 v63, v37
	v_cndmask_b32_e32 v33, v179, v33, vcc
	v_cmp_gt_u32_e32 vcc, s71, v38
	v_exp_f32_e32 v86, v33
	v_fma_f32 v33, v146, s65, -v57
	v_cndmask_b32_e32 v34, v179, v34, vcc
	v_exp_f32_e32 v87, v34
	v_fmamk_f32 v34, v40, 0x3e38aa3b, v33
	v_add_f32_e32 v35, v146, v33
	v_subrev_u32_e32 v38, 32, v137
	v_fmac_f32_e32 v35, 0x3e38aa3b, v41
	v_add_f32_e32 v37, v32, v33
	v_cmp_gt_u32_e32 vcc, s71, v38
	v_subrev_u32_e32 v38, 33, v137
	v_fmac_f32_e32 v37, 0x3e38aa3b, v42
	v_add_f32_e32 v33, v36, v33
	v_cndmask_b32_e32 v34, v179, v34, vcc
	v_cmp_gt_u32_e32 vcc, s71, v38
	v_subrev_u32_e32 v38, 34, v137
	v_fmac_f32_e32 v33, 0x3e38aa3b, v43
	v_cndmask_b32_e32 v35, v179, v35, vcc
	v_cmp_gt_u32_e32 vcc, s71, v38
	v_subrev_u32_e32 v38, 35, v137
	v_exp_f32_e32 v88, v34
	v_cndmask_b32_e32 v37, v179, v37, vcc
	v_cmp_gt_u32_e32 vcc, s71, v38
	v_exp_f32_e32 v89, v35
	v_exp_f32_e32 v90, v37
	v_cndmask_b32_e32 v33, v179, v33, vcc
	v_exp_f32_e32 v91, v33
	v_fma_f32 v33, v146, s66, -v57
	v_fmamk_f32 v34, v44, 0x3e38aa3b, v33
	v_add_f32_e32 v35, v146, v33
	v_add_f32_e32 v32, v32, v33
	v_add_f32_e32 v33, v36, v33
	v_subrev_u32_e32 v36, 48, v137
	v_fmac_f32_e32 v35, 0x3e38aa3b, v45
	v_cmp_gt_u32_e32 vcc, s71, v36
	v_subrev_u32_e32 v36, 49, v137
	v_fmac_f32_e32 v32, 0x3e38aa3b, v46
	v_cndmask_b32_e32 v34, v179, v34, vcc
	v_cmp_gt_u32_e32 vcc, s71, v36
	v_subrev_u32_e32 v36, 50, v137
	v_fmac_f32_e32 v33, 0x3e38aa3b, v47
	v_cndmask_b32_e32 v35, v179, v35, vcc
	v_cmp_gt_u32_e32 vcc, s71, v36
	v_subrev_u32_e32 v36, 51, v137
	v_exp_f32_e32 v92, v34
	v_cndmask_b32_e32 v32, v179, v32, vcc
	v_cmp_gt_u32_e32 vcc, s71, v36
	v_exp_f32_e32 v93, v35
	v_exp_f32_e32 v94, v32
	v_cndmask_b32_e32 v33, v179, v33, vcc
	v_exp_f32_e32 v95, v33
	ds_read_b128 v[32:35], v81 offset:40960
	ds_read_b128 v[36:39], v81 offset:43520
	ds_read_b128 v[40:43], v81 offset:46080
	ds_read_b128 v[44:47], v81 offset:48640
	v_cvt_pk_bf16_f32 v56, v58, v62
	v_cvt_pk_bf16_f32 v57, v59, v60
	v_cvt_pk_bf16_f32 v58, v61, v63
	v_cvt_pk_bf16_f32 v59, v86, v87
	s_setprio 1
	s_mov_b32 s30, s28
	s_mov_b32 s31, s28
	s_mov_b32 s29, s28
	v_mov_b64_e32 v[62:63], s[30:31]
	v_mov_b64_e32 v[60:61], s[28:29]
	s_waitcnt lgkmcnt(3)
	v_mfma_f32_16x16x32_bf16 v[16:19], v[32:35], v[56:59], v[16:19]
	s_waitcnt lgkmcnt(2)
	v_mfma_f32_16x16x32_bf16 v[20:23], v[36:39], v[56:59], v[20:23]
	s_waitcnt lgkmcnt(1)
	v_mfma_f32_16x16x32_bf16 v[24:27], v[40:43], v[56:59], v[24:27]
	s_waitcnt lgkmcnt(0)
	v_mfma_f32_16x16x32_bf16 v[28:31], v[44:47], v[56:59], v[28:31]
	v_mfma_f32_16x16x32_bf16 v[56:59], v[60:63], v[56:59], v[82:85]
	s_setprio 0
	ds_read_b128 v[32:35], v81 offset:41024
	ds_read_b128 v[36:39], v81 offset:43584
	ds_read_b128 v[40:43], v81 offset:46144
	ds_read_b128 v[44:47], v81 offset:48704
	v_cvt_pk_bf16_f32 v82, v88, v89
	v_cvt_pk_bf16_f32 v83, v90, v91
	v_cvt_pk_bf16_f32 v84, v92, v93
	v_cvt_pk_bf16_f32 v85, v94, v95
	s_setprio 1
	s_waitcnt lgkmcnt(3)
	v_mfma_f32_16x16x32_bf16 v[32:35], v[32:35], v[82:85], v[16:19]
	s_waitcnt lgkmcnt(2)
	v_mfma_f32_16x16x32_bf16 v[36:39], v[36:39], v[82:85], v[20:23]
	s_waitcnt lgkmcnt(1)
	v_mfma_f32_16x16x32_bf16 v[40:43], v[40:43], v[82:85], v[24:27]
	s_waitcnt lgkmcnt(0)
	v_mfma_f32_16x16x32_bf16 v[44:47], v[44:47], v[82:85], v[28:31]
	v_mfma_f32_16x16x32_bf16 v[118:121], v[60:63], v[82:85], v[56:59]
	s_branch .LBB0_985
